# K-loops: s_setprio 1 raised before the pre-MFMA barrier instead of after it (32 sites), on top of the fourth combination
# speedup vs baseline: 1.0023x; 1.0023x over previous
; #define PG8_STAGE(bufoff, gbase, voff) do { _Pragma("unroll") for (int _i = 0; _i < 2; ++_i) \
;         __builtin_amdgcn_global_load_lds((const unsigned*)((const char*)(gbase) + (voff)[_i]), (PG8_LAS unsigned*)(lds + (bufoff) + ldsw + _i * 8192), 16, 0, 0); } while (0)
; #define PG8_LDA(dst, b, h) do { _Pragma("unroll") for (int m = 0; m < 4; ++m) _Pragma("unroll") for (int k = 0; k < 2; ++k) dst[m][k] = *(const PG8_LAS bf16x8*)(lds + PG8_SA(b, h) + aoff + m * 2048 + k * 1024); } while (0)
; #define PG8_WAIT_V(n) asm volatile("s_waitcnt vmcnt(" #n ")" ::: "memory")
; template <class Epi, class Sched, class Gemm, bool ALIGN_EPI = false, bool SP2 = false>
; __device__ __forceinline__ void gemm_phase(PG8_LAS unsigned char* lds, const Gemm g, const Sched& S, const Epi& E) {
;     ...
;         for (int t = 0; t < nt; t += 2) {
;             const bool last = (t == nt - 2);
;             const char* a1 = cA + (size_t)(t + 1) * kstep;
;             const char* a2 = last ? nA : cA + (size_t)(t + 2) * kstep; const char* b2 = last ? nB : cB + (size_t)(t + 2) * kstep;
;             const char* a3 = a2 + kstep; const char* b3 = b2 + kstep;
;             if (last && has_next) S.a_ready(nxt);
;             if constexpr (SP2) {
;             PG8_LDB(B0, 0, 0); PG8_LDB(B1, 0, 1); PG8_SCHED; PG8_LDA(At, 0, 0); PG8_STAGE(PG8_SA(1, 1), a1 + hstepA, voffA);
;             PG8_WAIT_V(8); PG8_WAIT_L(0); PG8_BAR; PG8_MMA(0, 0, At, B0); PG8_MMA(0, 1, At, B1); PG8_BAR; PG8_SCHED;
;             PG8_LDA(At, 0, 1); PG8_STAGE(PG8_SB(0, 0), b2, voffB); PG8_STAGE(PG8_SB(0, 1), b2 + hB1, voffB1); PG8_STAGE(PG8_SA(0, 0), a2, voffA);
;             PG8_WAIT_V(8); PG8_WAIT_L(0); PG8_BAR; PG8_MMA(1, 0, At, B0); PG8_MMA(1, 1, At, B1); PG8_BAR; PG8_SCHED;
;             PG8_LDB(B0, 1, 0); PG8_LDB(B1, 1, 1); PG8_SCHED; PG8_LDA(At, 1, 0); PG8_STAGE(PG8_SA(0, 1), a2 + hstepA, voffA);
;             PG8_WAIT_V(8); PG8_WAIT_L(0); PG8_BAR; PG8_MMA(0, 0, At, B0); PG8_MMA(0, 1, At, B1); PG8_BAR; PG8_SCHED;
;             PG8_LDA(At, 1, 1); PG8_STAGE(PG8_SB(1, 0), b3, voffB); PG8_STAGE(PG8_SB(1, 1), b3 + hB1, voffB1); PG8_STAGE(PG8_SA(1, 0), a3, voffA);
;             PG8_WAIT_V(8);
;             if constexpr (epi_pre<Epi>::value) { if (last) E.pre(pre, cur, wr, wc, lane); }
;             PG8_WAIT_L(0); PG8_BAR; PG8_MMA(1, 0, At, B0); PG8_MMA(1, 1, At, B1); PG8_BAR; PG8_SCHED;
.LBB0_135:
	s_waitcnt lgkmcnt(0)
	s_nop 0
	s_setprio 1
	s_barrier
	v_mfma_i32_16x16x64_i8 v[78:81], v[174:177], v[206:209], v[78:81]
	v_mfma_i32_16x16x64_i8 v[74:77], v[166:169], v[206:209], v[74:77]
	v_mfma_i32_16x16x64_i8 v[62:65], v[174:177], v[194:197], v[62:65]
	v_mfma_i32_16x16x64_i8 v[58:61], v[166:169], v[194:197], v[58:61]
	v_mfma_i32_16x16x64_i8 v[46:49], v[174:177], v[186:189], v[46:49]
	v_mfma_i32_16x16x64_i8 v[42:45], v[166:169], v[186:189], v[42:45]
	v_mfma_i32_16x16x64_i8 v[30:33], v[174:177], v[182:185], v[30:33]
	v_mfma_i32_16x16x64_i8 v[26:29], v[166:169], v[182:185], v[26:29]
	v_mfma_i32_16x16x64_i8 v[78:81], v[170:173], v[202:205], v[78:81]
	v_mfma_i32_16x16x64_i8 v[74:77], v[162:165], v[202:205], v[74:77]
	v_mfma_i32_16x16x64_i8 v[62:65], v[170:173], v[198:201], v[62:65]
	v_mfma_i32_16x16x64_i8 v[58:61], v[162:165], v[198:201], v[58:61]
	v_mfma_i32_16x16x64_i8 v[46:49], v[170:173], v[190:193], v[46:49]
	v_mfma_i32_16x16x64_i8 v[42:45], v[162:165], v[190:193], v[42:45]
	v_mfma_i32_16x16x64_i8 v[30:33], v[170:173], v[178:181], v[30:33]
	v_mfma_i32_16x16x64_i8 v[26:29], v[162:165], v[178:181], v[26:29]
	s_setprio 0
	s_setprio 1
	v_mfma_i32_16x16x64_i8 v[162:165], v[150:153], v[206:209], v[70:73]
	v_mfma_i32_16x16x64_i8 v[70:73], v[154:157], v[202:205], v[162:165]
	v_mfma_i32_16x16x64_i8 v[166:169], v[158:161], v[206:209], v[66:69]
	v_mfma_i32_16x16x64_i8 v[170:173], v[150:153], v[194:197], v[54:57]
	v_mfma_i32_16x16x64_i8 v[174:177], v[158:161], v[194:197], v[50:53]
	v_mfma_i32_16x16x64_i8 v[242:245], v[150:153], v[186:189], v[38:41]
	v_mfma_i32_16x16x64_i8 v[246:249], v[158:161], v[186:189], v[34:37]
	v_mfma_i32_16x16x64_i8 v[162:165], v[150:153], v[182:185], v[22:25]
	v_mfma_i32_16x16x64_i8 v[18:21], v[158:161], v[182:185], v[18:21]
	v_mfma_i32_16x16x64_i8 v[66:69], v[146:149], v[202:205], v[166:169]
	v_mfma_i32_16x16x64_i8 v[54:57], v[154:157], v[198:201], v[170:173]
	v_mfma_i32_16x16x64_i8 v[50:53], v[146:149], v[198:201], v[174:177]
	v_mfma_i32_16x16x64_i8 v[38:41], v[154:157], v[190:193], v[242:245]
	v_mfma_i32_16x16x64_i8 v[34:37], v[146:149], v[190:193], v[246:249]
	v_mfma_i32_16x16x64_i8 v[22:25], v[154:157], v[178:181], v[162:165]
	v_mfma_i32_16x16x64_i8 v[18:21], v[146:149], v[178:181], v[18:21]
	s_setprio 0
	s_barrier
	s_add_i32 s2, s2, 2
	s_add_u32 s81, s81, 0x100
	s_addc_u32 s82, s82, 0
	s_add_u32 s48, s48, 0x100
	s_addc_u32 s49, s49, 0
	s_cmp_gt_u32 s2, 5
	s_cbranch_scc1 .LBB0_138
.LBB0_136:
	s_add_u32 s0, s48, 0xfffe0080
	s_addc_u32 s1, s49, -1
	s_cmp_eq_u32 s2, 4
	s_cselect_b32 s53, s7, s1
	s_cselect_b32 s52, s43, s0
	s_cselect_b32 s55, s79, s82
	s_cselect_b32 s54, s80, s81
	s_add_i32 s95, s76, s64
	ds_read_b128 v[174:177], v253
	ds_read_b128 v[170:173], v253 offset:1024
	ds_read_b128 v[166:169], v253 offset:2048
	ds_read_b128 v[162:165], v253 offset:3072
	ds_read_b128 v[158:161], v254
	ds_read_b128 v[154:157], v254 offset:1024
	ds_read_b128 v[150:153], v254 offset:2048
	ds_read_b128 v[146:149], v254 offset:3072
	s_add_i32 m0, s65, 0xc000
	s_add_i32 s96, s65, 0xe000
	s_add_i32 s92, s95, 0x2000
	s_add_u32 s56, s54, 0x20000
	s_addc_u32 s57, s55, 0
	s_add_i32 s94, s77, s64
	s_add_i32 s93, s94, 0x2000
	s_add_i32 s91, 0, 0x18000
	s_add_i32 s90, 0, 0x1c000
	s_add_u32 s50, s52, 0x20000
	s_addc_u32 s51, s53, 0
	s_add_i32 s83, s91, s64
	s_add_i32 s3, s83, 0x2000
	s_add_u32 s0, s54, 0x20080
	s_addc_u32 s1, s55, 0
	s_add_i32 s89, s90, s64
	s_add_i32 s88, s89, 0x2000
	s_cmp_lg_u32 s2, 4
	ds_read_b128 v[190:193], v222
	ds_read_b128 v[194:197], v222 offset:1024
	ds_read_b128 v[198:201], v222 offset:2048
	ds_read_b128 v[202:205], v222 offset:3072
	ds_read_b128 v[206:209], v222 offset:4096
	ds_read_b128 v[186:189], v222 offset:5120
	ds_read_b128 v[182:185], v222 offset:6144
	ds_read_b128 v[178:181], v222 offset:7168
	global_load_lds_dwordx4 v220, s[48:49]
	s_mov_b32 m0, s96
	s_nop 0
	global_load_lds_dwordx4 v218, s[48:49]
	s_waitcnt vmcnt(8)
	s_waitcnt lgkmcnt(0)
	s_nop 0
	s_setprio 1
	s_barrier
	v_mfma_i32_16x16x64_i8 v[142:145], v[174:177], v[190:193], v[142:145]
	v_mfma_i32_16x16x64_i8 v[138:141], v[166:169], v[190:193], v[138:141]
	v_mfma_i32_16x16x64_i8 v[126:129], v[174:177], v[198:201], v[126:129]
	v_mfma_i32_16x16x64_i8 v[122:125], v[166:169], v[198:201], v[122:125]
	v_mfma_i32_16x16x64_i8 v[110:113], v[174:177], v[206:209], v[110:113]
	v_mfma_i32_16x16x64_i8 v[106:109], v[166:169], v[206:209], v[106:109]
	v_mfma_i32_16x16x64_i8 v[94:97], v[174:177], v[182:185], v[94:97]
	v_mfma_i32_16x16x64_i8 v[90:93], v[166:169], v[182:185], v[90:93]
	v_mfma_i32_16x16x64_i8 v[142:145], v[170:173], v[194:197], v[142:145]
	v_mfma_i32_16x16x64_i8 v[138:141], v[162:165], v[194:197], v[138:141]
	v_mfma_i32_16x16x64_i8 v[126:129], v[170:173], v[202:205], v[126:129]
	v_mfma_i32_16x16x64_i8 v[122:125], v[162:165], v[202:205], v[122:125]
	v_mfma_i32_16x16x64_i8 v[110:113], v[170:173], v[186:189], v[110:113]
	v_mfma_i32_16x16x64_i8 v[106:109], v[162:165], v[186:189], v[106:109]
	v_mfma_i32_16x16x64_i8 v[94:97], v[170:173], v[178:181], v[94:97]
	v_mfma_i32_16x16x64_i8 v[90:93], v[162:165], v[178:181], v[90:93]
	s_setprio 0
	s_setprio 1
	v_mfma_i32_16x16x64_i8 v[134:137], v[158:161], v[190:193], v[134:137]
	v_mfma_i32_16x16x64_i8 v[130:133], v[150:153], v[190:193], v[130:133]
	v_mfma_i32_16x16x64_i8 v[118:121], v[158:161], v[198:201], v[118:121]
	v_mfma_i32_16x16x64_i8 v[114:117], v[150:153], v[198:201], v[114:117]
	v_mfma_i32_16x16x64_i8 v[102:105], v[158:161], v[206:209], v[102:105]
	v_mfma_i32_16x16x64_i8 v[98:101], v[150:153], v[206:209], v[98:101]
	v_mfma_i32_16x16x64_i8 v[86:89], v[158:161], v[182:185], v[86:89]
	v_mfma_i32_16x16x64_i8 v[82:85], v[150:153], v[182:185], v[82:85]
	v_mfma_i32_16x16x64_i8 v[134:137], v[154:157], v[194:197], v[134:137]
	v_mfma_i32_16x16x64_i8 v[130:133], v[146:149], v[194:197], v[130:133]
	v_mfma_i32_16x16x64_i8 v[118:121], v[154:157], v[202:205], v[118:121]
	v_mfma_i32_16x16x64_i8 v[114:117], v[146:149], v[202:205], v[114:117]
	v_mfma_i32_16x16x64_i8 v[102:105], v[154:157], v[186:189], v[102:105]
	v_mfma_i32_16x16x64_i8 v[98:101], v[146:149], v[186:189], v[98:101]
	v_mfma_i32_16x16x64_i8 v[86:89], v[154:157], v[178:181], v[86:89]
	v_mfma_i32_16x16x64_i8 v[82:85], v[146:149], v[178:181], v[82:85]
	s_setprio 0
	s_barrier
; #define PG8_STAGE(bufoff, gbase, voff) do { _Pragma("unroll") for (int _i = 0; _i < 2; ++_i) \
;         __builtin_amdgcn_global_load_lds((const unsigned*)((const char*)(gbase) + (voff)[_i]), (PG8_LAS unsigned*)(lds + (bufoff) + ldsw + _i * 8192), 16, 0, 0); } while (0)
; #define PG8_LDA(dst, b, h) do { _Pragma("unroll") for (int m = 0; m < 4; ++m) _Pragma("unroll") for (int k = 0; k < 2; ++k) dst[m][k] = *(const PG8_LAS bf16x8*)(lds + PG8_SA(b, h) + aoff + m * 2048 + k * 1024); } while (0)
; #define PG8_LDB(dst, b, h) do { _Pragma("unroll") for (int n = 0; n < 2; ++n) _Pragma("unroll") for (int k = 0; k < 2; ++k) dst[n][k] = *(const PG8_LAS bf16x8*)(lds + PG8_SB(b, h) + boff + n * 2048 + k * 1024); } while (0)
; #define PG8_MMA(ai, bj, At, Bt) do { __builtin_amdgcn_s_setprio(1); _Pragma("unroll") for (int m = 0; m < 4; ++m) _Pragma("unroll") for (int n = 0; n < 2; ++n) _Pragma("unroll") for (int k = 0; k < 2; ++k) \
;         acc[ai][bj][m][n] = Gemm::i8 ? ::mfma16i8_g(Bt[n][k], At[m][k], acc[ai][bj][m][n]) : ::mfma16_g(Bt[n][k], At[m][k], acc[ai][bj][m][n]); __builtin_amdgcn_s_setprio(0); } while (0)
; #define PG8_WAIT_V(n) asm volatile("s_waitcnt vmcnt(" #n ")" ::: "memory")
; #define PG8_WAIT_L(n) asm volatile("s_waitcnt lgkmcnt(" #n ")" ::: "memory")
; #define PG8_BAR __builtin_amdgcn_s_barrier()
; #define PG8_SCHED __builtin_amdgcn_sched_barrier(0)
; template <class Epi, class Sched, class Gemm, bool ALIGN_EPI = false, bool SP2 = false>
; __device__ __forceinline__ void gemm_phase(PG8_LAS unsigned char* lds, const Gemm g, const Sched& S, const Epi& E) {
;     ...
;             PG8_LDA(At, 0, 1); PG8_STAGE(PG8_SB(0, 0), b2, voffB); PG8_STAGE(PG8_SB(0, 1), b2 + hB1, voffB1); PG8_STAGE(PG8_SA(0, 0), a2, voffA);
;             PG8_WAIT_V(8); PG8_WAIT_L(0); PG8_BAR; PG8_MMA(1, 0, At, B0); PG8_MMA(1, 1, At, B1); PG8_BAR; PG8_SCHED;
;             PG8_LDB(B0, 1, 0); PG8_LDB(B1, 1, 1); PG8_SCHED; PG8_LDA(At, 1, 0); PG8_STAGE(PG8_SA(0, 1), a2 + hstepA, voffA);
;             PG8_WAIT_V(8); PG8_WAIT_L(0); PG8_BAR; PG8_MMA(0, 0, At, B0); PG8_MMA(0, 1, At, B1); PG8_BAR; PG8_SCHED;
;             PG8_LDA(At, 1, 1); PG8_STAGE(PG8_SB(1, 0), b3, voffB); PG8_STAGE(PG8_SB(1, 1), b3 + hB1, voffB1); PG8_STAGE(PG8_SA(1, 0), a3, voffA);
	s_mov_b32 m0, s95
	v_lshl_add_u64 v[242:243], s[54:55], 0, v[212:213]
	ds_read_b128 v[190:193], v222 offset:16384
	ds_read_b128 v[194:197], v222 offset:17408
	ds_read_b128 v[198:201], v222 offset:18432
	ds_read_b128 v[202:205], v222 offset:19456
	ds_read_b128 v[206:209], v222 offset:20480
	ds_read_b128 v[186:189], v222 offset:21504
	ds_read_b128 v[182:185], v222 offset:22528
	ds_read_b128 v[178:181], v222 offset:23552
	global_load_lds_dwordx4 v212, s[54:55]
	v_lshl_add_u64 v[244:245], s[54:55], 0, v[216:217]
	s_mov_b32 m0, s92
	v_lshl_add_u64 v[246:247], s[56:57], 0, v[212:213]
	global_load_lds_dwordx4 v216, s[54:55]
	s_mov_b32 m0, s94
	v_lshl_add_u64 v[248:249], s[52:53], 0, v[214:215]
	global_load_lds_dwordx4 v212, s[56:57]
	s_mov_b32 m0, s93
	s_nop 0
	global_load_lds_dwordx4 v216, s[56:57]
	v_lshl_add_u64 v[246:247], s[52:53], 0, v[210:211]
	s_mov_b32 m0, s65
	s_nop 0
	global_load_lds_dwordx4 v210, s[52:53]
	s_mov_b32 m0, s66
	s_nop 0
	global_load_lds_dwordx4 v214, s[52:53]
	s_waitcnt vmcnt(8)
	s_waitcnt lgkmcnt(0)
	s_nop 0
	s_setprio 1
	s_barrier
	v_mfma_i32_16x16x64_i8 v[78:81], v[174:177], v[190:193], v[78:81]
	v_mfma_i32_16x16x64_i8 v[74:77], v[166:169], v[190:193], v[74:77]
	v_mfma_i32_16x16x64_i8 v[62:65], v[174:177], v[198:201], v[62:65]
	v_mfma_i32_16x16x64_i8 v[58:61], v[166:169], v[198:201], v[58:61]
	v_mfma_i32_16x16x64_i8 v[46:49], v[174:177], v[206:209], v[46:49]
	v_mfma_i32_16x16x64_i8 v[42:45], v[166:169], v[206:209], v[42:45]
	v_mfma_i32_16x16x64_i8 v[30:33], v[174:177], v[182:185], v[30:33]
	v_mfma_i32_16x16x64_i8 v[26:29], v[166:169], v[182:185], v[26:29]
	v_mfma_i32_16x16x64_i8 v[78:81], v[170:173], v[194:197], v[78:81]
	v_mfma_i32_16x16x64_i8 v[74:77], v[162:165], v[194:197], v[74:77]
	v_mfma_i32_16x16x64_i8 v[62:65], v[170:173], v[202:205], v[62:65]
	v_mfma_i32_16x16x64_i8 v[58:61], v[162:165], v[202:205], v[58:61]
	v_mfma_i32_16x16x64_i8 v[46:49], v[170:173], v[186:189], v[46:49]
	v_mfma_i32_16x16x64_i8 v[42:45], v[162:165], v[186:189], v[42:45]
	v_mfma_i32_16x16x64_i8 v[30:33], v[170:173], v[178:181], v[30:33]
	v_mfma_i32_16x16x64_i8 v[26:29], v[162:165], v[178:181], v[26:29]
	s_setprio 0
	s_setprio 1
	v_mfma_i32_16x16x64_i8 v[70:73], v[158:161], v[190:193], v[70:73]
	v_mfma_i32_16x16x64_i8 v[66:69], v[150:153], v[190:193], v[66:69]
	v_mfma_i32_16x16x64_i8 v[54:57], v[158:161], v[198:201], v[54:57]
	v_mfma_i32_16x16x64_i8 v[50:53], v[150:153], v[198:201], v[50:53]
	v_mfma_i32_16x16x64_i8 v[38:41], v[158:161], v[206:209], v[38:41]
	v_mfma_i32_16x16x64_i8 v[34:37], v[150:153], v[206:209], v[34:37]
	v_mfma_i32_16x16x64_i8 v[22:25], v[158:161], v[182:185], v[22:25]
	v_mfma_i32_16x16x64_i8 v[18:21], v[150:153], v[182:185], v[18:21]
	v_mfma_i32_16x16x64_i8 v[70:73], v[154:157], v[194:197], v[70:73]
	v_mfma_i32_16x16x64_i8 v[66:69], v[146:149], v[194:197], v[66:69]
	v_mfma_i32_16x16x64_i8 v[54:57], v[154:157], v[202:205], v[54:57]
	v_mfma_i32_16x16x64_i8 v[50:53], v[146:149], v[202:205], v[50:53]
	v_mfma_i32_16x16x64_i8 v[38:41], v[154:157], v[186:189], v[38:41]
	v_mfma_i32_16x16x64_i8 v[34:37], v[146:149], v[186:189], v[34:37]
	v_mfma_i32_16x16x64_i8 v[22:25], v[154:157], v[178:181], v[22:25]
	v_mfma_i32_16x16x64_i8 v[18:21], v[146:149], v[178:181], v[18:21]
	s_setprio 0
	s_barrier
	v_add_u32_e32 v146, s91, v251
	ds_read_b128 v[174:177], v146
	ds_read_b128 v[170:173], v146 offset:1024
	ds_read_b128 v[166:169], v146 offset:2048
	ds_read_b128 v[162:165], v146 offset:3072
	v_add_u32_e32 v146, s90, v251
	ds_read_b128 v[150:153], v146
	ds_read_b128 v[154:157], v146 offset:1024
	ds_read_b128 v[158:161], v146 offset:2048
	ds_read_b128 v[146:149], v146 offset:3072
	s_mov_b32 m0, s67
	ds_read_b128 v[190:193], v222 offset:32768
	ds_read_b128 v[194:197], v222 offset:33792
	ds_read_b128 v[198:201], v222 offset:34816
	ds_read_b128 v[202:205], v222 offset:35840
	ds_read_b128 v[206:209], v222 offset:36864
	ds_read_b128 v[186:189], v222 offset:37888
	ds_read_b128 v[182:185], v222 offset:38912
	ds_read_b128 v[178:181], v222 offset:39936
	global_load_lds_dwordx4 v210, s[50:51]
	s_mov_b32 m0, s68
	s_nop 0
	global_load_lds_dwordx4 v214, s[50:51]
	s_waitcnt vmcnt(8)
	s_waitcnt lgkmcnt(0)
	s_nop 0
	s_setprio 1
	s_barrier
; #define PG8_STAGE(bufoff, gbase, voff) do { _Pragma("unroll") for (int _i = 0; _i < 2; ++_i) \
;         __builtin_amdgcn_global_load_lds((const unsigned*)((const char*)(gbase) + (voff)[_i]), (PG8_LAS unsigned*)(lds + (bufoff) + ldsw + _i * 8192), 16, 0, 0); } while (0)
; #define PG8_LDA(dst, b, h) do { _Pragma("unroll") for (int m = 0; m < 4; ++m) _Pragma("unroll") for (int k = 0; k < 2; ++k) dst[m][k] = *(const PG8_LAS bf16x8*)(lds + PG8_SA(b, h) + aoff + m * 2048 + k * 1024); } while (0)
; #define PG8_LDB(dst, b, h) do { _Pragma("unroll") for (int n = 0; n < 2; ++n) _Pragma("unroll") for (int k = 0; k < 2; ++k) dst[n][k] = *(const PG8_LAS bf16x8*)(lds + PG8_SB(b, h) + boff + n * 2048 + k * 1024); } while (0)
; #define PG8_MMA(ai, bj, At, Bt) do { __builtin_amdgcn_s_setprio(1); _Pragma("unroll") for (int m = 0; m < 4; ++m) _Pragma("unroll") for (int n = 0; n < 2; ++n) _Pragma("unroll") for (int k = 0; k < 2; ++k) \
;         acc[ai][bj][m][n] = Gemm::i8 ? ::mfma16i8_g(Bt[n][k], At[m][k], acc[ai][bj][m][n]) : ::mfma16_g(Bt[n][k], At[m][k], acc[ai][bj][m][n]); __builtin_amdgcn_s_setprio(0); } while (0)
; #define PG8_WAIT_V(n) asm volatile("s_waitcnt vmcnt(" #n ")" ::: "memory")
; #define PG8_WAIT_L(n) asm volatile("s_waitcnt lgkmcnt(" #n ")" ::: "memory")
; #define PG8_BAR __builtin_amdgcn_s_barrier()
; #define PG8_SCHED __builtin_amdgcn_sched_barrier(0)
; template <class Epi, class Sched, class Gemm, bool ALIGN_EPI = false, bool SP2 = false>
; __device__ __forceinline__ void gemm_phase(PG8_LAS unsigned char* lds, const Gemm g, const Sched& S, const Epi& E) {
;     ...
;             PG8_LDB(B0, 1, 0); PG8_LDB(B1, 1, 1); PG8_SCHED; PG8_LDA(At, 1, 0); PG8_STAGE(PG8_SA(0, 1), a2 + hstepA, voffA);
;             PG8_WAIT_V(8); PG8_WAIT_L(0); PG8_BAR; PG8_MMA(0, 0, At, B0); PG8_MMA(0, 1, At, B1); PG8_BAR; PG8_SCHED;
;             PG8_LDA(At, 1, 1); PG8_STAGE(PG8_SB(1, 0), b3, voffB); PG8_STAGE(PG8_SB(1, 1), b3 + hB1, voffB1); PG8_STAGE(PG8_SA(1, 0), a3, voffA);
;             PG8_WAIT_V(8);
;             if constexpr (epi_pre<Epi>::value) { if (last) E.pre(pre, cur, wr, wc, lane); }
;             PG8_WAIT_L(0); PG8_BAR; PG8_MMA(1, 0, At, B0); PG8_MMA(1, 1, At, B1); PG8_BAR; PG8_SCHED;
	v_mfma_i32_16x16x64_i8 v[142:145], v[174:177], v[190:193], v[142:145]
	v_mfma_i32_16x16x64_i8 v[138:141], v[166:169], v[190:193], v[138:141]
	v_mfma_i32_16x16x64_i8 v[126:129], v[174:177], v[198:201], v[126:129]
	v_mfma_i32_16x16x64_i8 v[122:125], v[166:169], v[198:201], v[122:125]
	v_mfma_i32_16x16x64_i8 v[110:113], v[174:177], v[206:209], v[110:113]
	v_mfma_i32_16x16x64_i8 v[106:109], v[166:169], v[206:209], v[106:109]
	v_mfma_i32_16x16x64_i8 v[94:97], v[174:177], v[182:185], v[94:97]
	v_mfma_i32_16x16x64_i8 v[90:93], v[166:169], v[182:185], v[90:93]
	v_mfma_i32_16x16x64_i8 v[142:145], v[170:173], v[194:197], v[142:145]
	v_mfma_i32_16x16x64_i8 v[138:141], v[162:165], v[194:197], v[138:141]
	v_mfma_i32_16x16x64_i8 v[126:129], v[170:173], v[202:205], v[126:129]
	v_mfma_i32_16x16x64_i8 v[122:125], v[162:165], v[202:205], v[122:125]
	v_mfma_i32_16x16x64_i8 v[110:113], v[170:173], v[186:189], v[110:113]
	v_mfma_i32_16x16x64_i8 v[106:109], v[162:165], v[186:189], v[106:109]
	v_mfma_i32_16x16x64_i8 v[94:97], v[170:173], v[178:181], v[94:97]
	v_mfma_i32_16x16x64_i8 v[90:93], v[162:165], v[178:181], v[90:93]
	s_setprio 0
	s_setprio 1
	v_mfma_i32_16x16x64_i8 v[134:137], v[150:153], v[190:193], v[134:137]
	v_mfma_i32_16x16x64_i8 v[130:133], v[158:161], v[190:193], v[130:133]
	v_mfma_i32_16x16x64_i8 v[118:121], v[150:153], v[198:201], v[118:121]
	v_mfma_i32_16x16x64_i8 v[114:117], v[158:161], v[198:201], v[114:117]
	v_mfma_i32_16x16x64_i8 v[102:105], v[150:153], v[206:209], v[102:105]
	v_mfma_i32_16x16x64_i8 v[98:101], v[158:161], v[206:209], v[98:101]
	v_mfma_i32_16x16x64_i8 v[86:89], v[150:153], v[182:185], v[86:89]
	v_mfma_i32_16x16x64_i8 v[82:85], v[158:161], v[182:185], v[82:85]
	v_mfma_i32_16x16x64_i8 v[134:137], v[154:157], v[194:197], v[134:137]
	v_mfma_i32_16x16x64_i8 v[130:133], v[146:149], v[194:197], v[130:133]
	v_mfma_i32_16x16x64_i8 v[118:121], v[154:157], v[202:205], v[118:121]
	v_mfma_i32_16x16x64_i8 v[114:117], v[146:149], v[202:205], v[114:117]
	v_mfma_i32_16x16x64_i8 v[102:105], v[154:157], v[186:189], v[102:105]
	v_mfma_i32_16x16x64_i8 v[98:101], v[146:149], v[186:189], v[98:101]
	v_mfma_i32_16x16x64_i8 v[86:89], v[154:157], v[178:181], v[86:89]
	v_mfma_i32_16x16x64_i8 v[82:85], v[146:149], v[178:181], v[82:85]
	s_setprio 0
	s_barrier
	s_mov_b32 m0, s83
	v_lshl_add_u64 v[224:225], v[242:243], 0, s[36:37]
	ds_read_b128 v[206:209], v222 offset:49152
	ds_read_b128 v[202:205], v222 offset:50176
	ds_read_b128 v[194:197], v222 offset:51200
	ds_read_b128 v[198:201], v222 offset:52224
	ds_read_b128 v[186:189], v222 offset:53248
	ds_read_b128 v[190:193], v222 offset:54272
	ds_read_b128 v[182:185], v222 offset:55296
	ds_read_b128 v[178:181], v222 offset:56320
	global_load_lds_dwordx4 v[224:225], off
	v_lshl_add_u64 v[224:225], v[244:245], 0, s[36:37]
	s_mov_b32 m0, s3
	s_nop 0
	global_load_lds_dwordx4 v[224:225], off
	s_mov_b32 m0, s89
	s_nop 0
	global_load_lds_dwordx4 v212, s[0:1]
	s_mov_b32 m0, s88
	s_nop 0
	global_load_lds_dwordx4 v216, s[0:1]
	v_lshl_add_u64 v[224:225], v[246:247], 0, s[36:37]
	s_mov_b32 m0, s72
	s_nop 0
	global_load_lds_dwordx4 v[224:225], off
	v_lshl_add_u64 v[224:225], v[248:249], 0, s[36:37]
	s_mov_b32 m0, s73
	s_nop 0
	global_load_lds_dwordx4 v[224:225], off
	s_waitcnt vmcnt(8)
	s_cbranch_scc1 .LBB0_135
	s_branch .LBB0_135

; #define PG8_STAGE(bufoff, gbase, voff) do { _Pragma("unroll") for (int _i = 0; _i < 2; ++_i) \
;         __builtin_amdgcn_global_load_lds((const unsigned*)((const char*)(gbase) + (voff)[_i]), (PG8_LAS unsigned*)(lds + (bufoff) + ldsw + _i * 8192), 16, 0, 0); } while (0)
; #define PG8_LDA(dst, b, h) do { _Pragma("unroll") for (int m = 0; m < 4; ++m) _Pragma("unroll") for (int k = 0; k < 2; ++k) dst[m][k] = *(const PG8_LAS bf16x8*)(lds + PG8_SA(b, h) + aoff + m * 2048 + k * 1024); } while (0)
; #define PG8_LDB(dst, b, h) do { _Pragma("unroll") for (int n = 0; n < 2; ++n) _Pragma("unroll") for (int k = 0; k < 2; ++k) dst[n][k] = *(const PG8_LAS bf16x8*)(lds + PG8_SB(b, h) + boff + n * 2048 + k * 1024); } while (0)
; #define PG8_WAIT_V(n) asm volatile("s_waitcnt vmcnt(" #n ")" ::: "memory")
; #define PG8_WAIT_L(n) asm volatile("s_waitcnt lgkmcnt(" #n ")" ::: "memory")
; #define PG8_BAR __builtin_amdgcn_s_barrier()
; #define PG8_SCHED __builtin_amdgcn_sched_barrier(0)
; template <class Epi, class Sched, class Gemm, bool ALIGN_EPI = false, bool SP2 = false>
; __device__ __forceinline__ void gemm_phase(PG8_LAS unsigned char* lds, const Gemm g, const Sched& S, const Epi& E) {
;     ...
;             PG8_LDB(B0, 0, 0); PG8_LDB(B1, 0, 1); PG8_SCHED; PG8_LDA(At, 0, 0); PG8_STAGE(PG8_SA(1, 1), a1 + hstepA, voffA);
;             PG8_WAIT_V(8); PG8_WAIT_L(0); PG8_BAR; PG8_MMA(0, 0, At, B0); PG8_MMA(0, 1, At, B1); PG8_BAR; PG8_SCHED;
;             PG8_LDA(At, 0, 1); PG8_STAGE(PG8_SB(0, 0), b2, voffB); PG8_STAGE(PG8_SB(0, 1), b2 + hB1, voffB1); PG8_STAGE(PG8_SA(0, 0), a2, voffA);
;             PG8_WAIT_V(8); PG8_WAIT_L(0); PG8_BAR; PG8_MMA(1, 0, At, B0); PG8_MMA(1, 1, At, B1); PG8_BAR; PG8_SCHED;
;             PG8_LDB(B0, 1, 0); PG8_LDB(B1, 1, 1); PG8_SCHED; PG8_LDA(At, 1, 0); PG8_STAGE(PG8_SA(0, 1), a2 + hstepA, voffA);
;             PG8_WAIT_V(8); PG8_WAIT_L(0); PG8_BAR; PG8_MMA(0, 0, At, B0); PG8_MMA(0, 1, At, B1); PG8_BAR; PG8_SCHED;
;             PG8_LDA(At, 1, 1); PG8_STAGE(PG8_SB(1, 0), b3, voffB); PG8_STAGE(PG8_SB(1, 1), b3 + hB1, voffB1); PG8_STAGE(PG8_SA(1, 0), a3, voffA);
;             PG8_WAIT_V(8);
;             if constexpr (epi_pre<Epi>::value) { if (last) E.pre(pre, cur, wr, wc, lane); }
;             PG8_WAIT_L(0); PG8_BAR; PG8_MMA(1, 0, At, B0); PG8_MMA(1, 1, At, B1); PG8_BAR; PG8_SCHED;
.Lfw_0:
	s_waitcnt lgkmcnt(0)
	s_nop 0
	s_setprio 1
	s_barrier
	v_mfma_i32_16x16x64_i8 v[224:227], v[172:175], v[164:167], v[126:129]
	v_mfma_i32_16x16x64_i8 v[126:129], v[188:191], v[168:171], v[224:227]
	v_mfma_i32_16x16x64_i8 v[228:231], v[192:195], v[164:167], v[122:125]
	v_mfma_i32_16x16x64_i8 v[232:235], v[172:175], v[200:203], v[110:113]
	v_mfma_i32_16x16x64_i8 v[236:239], v[192:195], v[200:203], v[106:109]
	v_mfma_i32_16x16x64_i8 v[240:243], v[172:175], v[208:211], v[94:97]
	v_mfma_i32_16x16x64_i8 v[244:247], v[192:195], v[208:211], v[90:93]
	v_mfma_i32_16x16x64_i8 v[224:227], v[172:175], v[216:219], v[78:81]
	v_mfma_i32_16x16x64_i8 v[74:77], v[192:195], v[216:219], v[74:77]
	v_mfma_i32_16x16x64_i8 v[122:125], v[196:199], v[168:171], v[228:231]
	v_mfma_i32_16x16x64_i8 v[110:113], v[188:191], v[204:207], v[232:235]
	v_mfma_i32_16x16x64_i8 v[106:109], v[196:199], v[204:207], v[236:239]
	v_mfma_i32_16x16x64_i8 v[94:97], v[188:191], v[212:215], v[240:243]
	v_mfma_i32_16x16x64_i8 v[90:93], v[196:199], v[212:215], v[244:247]
	v_mfma_i32_16x16x64_i8 v[78:81], v[188:191], v[220:223], v[224:227]
	v_mfma_i32_16x16x64_i8 v[74:77], v[196:199], v[220:223], v[74:77]
	s_setprio 0
	s_setprio 1
	v_mfma_i32_16x16x64_i8 v[224:227], v[134:137], v[164:167], v[118:121]
	v_mfma_i32_16x16x64_i8 v[118:121], v[138:141], v[168:171], v[224:227]
	v_mfma_i32_16x16x64_i8 v[228:231], v[142:145], v[164:167], v[114:117]
	v_mfma_i32_16x16x64_i8 v[232:235], v[134:137], v[200:203], v[102:105]
	v_mfma_i32_16x16x64_i8 v[236:239], v[142:145], v[200:203], v[98:101]
	v_mfma_i32_16x16x64_i8 v[240:243], v[134:137], v[208:211], v[86:89]
	v_mfma_i32_16x16x64_i8 v[244:247], v[142:145], v[208:211], v[82:85]
	v_mfma_i32_16x16x64_i8 v[164:167], v[134:137], v[216:219], v[70:73]
	v_mfma_i32_16x16x64_i8 v[66:69], v[142:145], v[216:219], v[66:69]
	v_mfma_i32_16x16x64_i8 v[114:117], v[130:133], v[168:171], v[228:231]
	v_mfma_i32_16x16x64_i8 v[102:105], v[138:141], v[204:207], v[232:235]
	v_mfma_i32_16x16x64_i8 v[98:101], v[130:133], v[204:207], v[236:239]
	v_mfma_i32_16x16x64_i8 v[86:89], v[138:141], v[212:215], v[240:243]
	v_mfma_i32_16x16x64_i8 v[82:85], v[130:133], v[212:215], v[244:247]
	v_mfma_i32_16x16x64_i8 v[70:73], v[138:141], v[220:223], v[164:167]
	v_mfma_i32_16x16x64_i8 v[66:69], v[130:133], v[220:223], v[66:69]
	s_setprio 0
	s_barrier
	s_add_i32 s65, s55, s33
	v_lshl_add_u64 v[164:165], s[40:41], 0, v[148:149]
	s_mov_b32 m0, s65
	ds_read_b128 v[200:203], v187 offset:16384
	ds_read_b128 v[204:207], v187 offset:17408
	ds_read_b128 v[208:211], v187 offset:18432
	ds_read_b128 v[212:215], v187 offset:19456
	ds_read_b128 v[216:219], v187 offset:20480
	ds_read_b128 v[220:223], v187 offset:21504
	ds_read_b128 v[224:227], v187 offset:22528
	ds_read_b128 v[228:231], v187 offset:23552
	global_load_lds_dwordx4 v148, s[40:41]
	s_add_i32 m0, s65, 0x2000
	s_add_u32 s66, s40, 0x2000
	v_lshl_add_u64 v[166:167], s[40:41], 0, v[152:153]
	s_addc_u32 s67, s41, 0
	s_add_i32 s65, s56, s33
	global_load_lds_dwordx4 v152, s[40:41]
	s_mov_b32 m0, s65
	v_lshl_add_u64 v[168:169], s[2:3], 0, v[146:147]
	global_load_lds_dwordx4 v148, s[66:67]
	v_lshl_add_u64 v[160:161], s[66:67], 0, v[152:153]
	s_add_i32 m0, s65, 0x2000
	v_lshl_add_u64 v[170:171], s[2:3], 0, v[150:151]
	global_load_lds_dwordx4 v152, s[66:67]
	s_mov_b32 m0, s39
	s_nop 0
	global_load_lds_dwordx4 v146, s[2:3]
	s_mov_b32 m0, s46
	s_nop 0
	global_load_lds_dwordx4 v150, s[2:3]
	s_cbranch_vccnz .Lfw_1
	s_waitcnt vmcnt(8)
.Lfw_1:
	s_waitcnt lgkmcnt(0)
	s_nop 0
	s_setprio 1
	s_barrier
	v_mfma_i32_16x16x64_i8 v[232:235], v[172:175], v[200:203], v[62:65]
	v_mfma_i32_16x16x64_i8 v[62:65], v[188:191], v[204:207], v[232:235]
	v_mfma_i32_16x16x64_i8 v[236:239], v[192:195], v[200:203], v[58:61]
	v_mfma_i32_16x16x64_i8 v[240:243], v[172:175], v[208:211], v[46:49]
	v_mfma_i32_16x16x64_i8 v[244:247], v[192:195], v[208:211], v[42:45]
	v_mfma_i32_16x16x64_i8 v[248:251], v[172:175], v[216:219], v[30:33]
	v_mfma_i32_16x16x64_i8 v[160:163], v[192:195], v[216:219], v[26:29]
	v_mfma_i32_16x16x64_i8 v[232:235], v[172:175], v[224:227], v[14:17]
	v_mfma_i32_16x16x64_i8 v[10:13], v[192:195], v[224:227], v[10:13]
	v_mfma_i32_16x16x64_i8 v[58:61], v[196:199], v[204:207], v[236:239]
	v_mfma_i32_16x16x64_i8 v[46:49], v[188:191], v[212:215], v[240:243]
	v_mfma_i32_16x16x64_i8 v[42:45], v[196:199], v[212:215], v[244:247]
	v_mfma_i32_16x16x64_i8 v[30:33], v[188:191], v[220:223], v[248:251]
	v_mfma_i32_16x16x64_i8 v[26:29], v[196:199], v[220:223], v[160:163]
	v_mfma_i32_16x16x64_i8 v[14:17], v[188:191], v[228:231], v[232:235]
	v_mfma_i32_16x16x64_i8 v[10:13], v[196:199], v[228:231], v[10:13]
	s_setprio 0
	s_setprio 1
	v_mfma_i32_16x16x64_i8 v[160:163], v[134:137], v[200:203], v[54:57]
	v_mfma_i32_16x16x64_i8 v[54:57], v[138:141], v[204:207], v[160:163]
	v_mfma_i32_16x16x64_i8 v[172:175], v[142:145], v[200:203], v[50:53]
	v_mfma_i32_16x16x64_i8 v[188:191], v[134:137], v[208:211], v[38:41]
	v_mfma_i32_16x16x64_i8 v[192:195], v[142:145], v[208:211], v[34:37]
	v_mfma_i32_16x16x64_i8 v[196:199], v[134:137], v[216:219], v[22:25]
	v_mfma_i32_16x16x64_i8 v[232:235], v[142:145], v[216:219], v[18:21]
	v_mfma_i32_16x16x64_i8 v[160:163], v[134:137], v[224:227], v[6:9]
	v_mfma_i32_16x16x64_i8 v[2:5], v[142:145], v[224:227], v[2:5]
	v_mfma_i32_16x16x64_i8 v[50:53], v[130:133], v[204:207], v[172:175]
	v_mfma_i32_16x16x64_i8 v[38:41], v[138:141], v[212:215], v[188:191]
	v_mfma_i32_16x16x64_i8 v[34:37], v[130:133], v[212:215], v[192:195]
	v_mfma_i32_16x16x64_i8 v[22:25], v[138:141], v[220:223], v[196:199]
	v_mfma_i32_16x16x64_i8 v[18:21], v[130:133], v[220:223], v[232:235]
	v_mfma_i32_16x16x64_i8 v[6:9], v[138:141], v[228:231], v[160:163]
	v_mfma_i32_16x16x64_i8 v[2:5], v[130:133], v[228:231], v[2:5]
	s_setprio 0
	s_barrier
; #define PG8_STAGE(bufoff, gbase, voff) do { _Pragma("unroll") for (int _i = 0; _i < 2; ++_i) \
;         __builtin_amdgcn_global_load_lds((const unsigned*)((const char*)(gbase) + (voff)[_i]), (PG8_LAS unsigned*)(lds + (bufoff) + ldsw + _i * 8192), 16, 0, 0); } while (0)
; #define PG8_LDA(dst, b, h) do { _Pragma("unroll") for (int m = 0; m < 4; ++m) _Pragma("unroll") for (int k = 0; k < 2; ++k) dst[m][k] = *(const PG8_LAS bf16x8*)(lds + PG8_SA(b, h) + aoff + m * 2048 + k * 1024); } while (0)
; #define PG8_LDB(dst, b, h) do { _Pragma("unroll") for (int n = 0; n < 2; ++n) _Pragma("unroll") for (int k = 0; k < 2; ++k) dst[n][k] = *(const PG8_LAS bf16x8*)(lds + PG8_SB(b, h) + boff + n * 2048 + k * 1024); } while (0)
; #define PG8_MMA(ai, bj, At, Bt) do { __builtin_amdgcn_s_setprio(1); _Pragma("unroll") for (int m = 0; m < 4; ++m) _Pragma("unroll") for (int n = 0; n < 2; ++n) _Pragma("unroll") for (int k = 0; k < 2; ++k) \
;         acc[ai][bj][m][n] = Gemm::i8 ? ::mfma16i8_g(Bt[n][k], At[m][k], acc[ai][bj][m][n]) : ::mfma16_g(Bt[n][k], At[m][k], acc[ai][bj][m][n]); __builtin_amdgcn_s_setprio(0); } while (0)
; #define PG8_WAIT_V(n) asm volatile("s_waitcnt vmcnt(" #n ")" ::: "memory")
; #define PG8_WAIT_L(n) asm volatile("s_waitcnt lgkmcnt(" #n ")" ::: "memory")
; #define PG8_BAR __builtin_amdgcn_s_barrier()
; #define PG8_SCHED __builtin_amdgcn_sched_barrier(0)
; template <class Epi, class Sched, class Gemm, bool ALIGN_EPI = false, bool SP2 = false>
; __device__ __forceinline__ void gemm_phase(PG8_LAS unsigned char* lds, const Gemm g, const Sched& S, const Epi& E) {
;     ...
;             PG8_LDB(B0, 1, 0); PG8_LDB(B1, 1, 1); PG8_SCHED; PG8_LDA(At, 1, 0); PG8_STAGE(PG8_SA(0, 1), a2 + hstepA, voffA);
;             PG8_WAIT_V(8); PG8_WAIT_L(0); PG8_BAR; PG8_MMA(0, 0, At, B0); PG8_MMA(0, 1, At, B1); PG8_BAR; PG8_SCHED;
;             PG8_LDA(At, 1, 1); PG8_STAGE(PG8_SB(1, 0), b3, voffB); PG8_STAGE(PG8_SB(1, 1), b3 + hB1, voffB1); PG8_STAGE(PG8_SA(1, 0), a3, voffA);
;             PG8_WAIT_V(8);
;             if constexpr (epi_pre<Epi>::value) { if (last) E.pre(pre, cur, wr, wc, lane); }
;             PG8_WAIT_L(0); PG8_BAR; PG8_MMA(1, 0, At, B0); PG8_MMA(1, 1, At, B1); PG8_BAR; PG8_SCHED;
	s_add_i32 s65, 0, 0x18000
	s_add_i32 s66, 0, 0x1c000
	v_add_u32_e32 v130, s65, v181
	v_add_u32_e32 v131, s66, v181
	ds_read_b128 v[160:163], v130
	ds_read_b128 v[172:175], v130 offset:1024
	ds_read_b128 v[188:191], v130 offset:2048
	ds_read_b128 v[192:195], v130 offset:3072
	ds_read_b128 v[134:137], v131
	ds_read_b128 v[138:141], v131 offset:1024
	ds_read_b128 v[142:145], v131 offset:2048
	ds_read_b128 v[130:133], v131 offset:3072
	s_add_u32 s2, s2, 0x20000
	s_addc_u32 s3, s3, 0
	s_mov_b32 m0, s47
	ds_read_b128 v[196:199], v187 offset:32768
	ds_read_b128 v[200:203], v187 offset:33792
	ds_read_b128 v[204:207], v187 offset:34816
	ds_read_b128 v[208:211], v187 offset:35840
	ds_read_b128 v[212:215], v187 offset:36864
	ds_read_b128 v[216:219], v187 offset:37888
	ds_read_b128 v[220:223], v187 offset:38912
	ds_read_b128 v[224:227], v187 offset:39936
	global_load_lds_dwordx4 v146, s[2:3]
	v_lshl_add_u64 v[176:177], s[2:3], 0, v[150:151]
	s_mov_b32 m0, s48
	s_nop 0
	global_load_lds_dwordx4 v150, s[2:3]
	s_waitcnt vmcnt(8)
	s_waitcnt lgkmcnt(0)
	s_nop 0
	s_setprio 1
	s_barrier
	v_mfma_i32_16x16x64_i8 v[228:231], v[160:163], v[196:199], v[126:129]
	v_mfma_i32_16x16x64_i8 v[126:129], v[172:175], v[200:203], v[228:231]
	v_mfma_i32_16x16x64_i8 v[232:235], v[188:191], v[196:199], v[122:125]
	v_mfma_i32_16x16x64_i8 v[236:239], v[160:163], v[204:207], v[110:113]
	v_mfma_i32_16x16x64_i8 v[240:243], v[188:191], v[204:207], v[106:109]
	v_mfma_i32_16x16x64_i8 v[244:247], v[160:163], v[212:215], v[94:97]
	v_mfma_i32_16x16x64_i8 v[248:251], v[188:191], v[212:215], v[90:93]
	v_mfma_i32_16x16x64_i8 v[228:231], v[160:163], v[220:223], v[78:81]
	v_mfma_i32_16x16x64_i8 v[74:77], v[188:191], v[220:223], v[74:77]
	v_mfma_i32_16x16x64_i8 v[122:125], v[192:195], v[200:203], v[232:235]
	v_mfma_i32_16x16x64_i8 v[110:113], v[172:175], v[208:211], v[236:239]
	v_mfma_i32_16x16x64_i8 v[106:109], v[192:195], v[208:211], v[240:243]
	v_mfma_i32_16x16x64_i8 v[94:97], v[172:175], v[216:219], v[244:247]
	v_mfma_i32_16x16x64_i8 v[90:93], v[192:195], v[216:219], v[248:251]
	v_mfma_i32_16x16x64_i8 v[78:81], v[172:175], v[224:227], v[228:231]
	v_mfma_i32_16x16x64_i8 v[74:77], v[192:195], v[224:227], v[74:77]
	s_setprio 0
	s_setprio 1
	v_mfma_i32_16x16x64_i8 v[228:231], v[134:137], v[196:199], v[118:121]
	v_mfma_i32_16x16x64_i8 v[118:121], v[138:141], v[200:203], v[228:231]
	v_mfma_i32_16x16x64_i8 v[232:235], v[142:145], v[196:199], v[114:117]
	v_mfma_i32_16x16x64_i8 v[236:239], v[134:137], v[204:207], v[102:105]
	v_mfma_i32_16x16x64_i8 v[240:243], v[142:145], v[204:207], v[98:101]
	v_mfma_i32_16x16x64_i8 v[244:247], v[134:137], v[212:215], v[86:89]
	v_mfma_i32_16x16x64_i8 v[248:251], v[142:145], v[212:215], v[82:85]
	v_mfma_i32_16x16x64_i8 v[196:199], v[134:137], v[220:223], v[70:73]
	v_mfma_i32_16x16x64_i8 v[66:69], v[142:145], v[220:223], v[66:69]
	v_mfma_i32_16x16x64_i8 v[114:117], v[130:133], v[200:203], v[232:235]
	v_mfma_i32_16x16x64_i8 v[102:105], v[138:141], v[208:211], v[236:239]
	v_mfma_i32_16x16x64_i8 v[98:101], v[130:133], v[208:211], v[240:243]
	v_mfma_i32_16x16x64_i8 v[86:89], v[138:141], v[216:219], v[244:247]
	v_mfma_i32_16x16x64_i8 v[82:85], v[130:133], v[216:219], v[248:251]
	v_mfma_i32_16x16x64_i8 v[70:73], v[138:141], v[224:227], v[196:199]
	v_mfma_i32_16x16x64_i8 v[66:69], v[130:133], v[224:227], v[66:69]
	s_setprio 0
	s_barrier
	s_add_i32 s2, s65, s33
	v_lshl_add_u64 v[164:165], v[164:165], 0, s[18:19]
	s_mov_b32 m0, s2
	ds_read_b128 v[196:199], v187 offset:49152
	ds_read_b128 v[200:203], v187 offset:50176
	ds_read_b128 v[204:207], v187 offset:51200
	ds_read_b128 v[208:211], v187 offset:52224
	ds_read_b128 v[212:215], v187 offset:53248
	ds_read_b128 v[216:219], v187 offset:54272
	ds_read_b128 v[220:223], v187 offset:55296
	ds_read_b128 v[224:227], v187 offset:56320
	global_load_lds_dwordx4 v[164:165], off
	s_add_i32 m0, s2, 0x2000
	s_add_u32 s2, s40, 0x2080
	v_lshl_add_u64 v[164:165], v[166:167], 0, s[18:19]
	s_addc_u32 s3, s41, 0
	s_add_i32 s40, s66, s33
	global_load_lds_dwordx4 v[164:165], off
	s_mov_b32 m0, s40
	s_nop 0
	global_load_lds_dwordx4 v148, s[2:3]
	s_add_i32 m0, s40, 0x2000
	s_nop 0
	global_load_lds_dwordx4 v152, s[2:3]
	v_lshl_add_u64 v[164:165], v[168:169], 0, s[18:19]
	s_mov_b32 m0, s51
	s_nop 0
	global_load_lds_dwordx4 v[164:165], off
	v_lshl_add_u64 v[164:165], v[170:171], 0, s[18:19]
	s_mov_b32 m0, s52
	s_nop 0
	global_load_lds_dwordx4 v[164:165], off
	s_waitcnt vmcnt(8)
	s_waitcnt lgkmcnt(0)
	s_nop 0
	s_setprio 1
	s_barrier
	v_mfma_i32_16x16x64_i8 v[164:167], v[160:163], v[196:199], v[62:65]
	v_mfma_i32_16x16x64_i8 v[62:65], v[172:175], v[200:203], v[164:167]
	v_mfma_i32_16x16x64_i8 v[168:171], v[188:191], v[196:199], v[58:61]
	v_mfma_i32_16x16x64_i8 v[228:231], v[160:163], v[204:207], v[46:49]
	v_mfma_i32_16x16x64_i8 v[232:235], v[188:191], v[204:207], v[42:45]
	v_mfma_i32_16x16x64_i8 v[236:239], v[160:163], v[212:215], v[30:33]
	v_mfma_i32_16x16x64_i8 v[240:243], v[188:191], v[212:215], v[26:29]
	v_mfma_i32_16x16x64_i8 v[164:167], v[160:163], v[220:223], v[14:17]
	v_mfma_i32_16x16x64_i8 v[10:13], v[188:191], v[220:223], v[10:13]
	v_mfma_i32_16x16x64_i8 v[58:61], v[192:195], v[200:203], v[168:171]
	v_mfma_i32_16x16x64_i8 v[46:49], v[172:175], v[208:211], v[228:231]
	v_mfma_i32_16x16x64_i8 v[42:45], v[192:195], v[208:211], v[232:235]
	v_mfma_i32_16x16x64_i8 v[30:33], v[172:175], v[216:219], v[236:239]
	v_mfma_i32_16x16x64_i8 v[26:29], v[192:195], v[216:219], v[240:243]
	v_mfma_i32_16x16x64_i8 v[14:17], v[172:175], v[224:227], v[164:167]
	v_mfma_i32_16x16x64_i8 v[10:13], v[192:195], v[224:227], v[10:13]
	s_setprio 0
	s_setprio 1
	v_mfma_i32_16x16x64_i8 v[160:163], v[134:137], v[196:199], v[54:57]
	v_mfma_i32_16x16x64_i8 v[54:57], v[138:141], v[200:203], v[160:163]
	v_mfma_i32_16x16x64_i8 v[164:167], v[142:145], v[196:199], v[50:53]
	v_mfma_i32_16x16x64_i8 v[168:171], v[134:137], v[204:207], v[38:41]
	v_mfma_i32_16x16x64_i8 v[172:175], v[142:145], v[204:207], v[34:37]
	v_mfma_i32_16x16x64_i8 v[188:191], v[134:137], v[212:215], v[22:25]
	v_mfma_i32_16x16x64_i8 v[192:195], v[142:145], v[212:215], v[18:21]
	v_mfma_i32_16x16x64_i8 v[160:163], v[134:137], v[220:223], v[6:9]
	v_mfma_i32_16x16x64_i8 v[2:5], v[142:145], v[220:223], v[2:5]
	v_mfma_i32_16x16x64_i8 v[50:53], v[130:133], v[200:203], v[164:167]
	v_mfma_i32_16x16x64_i8 v[38:41], v[138:141], v[208:211], v[168:171]
	v_mfma_i32_16x16x64_i8 v[34:37], v[130:133], v[208:211], v[172:175]
	v_mfma_i32_16x16x64_i8 v[22:25], v[138:141], v[216:219], v[188:191]
	v_mfma_i32_16x16x64_i8 v[18:21], v[130:133], v[216:219], v[192:195]
	v_mfma_i32_16x16x64_i8 v[6:9], v[138:141], v[224:227], v[160:163]
	v_mfma_i32_16x16x64_i8 v[2:5], v[130:133], v[224:227], v[2:5]
	s_setprio 0
	s_barrier
;     __device__ __forceinline__ void operator()(const f32x4 (&acc)[2][2][4][2], const Unit& u, int wr, int wc, int fr, int fq) const {
;         asm volatile("" : "+v"(fr), "+v"(fq));
;         const int row0 = u.pm * BM + wr * 64 + fr, col0 = u.pn * BM + wc * 64 + 16 * fq;
;         const int gn = u.pn >> 2, gbase = (gn < 3) ? 3072 + 1024 * gn : 0;
;         f32x4 bv[2][2];
; #pragma unroll
;         for (int bj = 0; bj < 2; ++bj)
; #pragma unroll
;             for (int n = 0; n < 2; ++n) bv[bj][n] = *(const f32x4*)(bias + col0 + 8 * bj + 4 * n) * -1.44269504f;
;         f32x4 wv[2][2];
; #pragma unroll
;         for (int bj = 0; bj < 2; ++bj)
; #pragma unroll
;             for (int n = 0; n < 2; ++n) wv[bj][n] = *(const f32x4*)(SW + col0 + 8 * bj + 4 * n) * -1.44269504f;
;         float rsv[8];
; #pragma unroll
;         for (int i = 0; i < 8; ++i) rsv[i] = SH[row0 + (i >> 2) * HALF + (i & 3) * 16];
	s_add_i32 s64, s64, 2
	s_add_u32 s62, s62, 0x100
	s_addc_u32 s63, s63, 0
	s_add_u32 s0, s0, 0x100
	s_addc_u32 s1, s1, 0
	s_cmp_gt_u32 s64, 5
	s_mov_b64 vcc, 0
	s_cbranch_scc0 .LBB0_1192
	s_lshl_b32 s0, s59, 8
	v_mov_b32_e32 v130, v179
	v_mov_b32_e32 v154, v1
	s_or_b32 s0, s0, s53
	v_cvt_f32_i32_e32 v212, v122
	v_lshl_add_u32 v144, v130, 4, s0
	s_lshl_b32 s0, s38, 8
	v_ashrrev_i32_e32 v145, 31, v144
	s_add_i32 s0, s0, s50
	v_lshlrev_b64 v[142:143], 2, v[144:145]
	v_add_u32_e32 v164, s0, v154
	v_lshl_add_u64 v[160:161], s[10:11], 0, v[142:143]
	v_ashrrev_i32_e32 v165, 31, v164
	global_load_dwordx4 v[130:133], v[160:161], off
	global_load_dwordx4 v[134:137], v[160:161], off offset:16
	global_load_dwordx4 v[138:141], v[160:161], off offset:32
	s_nop 0
	global_load_dwordx4 v[160:163], v[160:161], off offset:48
	v_lshl_add_u64 v[142:143], s[14:15], 0, v[142:143]
	v_lshl_add_u64 v[170:171], v[164:165], 2, s[16:17]
	global_load_dwordx4 v[166:169], v[142:143], off
	global_load_dwordx4 v[194:197], v[142:143], off offset:16
	global_load_dwordx4 v[198:201], v[142:143], off offset:32
	global_load_dwordx4 v[202:205], v[142:143], off offset:48
	global_load_dword v206, v[170:171], off
	global_load_dword v188, v[170:171], off offset:64
	global_load_dword v186, v[170:171], off offset:128
	global_load_dword v184, v[170:171], off offset:192
	global_load_dword v182, v[170:171], off offset:512
	global_load_dword v180, v[170:171], off offset:576
	global_load_dword v178, v[170:171], off offset:640
	global_load_dword v122, v[170:171], off offset:704
	s_ashr_i32 s0, s59, 2
	s_lshl_b32 s1, s0, 10
	v_mov_b64_e32 v[142:143], s[12:13]
	s_add_i32 s2, s1, 0xc00
	v_cvt_f32_i32_e32 v209, v127
	v_cvt_f32_i32_e32 v208, v126
	v_cvt_f32_i32_e32 v215, v125
	v_cvt_f32_i32_e32 v214, v124
	s_cmp_lt_i32 s0, 3
	v_mad_i64_i32 v[124:125], s[0:1], v164, s57, v[142:143]
	s_cselect_b32 s0, s2, 0
	v_cvt_f32_i32_e32 v211, v129
	v_cvt_f32_i32_e32 v210, v128
	s_ashr_i32 s1, s0, 31
	v_cvt_f32_i32_e32 v115, v115
	v_cvt_f32_i32_e32 v114, v114
	v_cvt_f32_i32_e32 v99, v99
	v_cvt_f32_i32_e32 v98, v98
	v_cvt_f32_i32_e32 v83, v83
	v_cvt_f32_i32_e32 v82, v82
	v_cvt_f32_i32_e32 v67, v67
	v_cvt_f32_i32_e32 v66, v66
	v_cvt_f32_i32_e32 v51, v51
	v_cvt_f32_i32_e32 v50, v50
	v_cvt_f32_i32_e32 v35, v35
	v_cvt_f32_i32_e32 v34, v34
	v_cvt_f32_i32_e32 v19, v19
	v_cvt_f32_i32_e32 v18, v18
	v_and_b32_e32 v154, 0x3f0, v144
	v_lshl_add_u64 v[124:125], v[124:125], 0, s[0:1]
	v_cvt_f32_i32_e32 v117, v117
	v_cvt_f32_i32_e32 v116, v116
	v_cvt_f32_i32_e32 v111, v111
	v_cvt_f32_i32_e32 v110, v110
	v_cvt_f32_i32_e32 v101, v101
	v_cvt_f32_i32_e32 v100, v100
	v_cvt_f32_i32_e32 v95, v95
	v_cvt_f32_i32_e32 v94, v94
	v_cvt_f32_i32_e32 v85, v85
	v_cvt_f32_i32_e32 v84, v84
	v_cvt_f32_i32_e32 v79, v79
	v_cvt_f32_i32_e32 v78, v78
	v_cvt_f32_i32_e32 v69, v69
	v_cvt_f32_i32_e32 v68, v68
	v_cvt_f32_i32_e32 v63, v63
	v_cvt_f32_i32_e32 v62, v62
	v_cvt_f32_i32_e32 v53, v53
	v_cvt_f32_i32_e32 v52, v52
	v_cvt_f32_i32_e32 v47, v47
	v_cvt_f32_i32_e32 v46, v46
	v_cvt_f32_i32_e32 v37, v37
	v_cvt_f32_i32_e32 v36, v36
	v_cvt_f32_i32_e32 v31, v31
	v_cvt_f32_i32_e32 v30, v30
	v_cvt_f32_i32_e32 v21, v21
	v_cvt_f32_i32_e32 v20, v20
	v_cvt_f32_i32_e32 v15, v15
	v_cvt_f32_i32_e32 v14, v14
	v_add_u32_e32 v207, 32, v164
	v_lshl_add_u64 v[216:217], v[124:125], 0, v[154:155]
	v_add_u32_e32 v189, 0xa0, v164
	v_cvt_f32_i32_e32 v213, v123
	v_add_u32_e32 v123, 0xb0, v164
	v_cvt_f32_i32_e32 v119, v119
	v_cvt_f32_i32_e32 v118, v118
	v_cvt_f32_i32_e32 v109, v109
	v_cvt_f32_i32_e32 v108, v108
	v_cvt_f32_i32_e32 v103, v103
	v_cvt_f32_i32_e32 v102, v102
	v_cvt_f32_i32_e32 v93, v93
	v_cvt_f32_i32_e32 v121, v121
	v_cvt_f32_i32_e32 v120, v120
	v_cvt_f32_i32_e32 v113, v113
	v_cvt_f32_i32_e32 v112, v112
	v_cvt_f32_i32_e32 v107, v107
	v_cvt_f32_i32_e32 v106, v106
	v_cvt_f32_i32_e32 v105, v105
	v_cvt_f32_i32_e32 v104, v104
	v_cvt_f32_i32_e32 v92, v92
	v_cvt_f32_i32_e32 v87, v87
	v_cvt_f32_i32_e32 v86, v86
	v_cvt_f32_i32_e32 v97, v97
	v_cvt_f32_i32_e32 v96, v96
	v_cvt_f32_i32_e32 v91, v91
	v_cvt_f32_i32_e32 v90, v90
	v_cvt_f32_i32_e32 v89, v89
	v_cvt_f32_i32_e32 v88, v88
	v_cvt_f32_i32_e32 v77, v77
	v_cvt_f32_i32_e32 v76, v76
	v_cvt_f32_i32_e32 v71, v71
	v_cvt_f32_i32_e32 v70, v70
	v_cvt_f32_i32_e32 v81, v81
	v_cvt_f32_i32_e32 v80, v80
	v_cvt_f32_i32_e32 v75, v75
	v_cvt_f32_i32_e32 v74, v74
	v_cvt_f32_i32_e32 v73, v73
	v_cvt_f32_i32_e32 v72, v72
	v_cvt_f32_i32_e32 v61, v61
	v_cvt_f32_i32_e32 v60, v60
	v_cvt_f32_i32_e32 v55, v55
	v_cvt_f32_i32_e32 v54, v54
	v_cvt_f32_i32_e32 v65, v65
	v_cvt_f32_i32_e32 v64, v64
	v_cvt_f32_i32_e32 v59, v59
	v_cvt_f32_i32_e32 v58, v58
	v_cvt_f32_i32_e32 v57, v57
	v_cvt_f32_i32_e32 v56, v56
	v_cvt_f32_i32_e32 v45, v45
	v_cvt_f32_i32_e32 v44, v44
	v_cvt_f32_i32_e32 v39, v39
	v_cvt_f32_i32_e32 v38, v38
	v_cvt_f32_i32_e32 v49, v49
	v_cvt_f32_i32_e32 v48, v48
	v_cvt_f32_i32_e32 v43, v43
	v_cvt_f32_i32_e32 v42, v42
	v_cvt_f32_i32_e32 v41, v41
	v_cvt_f32_i32_e32 v40, v40
	v_cvt_f32_i32_e32 v29, v29
	v_cvt_f32_i32_e32 v28, v28
	v_cvt_f32_i32_e32 v23, v23
	v_cvt_f32_i32_e32 v22, v22
	v_cvt_f32_i32_e32 v33, v33
	v_cvt_f32_i32_e32 v32, v32
	v_cvt_f32_i32_e32 v27, v27
	v_cvt_f32_i32_e32 v26, v26
	v_cvt_f32_i32_e32 v25, v25
	v_cvt_f32_i32_e32 v24, v24
	v_cvt_f32_i32_e32 v7, v7
	v_cvt_f32_i32_e32 v6, v6
	v_cvt_f32_i32_e32 v3, v3
	v_cvt_f32_i32_e32 v2, v2
	v_cvt_f32_i32_e32 v17, v17
	v_cvt_f32_i32_e32 v16, v16
	v_cvt_f32_i32_e32 v11, v11
	v_cvt_f32_i32_e32 v13, v13
	v_cvt_f32_i32_e32 v12, v12
	v_cvt_f32_i32_e32 v10, v10
	v_cvt_f32_i32_e32 v9, v9
	v_cvt_f32_i32_e32 v8, v8
	v_cvt_f32_i32_e32 v5, v5
	v_cvt_f32_i32_e32 v4, v4
	s_and_b64 vcc, exec, s[20:21]
	s_cbranch_vccz .LBB0_1195
	s_barrier

; #define PG8_STAGE(bufoff, gbase, voff) do { _Pragma("unroll") for (int _i = 0; _i < 2; ++_i) \
;         __builtin_amdgcn_global_load_lds((const unsigned*)((const char*)(gbase) + (voff)[_i]), (PG8_LAS unsigned*)(lds + (bufoff) + ldsw + _i * 8192), 16, 0, 0); } while (0)
; #define PG8_LDA(dst, b, h) do { _Pragma("unroll") for (int m = 0; m < 4; ++m) _Pragma("unroll") for (int k = 0; k < 2; ++k) dst[m][k] = *(const PG8_LAS bf16x8*)(lds + PG8_SA(b, h) + aoff + m * 2048 + k * 1024); } while (0)
; #define PG8_LDB(dst, b, h) do { _Pragma("unroll") for (int n = 0; n < 2; ++n) _Pragma("unroll") for (int k = 0; k < 2; ++k) dst[n][k] = *(const PG8_LAS bf16x8*)(lds + PG8_SB(b, h) + boff + n * 2048 + k * 1024); } while (0)
; #define PG8_WAIT_V(n) asm volatile("s_waitcnt vmcnt(" #n ")" ::: "memory")
; #define PG8_WAIT_L(n) asm volatile("s_waitcnt lgkmcnt(" #n ")" ::: "memory")
; #define PG8_BAR __builtin_amdgcn_s_barrier()
; #define PG8_SCHED __builtin_amdgcn_sched_barrier(0)
; template <class Epi, class Sched, class Gemm, bool ALIGN_EPI = false, bool SP2 = false>
; __device__ __forceinline__ void gemm_phase(PG8_LAS unsigned char* lds, const Gemm g, const Sched& S, const Epi& E) {
;     ...
;             PG8_LDB(B0, 0, 0); PG8_LDB(B1, 0, 1); PG8_SCHED; PG8_LDA(At, 0, 0); PG8_STAGE(PG8_SA(1, 1), a1 + hstepA, voffA);
;             PG8_WAIT_V(8); PG8_WAIT_L(0); PG8_BAR; PG8_MMA(0, 0, At, B0); PG8_MMA(0, 1, At, B1); PG8_BAR; PG8_SCHED;
;             PG8_LDA(At, 0, 1); PG8_STAGE(PG8_SB(0, 0), b2, voffB); PG8_STAGE(PG8_SB(0, 1), b2 + hB1, voffB1); PG8_STAGE(PG8_SA(0, 0), a2, voffA);
;             PG8_WAIT_V(8); PG8_WAIT_L(0); PG8_BAR; PG8_MMA(1, 0, At, B0); PG8_MMA(1, 1, At, B1); PG8_BAR; PG8_SCHED;
;             PG8_LDB(B0, 1, 0); PG8_LDB(B1, 1, 1); PG8_SCHED; PG8_LDA(At, 1, 0); PG8_STAGE(PG8_SA(0, 1), a2 + hstepA, voffA);
;             PG8_WAIT_V(8); PG8_WAIT_L(0); PG8_BAR; PG8_MMA(0, 0, At, B0); PG8_MMA(0, 1, At, B1); PG8_BAR; PG8_SCHED;
;             PG8_LDA(At, 1, 1); PG8_STAGE(PG8_SB(1, 0), b3, voffB); PG8_STAGE(PG8_SB(1, 1), b3 + hB1, voffB1); PG8_STAGE(PG8_SA(1, 0), a3, voffA);
;             PG8_WAIT_V(8);
;             if constexpr (epi_pre<Epi>::value) { if (last) E.pre(pre, cur, wr, wc, lane); }
;             PG8_WAIT_L(0); PG8_BAR; PG8_MMA(1, 0, At, B0); PG8_MMA(1, 1, At, B1); PG8_BAR; PG8_SCHED;
.LBB0_1273:
	s_add_u32 s42, s30, s36
	s_addc_u32 s43, s31, s37
	s_add_u32 s40, s42, 0x100
	s_addc_u32 s41, s43, 0
	s_and_b64 s[38:39], s[2:3], exec
	s_cselect_b32 s39, s1, s41
	s_cselect_b32 s38, s23, s40
	s_add_u32 s36, s28, s36
	s_addc_u32 s37, s29, s37
	s_add_u32 s36, s36, 0x100
	s_addc_u32 s37, s37, 0
	s_and_b64 s[2:3], s[2:3], exec
	s_cselect_b32 s41, s21, s37
	s_cselect_b32 s40, s67, s36
	s_add_u32 s74, s42, 0x40080
	s_addc_u32 s75, s43, 0
	s_add_i32 s77, s61, s49
	s_add_i32 m0, s50, 0xc000
	s_add_i32 s76, s50, 0xe000
	s_add_i32 s78, s77, 0x2000
	v_add_u32_e32 v2, s61, v184
	s_add_u32 s42, s40, 0x1000
	ds_read_b128 v[158:161], v2
	ds_read_b128 v[162:165], v2 offset:1024
	ds_read_b128 v[186:189], v2 offset:2048
	ds_read_b128 v[190:193], v2 offset:3072
	v_add_u32_e32 v2, s62, v184
	s_addc_u32 s43, s41, 0
	s_add_i32 s79, s62, s49
	ds_read_b128 v[138:141], v2
	ds_read_b128 v[142:145], v2 offset:1024
	ds_read_b128 v[146:149], v2 offset:2048
	ds_read_b128 v[134:137], v2 offset:3072
	s_add_i32 s80, s79, 0x2000
	s_add_i32 s73, 0, 0x18000
	s_add_i32 s72, 0, 0x1c000
	s_add_u32 s2, s38, 0x40000
	s_addc_u32 s3, s39, 0
	s_add_i32 s69, s73, s49
	s_add_i32 s68, s69, 0x2000
	s_add_u32 s36, s40, 0x1080
	s_addc_u32 s37, s41, 0
	s_add_i32 s71, s72, s49
	s_add_i32 s70, s71, 0x2000
	ds_read_b128 v[150:153], v185
	ds_read_b128 v[154:157], v185 offset:1024
	ds_read_b128 v[194:197], v185 offset:2048
	ds_read_b128 v[198:201], v185 offset:3072
	ds_read_b128 v[202:205], v185 offset:4096
	ds_read_b128 v[206:209], v185 offset:5120
	ds_read_b128 v[210:213], v185 offset:6144
	ds_read_b128 v[214:217], v185 offset:7168
	global_load_lds_dwordx4 v166, s[74:75]
	s_mov_b32 m0, s76
	s_nop 0
	global_load_lds_dwordx4 v170, s[74:75]
	s_waitcnt vmcnt(8)
	s_waitcnt lgkmcnt(0)
	s_nop 0
	s_setprio 1
	s_barrier
	v_mfma_f32_16x16x32_bf16 v[218:221], v[158:161], v[150:153], v[78:81]
	v_mfma_f32_16x16x32_bf16 v[78:81], v[162:165], v[154:157], v[218:221]
	v_mfma_f32_16x16x32_bf16 v[222:225], v[186:189], v[150:153], v[62:65]
	v_mfma_f32_16x16x32_bf16 v[226:229], v[158:161], v[194:197], v[130:133]
	v_mfma_f32_16x16x32_bf16 v[230:233], v[186:189], v[194:197], v[126:129]
	v_mfma_f32_16x16x32_bf16 v[234:237], v[158:161], v[202:205], v[74:77]
	v_mfma_f32_16x16x32_bf16 v[238:241], v[186:189], v[202:205], v[102:105]
	v_mfma_f32_16x16x32_bf16 v[218:221], v[158:161], v[210:213], v[122:125]
	v_mfma_f32_16x16x32_bf16 v[114:117], v[186:189], v[210:213], v[114:117]
	v_mfma_f32_16x16x32_bf16 v[62:65], v[190:193], v[154:157], v[222:225]
	v_mfma_f32_16x16x32_bf16 v[130:133], v[162:165], v[198:201], v[226:229]
	v_mfma_f32_16x16x32_bf16 v[126:129], v[190:193], v[198:201], v[230:233]
	v_mfma_f32_16x16x32_bf16 v[74:77], v[162:165], v[206:209], v[234:237]
	v_mfma_f32_16x16x32_bf16 v[102:105], v[190:193], v[206:209], v[238:241]
	v_mfma_f32_16x16x32_bf16 v[122:125], v[162:165], v[214:217], v[218:221]
	v_mfma_f32_16x16x32_bf16 v[114:117], v[190:193], v[214:217], v[114:117]
	s_setprio 0
	s_setprio 1
	v_mfma_f32_16x16x32_bf16 v[218:221], v[138:141], v[150:153], v[50:53]
	v_mfma_f32_16x16x32_bf16 v[50:53], v[142:145], v[154:157], v[218:221]
	v_mfma_f32_16x16x32_bf16 v[222:225], v[146:149], v[150:153], v[30:33]
	v_mfma_f32_16x16x32_bf16 v[226:229], v[138:141], v[194:197], v[110:113]
	v_mfma_f32_16x16x32_bf16 v[230:233], v[146:149], v[194:197], v[34:37]
	v_mfma_f32_16x16x32_bf16 v[234:237], v[138:141], v[202:205], v[46:49]
	v_mfma_f32_16x16x32_bf16 v[238:241], v[146:149], v[202:205], v[18:21]
	v_mfma_f32_16x16x32_bf16 v[150:153], v[138:141], v[210:213], v[90:93]
	v_mfma_f32_16x16x32_bf16 v[26:29], v[146:149], v[210:213], v[26:29]
	v_mfma_f32_16x16x32_bf16 v[30:33], v[134:137], v[154:157], v[222:225]
	v_mfma_f32_16x16x32_bf16 v[110:113], v[142:145], v[198:201], v[226:229]
	v_mfma_f32_16x16x32_bf16 v[34:37], v[134:137], v[198:201], v[230:233]
	v_mfma_f32_16x16x32_bf16 v[46:49], v[142:145], v[206:209], v[234:237]
	v_mfma_f32_16x16x32_bf16 v[18:21], v[134:137], v[206:209], v[238:241]
	v_mfma_f32_16x16x32_bf16 v[90:93], v[142:145], v[214:217], v[150:153]
	v_mfma_f32_16x16x32_bf16 v[26:29], v[134:137], v[214:217], v[26:29]
	s_setprio 0
	s_barrier
	s_mov_b32 m0, s77
	v_lshl_add_u64 v[150:151], s[40:41], 0, v[168:169]
	ds_read_b128 v[194:197], v185 offset:16384
	ds_read_b128 v[198:201], v185 offset:17408
	ds_read_b128 v[202:205], v185 offset:18432
	ds_read_b128 v[206:209], v185 offset:19456
	ds_read_b128 v[210:213], v185 offset:20480
	ds_read_b128 v[214:217], v185 offset:21504
	ds_read_b128 v[218:221], v185 offset:22528
	ds_read_b128 v[222:225], v185 offset:23552
	global_load_lds_dwordx4 v168, s[40:41]
	v_lshl_add_u64 v[152:153], s[40:41], 0, v[172:173]
	s_mov_b32 m0, s78
	v_lshl_add_u64 v[4:5], s[42:43], 0, v[168:169]
	global_load_lds_dwordx4 v172, s[40:41]
	s_mov_b32 m0, s79
	v_lshl_add_u64 v[154:155], s[38:39], 0, v[166:167]
	global_load_lds_dwordx4 v168, s[42:43]
	v_lshl_add_u64 v[4:5], s[42:43], 0, v[172:173]
	s_mov_b32 m0, s80
	v_lshl_add_u64 v[156:157], s[38:39], 0, v[170:171]
	global_load_lds_dwordx4 v172, s[42:43]
	s_mov_b32 m0, s50
	s_nop 0
	global_load_lds_dwordx4 v166, s[38:39]
	s_mov_b32 m0, s51
	s_nop 0
	global_load_lds_dwordx4 v170, s[38:39]
	s_waitcnt vmcnt(8)
	s_waitcnt lgkmcnt(0)
	s_nop 0
	s_setprio 1
	s_barrier
; #define PG8_STAGE(bufoff, gbase, voff) do { _Pragma("unroll") for (int _i = 0; _i < 2; ++_i) \
;         __builtin_amdgcn_global_load_lds((const unsigned*)((const char*)(gbase) + (voff)[_i]), (PG8_LAS unsigned*)(lds + (bufoff) + ldsw + _i * 8192), 16, 0, 0); } while (0)
; #define PG8_LDA(dst, b, h) do { _Pragma("unroll") for (int m = 0; m < 4; ++m) _Pragma("unroll") for (int k = 0; k < 2; ++k) dst[m][k] = *(const PG8_LAS bf16x8*)(lds + PG8_SA(b, h) + aoff + m * 2048 + k * 1024); } while (0)
; #define PG8_LDB(dst, b, h) do { _Pragma("unroll") for (int n = 0; n < 2; ++n) _Pragma("unroll") for (int k = 0; k < 2; ++k) dst[n][k] = *(const PG8_LAS bf16x8*)(lds + PG8_SB(b, h) + boff + n * 2048 + k * 1024); } while (0)
; #define PG8_WAIT_V(n) asm volatile("s_waitcnt vmcnt(" #n ")" ::: "memory")
; #define PG8_WAIT_L(n) asm volatile("s_waitcnt lgkmcnt(" #n ")" ::: "memory")
; #define PG8_BAR __builtin_amdgcn_s_barrier()
; #define PG8_SCHED __builtin_amdgcn_sched_barrier(0)
; template <class Epi, class Sched, class Gemm, bool ALIGN_EPI = false, bool SP2 = false>
; __device__ __forceinline__ void gemm_phase(PG8_LAS unsigned char* lds, const Gemm g, const Sched& S, const Epi& E) {
;     ...
;             PG8_LDB(B0, 0, 0); PG8_LDB(B1, 0, 1); PG8_SCHED; PG8_LDA(At, 0, 0); PG8_STAGE(PG8_SA(1, 1), a1 + hstepA, voffA);
;             PG8_WAIT_V(8); PG8_WAIT_L(0); PG8_BAR; PG8_MMA(0, 0, At, B0); PG8_MMA(0, 1, At, B1); PG8_BAR; PG8_SCHED;
;             PG8_LDA(At, 0, 1); PG8_STAGE(PG8_SB(0, 0), b2, voffB); PG8_STAGE(PG8_SB(0, 1), b2 + hB1, voffB1); PG8_STAGE(PG8_SA(0, 0), a2, voffA);
;             PG8_WAIT_V(8); PG8_WAIT_L(0); PG8_BAR; PG8_MMA(1, 0, At, B0); PG8_MMA(1, 1, At, B1); PG8_BAR; PG8_SCHED;
;             PG8_LDB(B0, 1, 0); PG8_LDB(B1, 1, 1); PG8_SCHED; PG8_LDA(At, 1, 0); PG8_STAGE(PG8_SA(0, 1), a2 + hstepA, voffA);
;             PG8_WAIT_V(8); PG8_WAIT_L(0); PG8_BAR; PG8_MMA(0, 0, At, B0); PG8_MMA(0, 1, At, B1); PG8_BAR; PG8_SCHED;
;             PG8_LDA(At, 1, 1); PG8_STAGE(PG8_SB(1, 0), b3, voffB); PG8_STAGE(PG8_SB(1, 1), b3 + hB1, voffB1); PG8_STAGE(PG8_SA(1, 0), a3, voffA);
;             PG8_WAIT_V(8);
;             if constexpr (epi_pre<Epi>::value) { if (last) E.pre(pre, cur, wr, wc, lane); }
;             PG8_WAIT_L(0); PG8_BAR; PG8_MMA(1, 0, At, B0); PG8_MMA(1, 1, At, B1); PG8_BAR; PG8_SCHED;
	v_mfma_f32_16x16x32_bf16 v[226:229], v[158:161], v[194:197], v[70:73]
	v_mfma_f32_16x16x32_bf16 v[70:73], v[162:165], v[198:201], v[226:229]
	v_mfma_f32_16x16x32_bf16 v[230:233], v[186:189], v[194:197], v[58:61]
	v_mfma_f32_16x16x32_bf16 v[234:237], v[158:161], v[202:205], v[98:101]
	v_mfma_f32_16x16x32_bf16 v[238:241], v[186:189], v[202:205], v[86:89]
	v_mfma_f32_16x16x32_bf16 v[242:245], v[158:161], v[210:213], v[66:69]
	v_mfma_f32_16x16x32_bf16 v[246:249], v[186:189], v[210:213], v[94:97]
	v_mfma_f32_16x16x32_bf16 v[226:229], v[158:161], v[218:221], v[118:121]
	v_mfma_f32_16x16x32_bf16 v[106:109], v[186:189], v[218:221], v[106:109]
	v_mfma_f32_16x16x32_bf16 v[58:61], v[190:193], v[198:201], v[230:233]
	v_mfma_f32_16x16x32_bf16 v[98:101], v[162:165], v[206:209], v[234:237]
	v_mfma_f32_16x16x32_bf16 v[86:89], v[190:193], v[206:209], v[238:241]
	v_mfma_f32_16x16x32_bf16 v[66:69], v[162:165], v[214:217], v[242:245]
	v_mfma_f32_16x16x32_bf16 v[94:97], v[190:193], v[214:217], v[246:249]
	v_mfma_f32_16x16x32_bf16 v[118:121], v[162:165], v[222:225], v[226:229]
	v_mfma_f32_16x16x32_bf16 v[106:109], v[190:193], v[222:225], v[106:109]
	s_setprio 0
	s_setprio 1
	v_mfma_f32_16x16x32_bf16 v[158:161], v[138:141], v[194:197], v[42:45]
	v_mfma_f32_16x16x32_bf16 v[42:45], v[142:145], v[198:201], v[158:161]
	v_mfma_f32_16x16x32_bf16 v[162:165], v[146:149], v[194:197], v[6:9]
	v_mfma_f32_16x16x32_bf16 v[186:189], v[138:141], v[202:205], v[54:57]
	v_mfma_f32_16x16x32_bf16 v[190:193], v[146:149], v[202:205], v[10:13]
	v_mfma_f32_16x16x32_bf16 v[226:229], v[138:141], v[210:213], v[38:41]
	v_mfma_f32_16x16x32_bf16 v[230:233], v[146:149], v[210:213], v[14:17]
	v_mfma_f32_16x16x32_bf16 v[158:161], v[138:141], v[218:221], v[82:85]
	v_mfma_f32_16x16x32_bf16 v[22:25], v[146:149], v[218:221], v[22:25]
	v_mfma_f32_16x16x32_bf16 v[4:7], v[134:137], v[198:201], v[162:165]
	v_mfma_f32_16x16x32_bf16 v[54:57], v[142:145], v[206:209], v[186:189]
	v_mfma_f32_16x16x32_bf16 v[10:13], v[134:137], v[206:209], v[190:193]
	v_mfma_f32_16x16x32_bf16 v[38:41], v[142:145], v[214:217], v[226:229]
	v_mfma_f32_16x16x32_bf16 v[14:17], v[134:137], v[214:217], v[230:233]
	v_mfma_f32_16x16x32_bf16 v[82:85], v[142:145], v[222:225], v[158:161]
	v_mfma_f32_16x16x32_bf16 v[22:25], v[134:137], v[222:225], v[22:25]
	s_setprio 0
	s_barrier
	v_add_u32_e32 v2, s73, v184
	ds_read_b128 v[158:161], v2
	ds_read_b128 v[162:165], v2 offset:1024
	ds_read_b128 v[186:189], v2 offset:2048
	ds_read_b128 v[190:193], v2 offset:3072
	v_add_u32_e32 v2, s72, v184
	ds_read_b128 v[138:141], v2
	ds_read_b128 v[142:145], v2 offset:1024
	ds_read_b128 v[146:149], v2 offset:2048
	ds_read_b128 v[134:137], v2 offset:3072
	s_mov_b32 m0, s52
	ds_read_b128 v[194:197], v185 offset:32768
	ds_read_b128 v[198:201], v185 offset:33792
	ds_read_b128 v[202:205], v185 offset:34816
	ds_read_b128 v[206:209], v185 offset:35840
	ds_read_b128 v[210:213], v185 offset:36864
	ds_read_b128 v[214:217], v185 offset:37888
	ds_read_b128 v[218:221], v185 offset:38912
	ds_read_b128 v[222:225], v185 offset:39936
	global_load_lds_dwordx4 v166, s[2:3]
	s_mov_b32 m0, s53
	s_nop 0
	global_load_lds_dwordx4 v170, s[2:3]
	s_waitcnt vmcnt(8)
	s_waitcnt lgkmcnt(0)
	s_nop 0
	s_setprio 1
	s_barrier
	v_mfma_f32_16x16x32_bf16 v[226:229], v[158:161], v[194:197], v[78:81]
	v_mfma_f32_16x16x32_bf16 v[78:81], v[162:165], v[198:201], v[226:229]
	v_mfma_f32_16x16x32_bf16 v[230:233], v[186:189], v[194:197], v[62:65]
	v_mfma_f32_16x16x32_bf16 v[234:237], v[158:161], v[202:205], v[130:133]
	v_mfma_f32_16x16x32_bf16 v[238:241], v[186:189], v[202:205], v[126:129]
	v_mfma_f32_16x16x32_bf16 v[242:245], v[158:161], v[210:213], v[74:77]
	v_mfma_f32_16x16x32_bf16 v[246:249], v[186:189], v[210:213], v[102:105]
	v_mfma_f32_16x16x32_bf16 v[226:229], v[158:161], v[218:221], v[122:125]
	v_mfma_f32_16x16x32_bf16 v[114:117], v[186:189], v[218:221], v[114:117]
	v_mfma_f32_16x16x32_bf16 v[62:65], v[190:193], v[198:201], v[230:233]
	v_mfma_f32_16x16x32_bf16 v[130:133], v[162:165], v[206:209], v[234:237]
	v_mfma_f32_16x16x32_bf16 v[126:129], v[190:193], v[206:209], v[238:241]
	v_mfma_f32_16x16x32_bf16 v[74:77], v[162:165], v[214:217], v[242:245]
	v_mfma_f32_16x16x32_bf16 v[102:105], v[190:193], v[214:217], v[246:249]
	v_mfma_f32_16x16x32_bf16 v[122:125], v[162:165], v[222:225], v[226:229]
	v_mfma_f32_16x16x32_bf16 v[114:117], v[190:193], v[222:225], v[114:117]
	s_setprio 0
	s_setprio 1
	v_mfma_f32_16x16x32_bf16 v[226:229], v[138:141], v[194:197], v[50:53]
	v_mfma_f32_16x16x32_bf16 v[50:53], v[142:145], v[198:201], v[226:229]
	v_mfma_f32_16x16x32_bf16 v[230:233], v[146:149], v[194:197], v[30:33]
	v_mfma_f32_16x16x32_bf16 v[234:237], v[138:141], v[202:205], v[110:113]
	v_mfma_f32_16x16x32_bf16 v[238:241], v[146:149], v[202:205], v[34:37]
	v_mfma_f32_16x16x32_bf16 v[242:245], v[138:141], v[210:213], v[46:49]
	v_mfma_f32_16x16x32_bf16 v[246:249], v[146:149], v[210:213], v[18:21]
	v_mfma_f32_16x16x32_bf16 v[194:197], v[138:141], v[218:221], v[90:93]
	v_mfma_f32_16x16x32_bf16 v[26:29], v[146:149], v[218:221], v[26:29]
	v_mfma_f32_16x16x32_bf16 v[30:33], v[134:137], v[198:201], v[230:233]
	v_mfma_f32_16x16x32_bf16 v[110:113], v[142:145], v[206:209], v[234:237]
	v_mfma_f32_16x16x32_bf16 v[34:37], v[134:137], v[206:209], v[238:241]
	v_mfma_f32_16x16x32_bf16 v[46:49], v[142:145], v[214:217], v[242:245]
	v_mfma_f32_16x16x32_bf16 v[18:21], v[134:137], v[214:217], v[246:249]
	v_mfma_f32_16x16x32_bf16 v[90:93], v[142:145], v[222:225], v[194:197]
	v_mfma_f32_16x16x32_bf16 v[26:29], v[134:137], v[222:225], v[26:29]
	s_setprio 0
	s_barrier
; #define EPC_LOAD(i) do { const unsigned o_ = gbase + EPC_GOFF(i); gq[i] = *(const u32x4*)(MG + (o_ + go)); gr[i] = *(const u32x4*)(nbase + ((o_ + gn) & nmask)); } while (0)
; #define PG8_STAGE(bufoff, gbase, voff) do { _Pragma("unroll") for (int _i = 0; _i < 2; ++_i) \
;         __builtin_amdgcn_global_load_lds((const unsigned*)((const char*)(gbase) + (voff)[_i]), (PG8_LAS unsigned*)(lds + (bufoff) + ldsw + _i * 8192), 16, 0, 0); } while (0)
; #define PG8_LDA(dst, b, h) do { _Pragma("unroll") for (int m = 0; m < 4; ++m) _Pragma("unroll") for (int k = 0; k < 2; ++k) dst[m][k] = *(const PG8_LAS bf16x8*)(lds + PG8_SA(b, h) + aoff + m * 2048 + k * 1024); } while (0)
; #define PG8_WAIT_V(n) asm volatile("s_waitcnt vmcnt(" #n ")" ::: "memory")
;     __device__ __forceinline__ void chain(f32x4 (&acc)[2][2][4][2], const Unit& u, int wr, int wc, int fr, int fq) const {
;     ...
;         const bool last = (u.sub == 3);
;         const unsigned gbase = (unsigned)(u.pm * BM + wr * 64 + fr) * 8704u + (unsigned)(u.pn * BM + wc * 64 + 16 * fq);
;         const unsigned obase = (unsigned)(u.pm * BM + wr * 64 + fr) * 1024u + (unsigned)(u.pn * BM + wc * 64 + 16 * fq);
;         const unsigned go = last ? 0u : 3072u + 1024u * (unsigned)u.sub;
;         const unsigned gn = (u.sub < 2) ? go + 1024u : 0u, nmask = last ? 0u : 0xffffffffu;
;         const unsigned char* nbase = last ? FF : MG;
;         const float keep = last ? 0.f : 1.f;
;         u32x4 gq[8], gr[8];
;     ...
; #pragma unroll
;         for (int i = 0; i < DEPTH; ++i) EPC_LOAD(i);
; template <class Epi, class Sched, class Gemm, bool ALIGN_EPI = false, bool SP2 = false>
; __device__ __forceinline__ void gemm_phase(PG8_LAS unsigned char* lds, const Gemm g, const Sched& S, const Epi& E) {
;     ...
;             PG8_LDB(B0, 1, 0); PG8_LDB(B1, 1, 1); PG8_SCHED; PG8_LDA(At, 1, 0); PG8_STAGE(PG8_SA(0, 1), a2 + hstepA, voffA);
;             PG8_WAIT_V(8); PG8_WAIT_L(0); PG8_BAR; PG8_MMA(0, 0, At, B0); PG8_MMA(0, 1, At, B1); PG8_BAR; PG8_SCHED;
;             PG8_LDA(At, 1, 1); PG8_STAGE(PG8_SB(1, 0), b3, voffB); PG8_STAGE(PG8_SB(1, 1), b3 + hB1, voffB1); PG8_STAGE(PG8_SA(1, 0), a3, voffA);
;             PG8_WAIT_V(8);
;             if constexpr (epi_pre<Epi>::value) { if (last) E.pre(pre, cur, wr, wc, lane); }
;             PG8_WAIT_L(0); PG8_BAR; PG8_MMA(1, 0, At, B0); PG8_MMA(1, 1, At, B1); PG8_BAR; PG8_SCHED;
	s_mov_b32 m0, s69
	v_lshl_add_u64 v[8:9], v[150:151], 0, s[16:17]
	ds_read_b128 v[194:197], v185 offset:49152
	ds_read_b128 v[198:201], v185 offset:50176
	ds_read_b128 v[202:205], v185 offset:51200
	ds_read_b128 v[206:209], v185 offset:52224
	ds_read_b128 v[210:213], v185 offset:53248
	ds_read_b128 v[214:217], v185 offset:54272
	ds_read_b128 v[218:221], v185 offset:55296
	ds_read_b128 v[222:225], v185 offset:56320
	global_load_lds_dwordx4 v[8:9], off
	v_lshl_add_u64 v[8:9], v[152:153], 0, s[16:17]
	s_mov_b32 m0, s68
	s_nop 0
	global_load_lds_dwordx4 v[8:9], off
	s_mov_b32 m0, s71
	s_nop 0
	global_load_lds_dwordx4 v168, s[36:37]
	s_mov_b32 m0, s70
	s_nop 0
	global_load_lds_dwordx4 v172, s[36:37]
	v_lshl_add_u64 v[8:9], v[154:155], 0, s[16:17]
	s_mov_b32 m0, s57
	s_nop 0
	global_load_lds_dwordx4 v[8:9], off
	v_lshl_add_u64 v[8:9], v[156:157], 0, s[16:17]
	s_mov_b32 m0, s58
	s_nop 0
	global_load_lds_dwordx4 v[8:9], off
	s_waitcnt vmcnt(8)
	s_waitcnt lgkmcnt(0)
	s_nop 0
	s_setprio 1
	s_barrier
	v_mfma_f32_16x16x32_bf16 v[150:153], v[158:161], v[194:197], v[70:73]
	v_mfma_f32_16x16x32_bf16 v[70:73], v[162:165], v[198:201], v[150:153]
	v_mfma_f32_16x16x32_bf16 v[154:157], v[186:189], v[194:197], v[58:61]
	v_mfma_f32_16x16x32_bf16 v[226:229], v[158:161], v[202:205], v[98:101]
	v_mfma_f32_16x16x32_bf16 v[230:233], v[186:189], v[202:205], v[86:89]
	v_mfma_f32_16x16x32_bf16 v[234:237], v[158:161], v[210:213], v[66:69]
	v_mfma_f32_16x16x32_bf16 v[238:241], v[186:189], v[210:213], v[94:97]
	v_mfma_f32_16x16x32_bf16 v[150:153], v[158:161], v[218:221], v[118:121]
	v_mfma_f32_16x16x32_bf16 v[106:109], v[186:189], v[218:221], v[106:109]
	v_mfma_f32_16x16x32_bf16 v[58:61], v[190:193], v[198:201], v[154:157]
	v_mfma_f32_16x16x32_bf16 v[98:101], v[162:165], v[206:209], v[226:229]
	v_mfma_f32_16x16x32_bf16 v[86:89], v[190:193], v[206:209], v[230:233]
	v_mfma_f32_16x16x32_bf16 v[66:69], v[162:165], v[214:217], v[234:237]
	v_mfma_f32_16x16x32_bf16 v[94:97], v[190:193], v[214:217], v[238:241]
	v_mfma_f32_16x16x32_bf16 v[118:121], v[162:165], v[222:225], v[150:153]
	v_mfma_f32_16x16x32_bf16 v[106:109], v[190:193], v[222:225], v[106:109]
	s_setprio 0
	s_setprio 1
	v_mfma_f32_16x16x32_bf16 v[150:153], v[138:141], v[194:197], v[42:45]
	v_mfma_f32_16x16x32_bf16 v[42:45], v[142:145], v[198:201], v[150:153]
	v_mfma_f32_16x16x32_bf16 v[154:157], v[146:149], v[194:197], v[4:7]
	v_mfma_f32_16x16x32_bf16 v[158:161], v[138:141], v[202:205], v[54:57]
	v_mfma_f32_16x16x32_bf16 v[162:165], v[146:149], v[202:205], v[10:13]
	v_mfma_f32_16x16x32_bf16 v[186:189], v[138:141], v[210:213], v[38:41]
	v_mfma_f32_16x16x32_bf16 v[190:193], v[146:149], v[210:213], v[14:17]
	v_mfma_f32_16x16x32_bf16 v[150:153], v[138:141], v[218:221], v[82:85]
	v_mfma_f32_16x16x32_bf16 v[22:25], v[146:149], v[218:221], v[22:25]
	v_mfma_f32_16x16x32_bf16 v[6:9], v[134:137], v[198:201], v[154:157]
	v_mfma_f32_16x16x32_bf16 v[54:57], v[142:145], v[206:209], v[158:161]
	v_mfma_f32_16x16x32_bf16 v[10:13], v[134:137], v[206:209], v[162:165]
	v_mfma_f32_16x16x32_bf16 v[38:41], v[142:145], v[214:217], v[186:189]
	v_mfma_f32_16x16x32_bf16 v[14:17], v[134:137], v[214:217], v[190:193]
	v_mfma_f32_16x16x32_bf16 v[82:85], v[142:145], v[222:225], v[150:153]
	v_mfma_f32_16x16x32_bf16 v[22:25], v[134:137], v[222:225], v[22:25]
	s_setprio 0
	s_barrier
	s_andn2_b64 vcc, exec, s[34:35]
	s_mov_b64 s[2:3], -1
	s_mov_b64 s[34:35], 0
	s_mov_b64 s[36:37], 0x100
	s_cbranch_vccz .LBB0_1273
	s_lshl_b32 s0, s0, 8
	s_lshl_b32 s1, s6, 8
	s_or_b32 s21, s0, s59
	s_lshl_b32 s0, s7, 10
	s_add_i32 s6, s1, s56
	s_add_i32 s23, s0, 0xc00
	s_cmp_eq_u32 s7, 3
	v_mov_b32_e32 v2, v1
	v_mov_b32_e32 v4, v181
	s_cselect_b64 s[0:1], -1, 0
	s_and_b64 s[2:3], s[0:1], exec
	s_cselect_b32 s2, 0, s23
	v_add_u32_e32 v2, s6, v2
	v_mul_lo_u32 v5, v2, s63
	v_lshlrev_b32_e32 v4, 4, v4
	s_cselect_b32 s28, s54, s14
	s_cselect_b32 s29, s55, s15
	s_add_i32 s3, s2, 0x400
	v_add3_u32 v180, s21, v4, v5
	s_cmp_lt_u32 s7, 2
	v_add_u32_e32 v4, s2, v180
	s_cselect_b32 s3, s3, 0
	global_load_dwordx4 v[142:145], v4, s[14:15]
	v_add_u32_e32 v4, s3, v180
	v_cndmask_b32_e64 v4, v4, 0, s[0:1]
	global_load_dwordx4 v[146:149], v4, s[28:29]
	v_add_u32_e32 v4, 0x22000, v180
	v_add_u32_e32 v138, 0x66000, v180
	v_add_u32_e32 v5, 0x44000, v180
	v_add_u32_e32 v134, s2, v4
	v_add_u32_e32 v136, s2, v138
	v_add_u32_e32 v4, s3, v4
	v_add_u32_e32 v138, s3, v138
	v_add_u32_e32 v135, s2, v5
	v_add_u32_e32 v5, s3, v5
	v_cndmask_b32_e64 v4, v4, 0, s[0:1]
	v_cndmask_b32_e64 v138, v138, 0, s[0:1]
	global_load_dwordx4 v[150:153], v134, s[14:15]
	global_load_dwordx4 v[154:157], v135, s[14:15]
	s_nop 0
	global_load_dwordx4 v[134:137], v136, s[14:15]
	v_cndmask_b32_e64 v5, v5, 0, s[0:1]
	global_load_dwordx4 v[158:161], v4, s[28:29]
	global_load_dwordx4 v[162:165], v5, s[28:29]
	s_nop 0
	global_load_dwordx4 v[138:141], v138, s[28:29]
	v_mad_u64_u32 v[4:5], s[30:31], v2, s64, v[180:181]
	s_and_b64 vcc, exec, s[18:19]
	s_cbranch_vccz .LBB0_1276
	s_barrier

; #define PG8_STAGE(bufoff, gbase, voff) do { _Pragma("unroll") for (int _i = 0; _i < 2; ++_i) \
;         __builtin_amdgcn_global_load_lds((const unsigned*)((const char*)(gbase) + (voff)[_i]), (PG8_LAS unsigned*)(lds + (bufoff) + ldsw + _i * 8192), 16, 0, 0); } while (0)
; #define PG8_LDA(dst, b, h) do { _Pragma("unroll") for (int m = 0; m < 4; ++m) _Pragma("unroll") for (int k = 0; k < 2; ++k) dst[m][k] = *(const PG8_LAS bf16x8*)(lds + PG8_SA(b, h) + aoff + m * 2048 + k * 1024); } while (0)
; #define PG8_LDB(dst, b, h) do { _Pragma("unroll") for (int n = 0; n < 2; ++n) _Pragma("unroll") for (int k = 0; k < 2; ++k) dst[n][k] = *(const PG8_LAS bf16x8*)(lds + PG8_SB(b, h) + boff + n * 2048 + k * 1024); } while (0)
; #define PG8_MMA(ai, bj, At, Bt) do { __builtin_amdgcn_s_setprio(1); _Pragma("unroll") for (int m = 0; m < 4; ++m) _Pragma("unroll") for (int n = 0; n < 2; ++n) _Pragma("unroll") for (int k = 0; k < 2; ++k) \
;         acc[ai][bj][m][n] = Gemm::i8 ? ::mfma16i8_g(Bt[n][k], At[m][k], acc[ai][bj][m][n]) : ::mfma16_g(Bt[n][k], At[m][k], acc[ai][bj][m][n]); __builtin_amdgcn_s_setprio(0); } while (0)
; #define PG8_WAIT_V(n) asm volatile("s_waitcnt vmcnt(" #n ")" ::: "memory")
; #define PG8_WAIT_L(n) asm volatile("s_waitcnt lgkmcnt(" #n ")" ::: "memory")
; template <class Epi, class Sched, class Gemm, bool ALIGN_EPI = false, bool SP2 = false>
; __device__ __forceinline__ void gemm_phase(PG8_LAS unsigned char* lds, const Gemm g, const Sched& S, const Epi& E) {
;     ...
;             PG8_LDB(B0, 0, 0); PG8_LDB(B1, 0, 1); PG8_SCHED; PG8_LDA(At, 0, 0); PG8_STAGE(PG8_SA(1, 1), a1 + hstepA, voffA);
;             PG8_WAIT_V(8); PG8_WAIT_L(0); PG8_BAR; PG8_MMA(0, 0, At, B0); PG8_MMA(0, 1, At, B1); PG8_BAR; PG8_SCHED;
;             PG8_LDA(At, 0, 1); PG8_STAGE(PG8_SB(0, 0), b2, voffB); PG8_STAGE(PG8_SB(0, 1), b2 + hB1, voffB1); PG8_STAGE(PG8_SA(0, 0), a2, voffA);
;             PG8_WAIT_V(8); PG8_WAIT_L(0); PG8_BAR; PG8_MMA(1, 0, At, B0); PG8_MMA(1, 1, At, B1); PG8_BAR; PG8_SCHED;
;             PG8_LDB(B0, 1, 0); PG8_LDB(B1, 1, 1); PG8_SCHED; PG8_LDA(At, 1, 0); PG8_STAGE(PG8_SA(0, 1), a2 + hstepA, voffA);
;             PG8_WAIT_V(8); PG8_WAIT_L(0); PG8_BAR; PG8_MMA(0, 0, At, B0); PG8_MMA(0, 1, At, B1); PG8_BAR; PG8_SCHED;
;             PG8_LDA(At, 1, 1); PG8_STAGE(PG8_SB(1, 0), b3, voffB); PG8_STAGE(PG8_SB(1, 1), b3 + hB1, voffB1); PG8_STAGE(PG8_SA(1, 0), a3, voffA);
.LBB0_1370:
	ds_read_b128 v[170:173], v236
	ds_read_b128 v[174:177], v236 offset:1024
	ds_read_b128 v[178:181], v236 offset:2048
	ds_read_b128 v[182:185], v236 offset:3072
	ds_read_b128 v[150:153], v237
	ds_read_b128 v[154:157], v237 offset:1024
	ds_read_b128 v[158:161], v237 offset:2048
	ds_read_b128 v[146:149], v237 offset:3072
	s_add_u32 s2, s0, 0xfffc0080
	s_addc_u32 s3, s1, -1
	s_cmp_eq_u32 s72, 12
	s_cselect_b32 s3, s9, s3
	s_cselect_b32 s2, s33, s2
	s_cselect_b32 s7, s37, s71
	s_cselect_b32 s6, s39, s45
	s_add_i32 m0, s52, 0xc000
	ds_read_b128 v[162:165], v238
	ds_read_b128 v[166:169], v238 offset:1024
	ds_read_b128 v[186:189], v238 offset:2048
	ds_read_b128 v[190:193], v238 offset:3072
	ds_read_b128 v[210:213], v238 offset:4096
	ds_read_b128 v[214:217], v238 offset:5120
	ds_read_b128 v[218:221], v238 offset:6144
	ds_read_b128 v[222:225], v238 offset:7168
	global_load_lds_dwordx4 v204, s[0:1]
	v_lshl_add_u64 v[2:3], s[0:1], 0, v[202:203]
	s_add_i32 m0, s52, 0xe000
	s_nop 0
	global_load_lds_dwordx4 v202, s[0:1]
	s_waitcnt vmcnt(8)
	s_waitcnt lgkmcnt(0)
	s_nop 0
	s_setprio 1
	s_barrier
	v_mfma_f32_16x16x32_bf16 v[10:13], v[170:173], v[162:165], v[94:97]
	v_mfma_f32_16x16x32_bf16 v[14:17], v[178:181], v[162:165], v[90:93]
	v_mfma_f32_16x16x32_bf16 v[2:5], v[174:177], v[166:169], v[10:13]
	v_mfma_f32_16x16x32_bf16 v[90:93], v[182:185], v[166:169], v[14:17]
	v_mfma_f32_16x16x32_bf16 v[94:97], v[170:173], v[186:189], v[110:113]
	v_mfma_f32_16x16x32_bf16 v[226:229], v[178:181], v[186:189], v[106:109]
	v_mfma_f32_16x16x32_bf16 v[230:233], v[178:181], v[210:213], v[122:125]
	v_mfma_f32_16x16x32_bf16 v[10:13], v[170:173], v[218:221], v[142:145]
	v_mfma_f32_16x16x32_bf16 v[14:17], v[178:181], v[218:221], v[138:141]
	v_mfma_f32_16x16x32_bf16 v[110:113], v[174:177], v[190:193], v[94:97]
	v_mfma_f32_16x16x32_bf16 v[106:109], v[182:185], v[190:193], v[226:229]
	v_mfma_f32_16x16x32_bf16 v[130:133], v[170:173], v[210:213], v[130:133]
	v_mfma_f32_16x16x32_bf16 v[122:125], v[182:185], v[214:217], v[230:233]
	v_mfma_f32_16x16x32_bf16 v[142:145], v[174:177], v[222:225], v[10:13]
	v_mfma_f32_16x16x32_bf16 v[138:141], v[182:185], v[222:225], v[14:17]
	v_mfma_f32_16x16x32_bf16 v[6:9], v[174:177], v[214:217], v[130:133]
	s_setprio 0
	s_setprio 1
	v_mfma_f32_16x16x32_bf16 v[86:89], v[150:153], v[162:165], v[86:89]
	v_mfma_f32_16x16x32_bf16 v[82:85], v[158:161], v[162:165], v[82:85]
	v_mfma_f32_16x16x32_bf16 v[10:13], v[154:157], v[166:169], v[86:89]
	v_mfma_f32_16x16x32_bf16 v[14:17], v[146:149], v[166:169], v[82:85]
	v_mfma_f32_16x16x32_bf16 v[94:97], v[150:153], v[186:189], v[102:105]
	v_mfma_f32_16x16x32_bf16 v[130:133], v[158:161], v[186:189], v[98:101]
	v_mfma_f32_16x16x32_bf16 v[226:229], v[150:153], v[210:213], v[118:121]
	v_mfma_f32_16x16x32_bf16 v[230:233], v[158:161], v[210:213], v[114:117]
	v_mfma_f32_16x16x32_bf16 v[82:85], v[150:153], v[218:221], v[134:137]
	v_mfma_f32_16x16x32_bf16 v[86:89], v[158:161], v[218:221], v[126:129]
	v_mfma_f32_16x16x32_bf16 v[102:105], v[154:157], v[190:193], v[94:97]
	v_mfma_f32_16x16x32_bf16 v[98:101], v[146:149], v[190:193], v[130:133]
	v_mfma_f32_16x16x32_bf16 v[118:121], v[154:157], v[214:217], v[226:229]
	v_mfma_f32_16x16x32_bf16 v[114:117], v[146:149], v[214:217], v[230:233]
	v_mfma_f32_16x16x32_bf16 v[134:137], v[154:157], v[222:225], v[82:85]
	v_mfma_f32_16x16x32_bf16 v[126:129], v[146:149], v[222:225], v[86:89]
	s_setprio 0
	s_barrier
	s_add_i32 s73, s66, s51
	v_lshl_add_u64 v[162:163], s[6:7], 0, v[196:197]
	s_mov_b32 m0, s73
	ds_read_b128 v[82:85], v238 offset:16384
	ds_read_b128 v[86:89], v238 offset:17408
	ds_read_b128 v[94:97], v238 offset:18432
	ds_read_b128 v[130:133], v238 offset:19456
	ds_read_b128 v[186:189], v238 offset:20480
	ds_read_b128 v[190:193], v238 offset:21504
	ds_read_b128 v[210:213], v238 offset:22528
	ds_read_b128 v[214:217], v238 offset:23552
	global_load_lds_dwordx4 v196, s[6:7]
	s_add_i32 m0, s73, 0x2000
	s_add_u32 s74, s6, 0x40000
	v_lshl_add_u64 v[164:165], s[6:7], 0, v[200:201]
	s_addc_u32 s75, s7, 0
	s_add_i32 s73, s67, s51
	global_load_lds_dwordx4 v200, s[6:7]
	s_mov_b32 m0, s73
	v_lshl_add_u64 v[168:169], s[2:3], 0, v[198:199]
	global_load_lds_dwordx4 v196, s[74:75]
	s_add_i32 m0, s73, 0x2000
	s_nop 0
	global_load_lds_dwordx4 v200, s[74:75]
	v_lshl_add_u64 v[166:167], s[2:3], 0, v[194:195]
	s_mov_b32 m0, s52
	s_nop 0
	global_load_lds_dwordx4 v194, s[2:3]
	s_mov_b32 m0, s53
	s_nop 0
	global_load_lds_dwordx4 v198, s[2:3]
	s_waitcnt vmcnt(8)
	s_waitcnt lgkmcnt(0)
	s_nop 0
	s_setprio 1
	s_barrier
; #define PG8_STAGE(bufoff, gbase, voff) do { _Pragma("unroll") for (int _i = 0; _i < 2; ++_i) \
;         __builtin_amdgcn_global_load_lds((const unsigned*)((const char*)(gbase) + (voff)[_i]), (PG8_LAS unsigned*)(lds + (bufoff) + ldsw + _i * 8192), 16, 0, 0); } while (0)
; #define PG8_LDA(dst, b, h) do { _Pragma("unroll") for (int m = 0; m < 4; ++m) _Pragma("unroll") for (int k = 0; k < 2; ++k) dst[m][k] = *(const PG8_LAS bf16x8*)(lds + PG8_SA(b, h) + aoff + m * 2048 + k * 1024); } while (0)
; #define PG8_LDB(dst, b, h) do { _Pragma("unroll") for (int n = 0; n < 2; ++n) _Pragma("unroll") for (int k = 0; k < 2; ++k) dst[n][k] = *(const PG8_LAS bf16x8*)(lds + PG8_SB(b, h) + boff + n * 2048 + k * 1024); } while (0)
; #define PG8_MMA(ai, bj, At, Bt) do { __builtin_amdgcn_s_setprio(1); _Pragma("unroll") for (int m = 0; m < 4; ++m) _Pragma("unroll") for (int n = 0; n < 2; ++n) _Pragma("unroll") for (int k = 0; k < 2; ++k) \
;         acc[ai][bj][m][n] = Gemm::i8 ? ::mfma16i8_g(Bt[n][k], At[m][k], acc[ai][bj][m][n]) : ::mfma16_g(Bt[n][k], At[m][k], acc[ai][bj][m][n]); __builtin_amdgcn_s_setprio(0); } while (0)
; #define PG8_WAIT_V(n) asm volatile("s_waitcnt vmcnt(" #n ")" ::: "memory")
; #define PG8_WAIT_L(n) asm volatile("s_waitcnt lgkmcnt(" #n ")" ::: "memory")
; template <class Epi, class Sched, class Gemm, bool ALIGN_EPI = false, bool SP2 = false>
; __device__ __forceinline__ void gemm_phase(PG8_LAS unsigned char* lds, const Gemm g, const Sched& S, const Epi& E) {
;     ...
;             PG8_LDB(B0, 0, 0); PG8_LDB(B1, 0, 1); PG8_SCHED; PG8_LDA(At, 0, 0); PG8_STAGE(PG8_SA(1, 1), a1 + hstepA, voffA);
;             PG8_WAIT_V(8); PG8_WAIT_L(0); PG8_BAR; PG8_MMA(0, 0, At, B0); PG8_MMA(0, 1, At, B1); PG8_BAR; PG8_SCHED;
;             PG8_LDA(At, 0, 1); PG8_STAGE(PG8_SB(0, 0), b2, voffB); PG8_STAGE(PG8_SB(0, 1), b2 + hB1, voffB1); PG8_STAGE(PG8_SA(0, 0), a2, voffA);
;             PG8_WAIT_V(8); PG8_WAIT_L(0); PG8_BAR; PG8_MMA(1, 0, At, B0); PG8_MMA(1, 1, At, B1); PG8_BAR; PG8_SCHED;
;             PG8_LDB(B0, 1, 0); PG8_LDB(B1, 1, 1); PG8_SCHED; PG8_LDA(At, 1, 0); PG8_STAGE(PG8_SA(0, 1), a2 + hstepA, voffA);
;             PG8_WAIT_V(8); PG8_WAIT_L(0); PG8_BAR; PG8_MMA(0, 0, At, B0); PG8_MMA(0, 1, At, B1); PG8_BAR; PG8_SCHED;
;             PG8_LDA(At, 1, 1); PG8_STAGE(PG8_SB(1, 0), b3, voffB); PG8_STAGE(PG8_SB(1, 1), b3 + hB1, voffB1); PG8_STAGE(PG8_SA(1, 0), a3, voffA);
	v_mfma_f32_16x16x32_bf16 v[218:221], v[170:173], v[82:85], v[78:81]
	v_mfma_f32_16x16x32_bf16 v[78:81], v[174:177], v[86:89], v[218:221]
	v_mfma_f32_16x16x32_bf16 v[222:225], v[178:181], v[82:85], v[74:77]
	v_mfma_f32_16x16x32_bf16 v[226:229], v[170:173], v[94:97], v[62:65]
	v_mfma_f32_16x16x32_bf16 v[230:233], v[178:181], v[94:97], v[58:61]
	v_mfma_f32_16x16x32_bf16 v[242:245], v[170:173], v[186:189], v[46:49]
	v_mfma_f32_16x16x32_bf16 v[246:249], v[178:181], v[186:189], v[42:45]
	v_mfma_f32_16x16x32_bf16 v[218:221], v[170:173], v[210:213], v[30:33]
	v_mfma_f32_16x16x32_bf16 v[26:29], v[178:181], v[210:213], v[26:29]
	v_mfma_f32_16x16x32_bf16 v[74:77], v[182:185], v[86:89], v[222:225]
	v_mfma_f32_16x16x32_bf16 v[62:65], v[174:177], v[130:133], v[226:229]
	v_mfma_f32_16x16x32_bf16 v[58:61], v[182:185], v[130:133], v[230:233]
	v_mfma_f32_16x16x32_bf16 v[46:49], v[174:177], v[190:193], v[242:245]
	v_mfma_f32_16x16x32_bf16 v[42:45], v[182:185], v[190:193], v[246:249]
	v_mfma_f32_16x16x32_bf16 v[30:33], v[174:177], v[214:217], v[218:221]
	v_mfma_f32_16x16x32_bf16 v[26:29], v[182:185], v[214:217], v[26:29]
	s_setprio 0
	s_setprio 1
	v_mfma_f32_16x16x32_bf16 v[170:173], v[150:153], v[82:85], v[70:73]
	v_mfma_f32_16x16x32_bf16 v[70:73], v[154:157], v[86:89], v[170:173]
	v_mfma_f32_16x16x32_bf16 v[174:177], v[158:161], v[82:85], v[66:69]
	v_mfma_f32_16x16x32_bf16 v[178:181], v[150:153], v[94:97], v[54:57]
	v_mfma_f32_16x16x32_bf16 v[182:185], v[158:161], v[94:97], v[50:53]
	v_mfma_f32_16x16x32_bf16 v[218:221], v[150:153], v[186:189], v[38:41]
	v_mfma_f32_16x16x32_bf16 v[222:225], v[158:161], v[186:189], v[34:37]
	v_mfma_f32_16x16x32_bf16 v[82:85], v[150:153], v[210:213], v[22:25]
	v_mfma_f32_16x16x32_bf16 v[18:21], v[158:161], v[210:213], v[18:21]
	v_mfma_f32_16x16x32_bf16 v[66:69], v[146:149], v[86:89], v[174:177]
	v_mfma_f32_16x16x32_bf16 v[54:57], v[154:157], v[130:133], v[178:181]
	v_mfma_f32_16x16x32_bf16 v[50:53], v[146:149], v[130:133], v[182:185]
	v_mfma_f32_16x16x32_bf16 v[38:41], v[154:157], v[190:193], v[218:221]
	v_mfma_f32_16x16x32_bf16 v[34:37], v[146:149], v[190:193], v[222:225]
	v_mfma_f32_16x16x32_bf16 v[22:25], v[154:157], v[214:217], v[82:85]
	v_mfma_f32_16x16x32_bf16 v[18:21], v[146:149], v[214:217], v[18:21]
	s_setprio 0
	s_barrier
	s_add_i32 s73, 0, 0x18000
	v_add_u32_e32 v82, s73, v235
	s_add_i32 s74, 0, 0x1c000
	ds_read_b128 v[170:173], v82
	ds_read_b128 v[174:177], v82 offset:1024
	ds_read_b128 v[178:181], v82 offset:2048
	ds_read_b128 v[182:185], v82 offset:3072
	v_add_u32_e32 v82, s74, v235
	ds_read_b128 v[150:153], v82
	ds_read_b128 v[154:157], v82 offset:1024
	ds_read_b128 v[158:161], v82 offset:2048
	ds_read_b128 v[146:149], v82 offset:3072
	s_add_u32 s2, s2, 0x40000
	s_addc_u32 s3, s3, 0
	s_mov_b32 m0, s54
	ds_read_b128 v[186:189], v238 offset:32768
	ds_read_b128 v[190:193], v238 offset:33792
	ds_read_b128 v[210:213], v238 offset:34816
	ds_read_b128 v[214:217], v238 offset:35840
	ds_read_b128 v[218:221], v238 offset:36864
	ds_read_b128 v[222:225], v238 offset:37888
	ds_read_b128 v[226:229], v238 offset:38912
	ds_read_b128 v[230:233], v238 offset:39936
	global_load_lds_dwordx4 v194, s[2:3]
	v_lshl_add_u64 v[82:83], s[2:3], 0, v[198:199]
	s_mov_b32 m0, s55
	s_nop 0
	global_load_lds_dwordx4 v198, s[2:3]
	s_waitcnt vmcnt(8)
	s_waitcnt lgkmcnt(0)
	s_nop 0
	s_setprio 1
	s_barrier
	v_mfma_f32_16x16x32_bf16 v[2:5], v[170:173], v[186:189], v[2:5]
	v_mfma_f32_16x16x32_bf16 v[82:85], v[178:181], v[186:189], v[90:93]
	v_mfma_f32_16x16x32_bf16 v[86:89], v[170:173], v[210:213], v[110:113]
	v_mfma_f32_16x16x32_bf16 v[242:245], v[178:181], v[210:213], v[106:109]
	v_mfma_f32_16x16x32_bf16 v[6:9], v[170:173], v[218:221], v[6:9]
	v_mfma_f32_16x16x32_bf16 v[94:97], v[174:177], v[190:193], v[2:5]
	v_mfma_f32_16x16x32_bf16 v[90:93], v[182:185], v[190:193], v[82:85]
	v_mfma_f32_16x16x32_bf16 v[110:113], v[174:177], v[214:217], v[86:89]
	v_mfma_f32_16x16x32_bf16 v[106:109], v[182:185], v[214:217], v[242:245]
	v_mfma_f32_16x16x32_bf16 v[130:133], v[174:177], v[222:225], v[6:9]
	v_mfma_f32_16x16x32_bf16 v[246:249], v[178:181], v[218:221], v[122:125]
	v_mfma_f32_16x16x32_bf16 v[2:5], v[170:173], v[226:229], v[142:145]
	v_mfma_f32_16x16x32_bf16 v[6:9], v[178:181], v[226:229], v[138:141]
	v_mfma_f32_16x16x32_bf16 v[122:125], v[182:185], v[222:225], v[246:249]
	v_mfma_f32_16x16x32_bf16 v[142:145], v[174:177], v[230:233], v[2:5]
	v_mfma_f32_16x16x32_bf16 v[138:141], v[182:185], v[230:233], v[6:9]
	s_setprio 0
	s_setprio 1
	v_mfma_f32_16x16x32_bf16 v[2:5], v[150:153], v[186:189], v[10:13]
	v_mfma_f32_16x16x32_bf16 v[6:9], v[158:161], v[186:189], v[14:17]
	v_mfma_f32_16x16x32_bf16 v[86:89], v[154:157], v[190:193], v[2:5]
	v_mfma_f32_16x16x32_bf16 v[82:85], v[146:149], v[190:193], v[6:9]
	v_mfma_f32_16x16x32_bf16 v[10:13], v[150:153], v[210:213], v[102:105]
	v_mfma_f32_16x16x32_bf16 v[14:17], v[158:161], v[210:213], v[98:101]
	v_mfma_f32_16x16x32_bf16 v[242:245], v[150:153], v[218:221], v[118:121]
	v_mfma_f32_16x16x32_bf16 v[246:249], v[158:161], v[218:221], v[114:117]
	v_mfma_f32_16x16x32_bf16 v[2:5], v[150:153], v[226:229], v[134:137]
	v_mfma_f32_16x16x32_bf16 v[6:9], v[158:161], v[226:229], v[126:129]
	v_mfma_f32_16x16x32_bf16 v[102:105], v[154:157], v[214:217], v[10:13]
	v_mfma_f32_16x16x32_bf16 v[98:101], v[146:149], v[214:217], v[14:17]
	v_mfma_f32_16x16x32_bf16 v[118:121], v[154:157], v[222:225], v[242:245]
	v_mfma_f32_16x16x32_bf16 v[114:117], v[146:149], v[222:225], v[246:249]
	v_mfma_f32_16x16x32_bf16 v[134:137], v[154:157], v[230:233], v[2:5]
	v_mfma_f32_16x16x32_bf16 v[126:129], v[146:149], v[230:233], v[6:9]
	s_setprio 0
	s_barrier
; #define PG8_STAGE(bufoff, gbase, voff) do { _Pragma("unroll") for (int _i = 0; _i < 2; ++_i) \
;         __builtin_amdgcn_global_load_lds((const unsigned*)((const char*)(gbase) + (voff)[_i]), (PG8_LAS unsigned*)(lds + (bufoff) + ldsw + _i * 8192), 16, 0, 0); } while (0)
; #define PG8_LDA(dst, b, h) do { _Pragma("unroll") for (int m = 0; m < 4; ++m) _Pragma("unroll") for (int k = 0; k < 2; ++k) dst[m][k] = *(const PG8_LAS bf16x8*)(lds + PG8_SA(b, h) + aoff + m * 2048 + k * 1024); } while (0)
; #define PG8_LDB(dst, b, h) do { _Pragma("unroll") for (int n = 0; n < 2; ++n) _Pragma("unroll") for (int k = 0; k < 2; ++k) dst[n][k] = *(const PG8_LAS bf16x8*)(lds + PG8_SB(b, h) + boff + n * 2048 + k * 1024); } while (0)
; #define PG8_MMA(ai, bj, At, Bt) do { __builtin_amdgcn_s_setprio(1); _Pragma("unroll") for (int m = 0; m < 4; ++m) _Pragma("unroll") for (int n = 0; n < 2; ++n) _Pragma("unroll") for (int k = 0; k < 2; ++k) \
;         acc[ai][bj][m][n] = Gemm::i8 ? ::mfma16i8_g(Bt[n][k], At[m][k], acc[ai][bj][m][n]) : ::mfma16_g(Bt[n][k], At[m][k], acc[ai][bj][m][n]); __builtin_amdgcn_s_setprio(0); } while (0)
; #define PG8_WAIT_V(n) asm volatile("s_waitcnt vmcnt(" #n ")" ::: "memory")
; #define PG8_WAIT_L(n) asm volatile("s_waitcnt lgkmcnt(" #n ")" ::: "memory")
; #define PG8_BAR __builtin_amdgcn_s_barrier()
; #define PG8_SCHED __builtin_amdgcn_sched_barrier(0)
; template <class Epi, class Sched, class Gemm, bool ALIGN_EPI = false, bool SP2 = false>
; __device__ __forceinline__ void gemm_phase(PG8_LAS unsigned char* lds, const Gemm g, const Sched& S, const Epi& E) {
;     ...
;             PG8_LDB(B0, 1, 0); PG8_LDB(B1, 1, 1); PG8_SCHED; PG8_LDA(At, 1, 0); PG8_STAGE(PG8_SA(0, 1), a2 + hstepA, voffA);
;             PG8_WAIT_V(8); PG8_WAIT_L(0); PG8_BAR; PG8_MMA(0, 0, At, B0); PG8_MMA(0, 1, At, B1); PG8_BAR; PG8_SCHED;
;             PG8_LDA(At, 1, 1); PG8_STAGE(PG8_SB(1, 0), b3, voffB); PG8_STAGE(PG8_SB(1, 1), b3 + hB1, voffB1); PG8_STAGE(PG8_SA(1, 0), a3, voffA);
;             PG8_WAIT_V(8);
;             if constexpr (epi_pre<Epi>::value) { if (last) E.pre(pre, cur, wr, wc, lane); }
;             PG8_WAIT_L(0); PG8_BAR; PG8_MMA(1, 0, At, B0); PG8_MMA(1, 1, At, B1); PG8_BAR; PG8_SCHED;
	s_add_i32 s2, s73, s51
	v_lshl_add_u64 v[162:163], v[162:163], 0, s[28:29]
	s_mov_b32 m0, s2
	ds_read_b128 v[2:5], v238 offset:49152
	ds_read_b128 v[6:9], v238 offset:50176
	ds_read_b128 v[10:13], v238 offset:51200
	ds_read_b128 v[14:17], v238 offset:52224
	ds_read_b128 v[186:189], v238 offset:53248
	ds_read_b128 v[190:193], v238 offset:54272
	ds_read_b128 v[210:213], v238 offset:55296
	ds_read_b128 v[214:217], v238 offset:56320
	global_load_lds_dwordx4 v[162:163], off
	s_add_i32 m0, s2, 0x2000
	s_add_u32 s2, s6, 0x40080
	v_lshl_add_u64 v[162:163], v[164:165], 0, s[28:29]
	s_addc_u32 s3, s7, 0
	s_add_i32 s6, s74, s51
	global_load_lds_dwordx4 v[162:163], off
	s_mov_b32 m0, s6
	s_nop 0
	global_load_lds_dwordx4 v196, s[2:3]
	s_add_i32 m0, s6, 0x2000
	s_nop 0
	global_load_lds_dwordx4 v200, s[2:3]
	v_lshl_add_u64 v[162:163], v[166:167], 0, s[28:29]
	s_mov_b32 m0, s62
	s_nop 0
	global_load_lds_dwordx4 v[162:163], off
	v_lshl_add_u64 v[162:163], v[168:169], 0, s[28:29]
	s_mov_b32 m0, s63
	s_nop 0
	global_load_lds_dwordx4 v[162:163], off
	s_waitcnt vmcnt(8)
	s_waitcnt lgkmcnt(0)
	s_nop 0
	s_setprio 1
	s_barrier
	v_mfma_f32_16x16x32_bf16 v[162:165], v[170:173], v[2:5], v[78:81]
	v_mfma_f32_16x16x32_bf16 v[78:81], v[174:177], v[6:9], v[162:165]
	v_mfma_f32_16x16x32_bf16 v[166:169], v[178:181], v[2:5], v[74:77]
	v_mfma_f32_16x16x32_bf16 v[218:221], v[170:173], v[10:13], v[62:65]
	v_mfma_f32_16x16x32_bf16 v[222:225], v[178:181], v[10:13], v[58:61]
	v_mfma_f32_16x16x32_bf16 v[226:229], v[170:173], v[186:189], v[46:49]
	v_mfma_f32_16x16x32_bf16 v[230:233], v[178:181], v[186:189], v[42:45]
	v_mfma_f32_16x16x32_bf16 v[162:165], v[170:173], v[210:213], v[30:33]
	v_mfma_f32_16x16x32_bf16 v[26:29], v[178:181], v[210:213], v[26:29]
	v_mfma_f32_16x16x32_bf16 v[74:77], v[182:185], v[6:9], v[166:169]
	v_mfma_f32_16x16x32_bf16 v[62:65], v[174:177], v[14:17], v[218:221]
	v_mfma_f32_16x16x32_bf16 v[58:61], v[182:185], v[14:17], v[222:225]
	v_mfma_f32_16x16x32_bf16 v[46:49], v[174:177], v[190:193], v[226:229]
	v_mfma_f32_16x16x32_bf16 v[42:45], v[182:185], v[190:193], v[230:233]
	v_mfma_f32_16x16x32_bf16 v[30:33], v[174:177], v[214:217], v[162:165]
	v_mfma_f32_16x16x32_bf16 v[26:29], v[182:185], v[214:217], v[26:29]
	s_setprio 0
	s_setprio 1
	v_mfma_f32_16x16x32_bf16 v[162:165], v[150:153], v[2:5], v[70:73]
	v_mfma_f32_16x16x32_bf16 v[166:169], v[158:161], v[2:5], v[66:69]
	v_mfma_f32_16x16x32_bf16 v[70:73], v[154:157], v[6:9], v[162:165]
	v_mfma_f32_16x16x32_bf16 v[66:69], v[146:149], v[6:9], v[166:169]
	v_mfma_f32_16x16x32_bf16 v[170:173], v[150:153], v[10:13], v[54:57]
	v_mfma_f32_16x16x32_bf16 v[174:177], v[158:161], v[10:13], v[50:53]
	v_mfma_f32_16x16x32_bf16 v[178:181], v[150:153], v[186:189], v[38:41]
	v_mfma_f32_16x16x32_bf16 v[182:185], v[158:161], v[186:189], v[34:37]
	v_mfma_f32_16x16x32_bf16 v[2:5], v[150:153], v[210:213], v[22:25]
	v_mfma_f32_16x16x32_bf16 v[6:9], v[158:161], v[210:213], v[18:21]
	v_mfma_f32_16x16x32_bf16 v[54:57], v[154:157], v[14:17], v[170:173]
	v_mfma_f32_16x16x32_bf16 v[50:53], v[146:149], v[14:17], v[174:177]
	v_mfma_f32_16x16x32_bf16 v[38:41], v[154:157], v[190:193], v[178:181]
	v_mfma_f32_16x16x32_bf16 v[34:37], v[146:149], v[190:193], v[182:185]
	v_mfma_f32_16x16x32_bf16 v[22:25], v[154:157], v[214:217], v[2:5]
	v_mfma_f32_16x16x32_bf16 v[18:21], v[146:149], v[214:217], v[6:9]
	s_setprio 0
	s_barrier
	s_add_i32 s72, s72, 2
	s_add_u32 s45, s45, 0x100
	s_addc_u32 s71, s71, 0
	s_add_u32 s0, s0, 0x100
	s_addc_u32 s1, s1, 0
	s_cmp_gt_u32 s72, 13
	s_cbranch_scc0 .LBB0_1370
	s_and_b64 vcc, exec, s[30:31]
	s_cbranch_vccz .LBB0_1373
	s_barrier

; #define PG8_STAGE(bufoff, gbase, voff) do { _Pragma("unroll") for (int _i = 0; _i < 2; ++_i) \
;         __builtin_amdgcn_global_load_lds((const unsigned*)((const char*)(gbase) + (voff)[_i]), (PG8_LAS unsigned*)(lds + (bufoff) + ldsw + _i * 8192), 16, 0, 0); } while (0)
; #define PG8_LDA(dst, b, h) do { _Pragma("unroll") for (int m = 0; m < 4; ++m) _Pragma("unroll") for (int k = 0; k < 2; ++k) dst[m][k] = *(const PG8_LAS bf16x8*)(lds + PG8_SA(b, h) + aoff + m * 2048 + k * 1024); } while (0)
; #define PG8_LDB(dst, b, h) do { _Pragma("unroll") for (int n = 0; n < 2; ++n) _Pragma("unroll") for (int k = 0; k < 2; ++k) dst[n][k] = *(const PG8_LAS bf16x8*)(lds + PG8_SB(b, h) + boff + n * 2048 + k * 1024); } while (0)
; #define PG8_MMA(ai, bj, At, Bt) do { __builtin_amdgcn_s_setprio(1); _Pragma("unroll") for (int m = 0; m < 4; ++m) _Pragma("unroll") for (int n = 0; n < 2; ++n) _Pragma("unroll") for (int k = 0; k < 2; ++k) \
;         acc[ai][bj][m][n] = Gemm::i8 ? ::mfma16i8_g(Bt[n][k], At[m][k], acc[ai][bj][m][n]) : ::mfma16_g(Bt[n][k], At[m][k], acc[ai][bj][m][n]); __builtin_amdgcn_s_setprio(0); } while (0)
; #define PG8_WAIT_V(n) asm volatile("s_waitcnt vmcnt(" #n ")" ::: "memory")
; #define PG8_WAIT_L(n) asm volatile("s_waitcnt lgkmcnt(" #n ")" ::: "memory")
; template <class Epi, class Sched, class Gemm, bool ALIGN_EPI = false, bool SP2 = false>
; __device__ __forceinline__ void gemm_phase(PG8_LAS unsigned char* lds, const Gemm g, const Sched& S, const Epi& E) {
;     ...
;             PG8_LDB(B0, 0, 0); PG8_LDB(B1, 0, 1); PG8_SCHED; PG8_LDA(At, 0, 0); PG8_STAGE(PG8_SA(1, 1), a1 + hstepA, voffA);
;             PG8_WAIT_V(8); PG8_WAIT_L(0); PG8_BAR; PG8_MMA(0, 0, At, B0); PG8_MMA(0, 1, At, B1); PG8_BAR; PG8_SCHED;
;             PG8_LDA(At, 0, 1); PG8_STAGE(PG8_SB(0, 0), b2, voffB); PG8_STAGE(PG8_SB(0, 1), b2 + hB1, voffB1); PG8_STAGE(PG8_SA(0, 0), a2, voffA);
;             PG8_WAIT_V(8); PG8_WAIT_L(0); PG8_BAR; PG8_MMA(1, 0, At, B0); PG8_MMA(1, 1, At, B1); PG8_BAR; PG8_SCHED;
;             PG8_LDB(B0, 1, 0); PG8_LDB(B1, 1, 1); PG8_SCHED; PG8_LDA(At, 1, 0); PG8_STAGE(PG8_SA(0, 1), a2 + hstepA, voffA);
;             PG8_WAIT_V(8); PG8_WAIT_L(0); PG8_BAR; PG8_MMA(0, 0, At, B0); PG8_MMA(0, 1, At, B1); PG8_BAR; PG8_SCHED;
;             PG8_LDA(At, 1, 1); PG8_STAGE(PG8_SB(1, 0), b3, voffB); PG8_STAGE(PG8_SB(1, 1), b3 + hB1, voffB1); PG8_STAGE(PG8_SA(1, 0), a3, voffA);
.Lfw_2:
	s_waitcnt lgkmcnt(0)
	s_nop 0
	s_setprio 1
	s_barrier
	v_mfma_i32_16x16x64_i8 v[224:227], v[172:175], v[164:167], v[126:129]
	v_mfma_i32_16x16x64_i8 v[126:129], v[188:191], v[168:171], v[224:227]
	v_mfma_i32_16x16x64_i8 v[228:231], v[192:195], v[164:167], v[122:125]
	v_mfma_i32_16x16x64_i8 v[232:235], v[172:175], v[200:203], v[110:113]
	v_mfma_i32_16x16x64_i8 v[236:239], v[192:195], v[200:203], v[106:109]
	v_mfma_i32_16x16x64_i8 v[240:243], v[172:175], v[208:211], v[94:97]
	v_mfma_i32_16x16x64_i8 v[244:247], v[192:195], v[208:211], v[90:93]
	v_mfma_i32_16x16x64_i8 v[224:227], v[172:175], v[216:219], v[78:81]
	v_mfma_i32_16x16x64_i8 v[74:77], v[192:195], v[216:219], v[74:77]
	v_mfma_i32_16x16x64_i8 v[122:125], v[196:199], v[168:171], v[228:231]
	v_mfma_i32_16x16x64_i8 v[110:113], v[188:191], v[204:207], v[232:235]
	v_mfma_i32_16x16x64_i8 v[106:109], v[196:199], v[204:207], v[236:239]
	v_mfma_i32_16x16x64_i8 v[94:97], v[188:191], v[212:215], v[240:243]
	v_mfma_i32_16x16x64_i8 v[90:93], v[196:199], v[212:215], v[244:247]
	v_mfma_i32_16x16x64_i8 v[78:81], v[188:191], v[220:223], v[224:227]
	v_mfma_i32_16x16x64_i8 v[74:77], v[196:199], v[220:223], v[74:77]
	s_setprio 0
	s_setprio 1
	v_mfma_i32_16x16x64_i8 v[224:227], v[134:137], v[164:167], v[118:121]
	v_mfma_i32_16x16x64_i8 v[118:121], v[138:141], v[168:171], v[224:227]
	v_mfma_i32_16x16x64_i8 v[228:231], v[142:145], v[164:167], v[114:117]
	v_mfma_i32_16x16x64_i8 v[232:235], v[134:137], v[200:203], v[102:105]
	v_mfma_i32_16x16x64_i8 v[236:239], v[142:145], v[200:203], v[98:101]
	v_mfma_i32_16x16x64_i8 v[240:243], v[134:137], v[208:211], v[86:89]
	v_mfma_i32_16x16x64_i8 v[244:247], v[142:145], v[208:211], v[82:85]
	v_mfma_i32_16x16x64_i8 v[164:167], v[134:137], v[216:219], v[70:73]
	v_mfma_i32_16x16x64_i8 v[66:69], v[142:145], v[216:219], v[66:69]
	v_mfma_i32_16x16x64_i8 v[114:117], v[130:133], v[168:171], v[228:231]
	v_mfma_i32_16x16x64_i8 v[102:105], v[138:141], v[204:207], v[232:235]
	v_mfma_i32_16x16x64_i8 v[98:101], v[130:133], v[204:207], v[236:239]
	v_mfma_i32_16x16x64_i8 v[86:89], v[138:141], v[212:215], v[240:243]
	v_mfma_i32_16x16x64_i8 v[82:85], v[130:133], v[212:215], v[244:247]
	v_mfma_i32_16x16x64_i8 v[70:73], v[138:141], v[220:223], v[164:167]
	v_mfma_i32_16x16x64_i8 v[66:69], v[130:133], v[220:223], v[66:69]
	s_setprio 0
	s_barrier
	s_add_i32 s65, s55, s43
	v_lshl_add_u64 v[164:165], s[40:41], 0, v[148:149]
	s_mov_b32 m0, s65
	ds_read_b128 v[200:203], v187 offset:16384
	ds_read_b128 v[204:207], v187 offset:17408
	ds_read_b128 v[208:211], v187 offset:18432
	ds_read_b128 v[212:215], v187 offset:19456
	ds_read_b128 v[216:219], v187 offset:20480
	ds_read_b128 v[220:223], v187 offset:21504
	ds_read_b128 v[224:227], v187 offset:22528
	ds_read_b128 v[228:231], v187 offset:23552
	global_load_lds_dwordx4 v148, s[40:41]
	s_add_i32 m0, s65, 0x2000
	s_add_u32 s66, s40, 0x2000
	v_lshl_add_u64 v[166:167], s[40:41], 0, v[152:153]
	s_addc_u32 s67, s41, 0
	s_add_i32 s65, s56, s43
	global_load_lds_dwordx4 v152, s[40:41]
	s_mov_b32 m0, s65
	v_lshl_add_u64 v[168:169], s[2:3], 0, v[146:147]
	global_load_lds_dwordx4 v148, s[66:67]
	v_lshl_add_u64 v[160:161], s[66:67], 0, v[152:153]
	s_add_i32 m0, s65, 0x2000
	v_lshl_add_u64 v[170:171], s[2:3], 0, v[150:151]
	global_load_lds_dwordx4 v152, s[66:67]
	s_mov_b32 m0, s39
	s_nop 0
	global_load_lds_dwordx4 v146, s[2:3]
	s_mov_b32 m0, s46
	s_nop 0
	global_load_lds_dwordx4 v150, s[2:3]
	s_cbranch_vccnz .Lfw_3
	s_waitcnt vmcnt(8)
.Lfw_3:
	s_waitcnt lgkmcnt(0)
	s_nop 0
	s_setprio 1
	s_barrier
	v_mfma_i32_16x16x64_i8 v[232:235], v[172:175], v[200:203], v[62:65]
	v_mfma_i32_16x16x64_i8 v[62:65], v[188:191], v[204:207], v[232:235]
	v_mfma_i32_16x16x64_i8 v[236:239], v[192:195], v[200:203], v[58:61]
	v_mfma_i32_16x16x64_i8 v[240:243], v[172:175], v[208:211], v[46:49]
	v_mfma_i32_16x16x64_i8 v[244:247], v[192:195], v[208:211], v[42:45]
	v_mfma_i32_16x16x64_i8 v[248:251], v[172:175], v[216:219], v[30:33]
	v_mfma_i32_16x16x64_i8 v[160:163], v[192:195], v[216:219], v[26:29]
	v_mfma_i32_16x16x64_i8 v[232:235], v[172:175], v[224:227], v[14:17]
	v_mfma_i32_16x16x64_i8 v[10:13], v[192:195], v[224:227], v[10:13]
	v_mfma_i32_16x16x64_i8 v[58:61], v[196:199], v[204:207], v[236:239]
	v_mfma_i32_16x16x64_i8 v[46:49], v[188:191], v[212:215], v[240:243]
	v_mfma_i32_16x16x64_i8 v[42:45], v[196:199], v[212:215], v[244:247]
	v_mfma_i32_16x16x64_i8 v[30:33], v[188:191], v[220:223], v[248:251]
	v_mfma_i32_16x16x64_i8 v[26:29], v[196:199], v[220:223], v[160:163]
	v_mfma_i32_16x16x64_i8 v[14:17], v[188:191], v[228:231], v[232:235]
	v_mfma_i32_16x16x64_i8 v[10:13], v[196:199], v[228:231], v[10:13]
	s_setprio 0
	s_setprio 1
	v_mfma_i32_16x16x64_i8 v[160:163], v[134:137], v[200:203], v[54:57]
	v_mfma_i32_16x16x64_i8 v[54:57], v[138:141], v[204:207], v[160:163]
	v_mfma_i32_16x16x64_i8 v[172:175], v[142:145], v[200:203], v[50:53]
	v_mfma_i32_16x16x64_i8 v[188:191], v[134:137], v[208:211], v[38:41]
	v_mfma_i32_16x16x64_i8 v[192:195], v[142:145], v[208:211], v[34:37]
	v_mfma_i32_16x16x64_i8 v[196:199], v[134:137], v[216:219], v[22:25]
	v_mfma_i32_16x16x64_i8 v[232:235], v[142:145], v[216:219], v[18:21]
	v_mfma_i32_16x16x64_i8 v[160:163], v[134:137], v[224:227], v[6:9]
	v_mfma_i32_16x16x64_i8 v[2:5], v[142:145], v[224:227], v[2:5]
	v_mfma_i32_16x16x64_i8 v[50:53], v[130:133], v[204:207], v[172:175]
	v_mfma_i32_16x16x64_i8 v[38:41], v[138:141], v[212:215], v[188:191]
	v_mfma_i32_16x16x64_i8 v[34:37], v[130:133], v[212:215], v[192:195]
	v_mfma_i32_16x16x64_i8 v[22:25], v[138:141], v[220:223], v[196:199]
	v_mfma_i32_16x16x64_i8 v[18:21], v[130:133], v[220:223], v[232:235]
	v_mfma_i32_16x16x64_i8 v[6:9], v[138:141], v[228:231], v[160:163]
	v_mfma_i32_16x16x64_i8 v[2:5], v[130:133], v[228:231], v[2:5]
	s_setprio 0
	s_barrier
; #define PG8_STAGE(bufoff, gbase, voff) do { _Pragma("unroll") for (int _i = 0; _i < 2; ++_i) \
;         __builtin_amdgcn_global_load_lds((const unsigned*)((const char*)(gbase) + (voff)[_i]), (PG8_LAS unsigned*)(lds + (bufoff) + ldsw + _i * 8192), 16, 0, 0); } while (0)
; #define PG8_LDA(dst, b, h) do { _Pragma("unroll") for (int m = 0; m < 4; ++m) _Pragma("unroll") for (int k = 0; k < 2; ++k) dst[m][k] = *(const PG8_LAS bf16x8*)(lds + PG8_SA(b, h) + aoff + m * 2048 + k * 1024); } while (0)
; #define PG8_LDB(dst, b, h) do { _Pragma("unroll") for (int n = 0; n < 2; ++n) _Pragma("unroll") for (int k = 0; k < 2; ++k) dst[n][k] = *(const PG8_LAS bf16x8*)(lds + PG8_SB(b, h) + boff + n * 2048 + k * 1024); } while (0)
; #define PG8_MMA(ai, bj, At, Bt) do { __builtin_amdgcn_s_setprio(1); _Pragma("unroll") for (int m = 0; m < 4; ++m) _Pragma("unroll") for (int n = 0; n < 2; ++n) _Pragma("unroll") for (int k = 0; k < 2; ++k) \
;         acc[ai][bj][m][n] = Gemm::i8 ? ::mfma16i8_g(Bt[n][k], At[m][k], acc[ai][bj][m][n]) : ::mfma16_g(Bt[n][k], At[m][k], acc[ai][bj][m][n]); __builtin_amdgcn_s_setprio(0); } while (0)
; #define PG8_WAIT_V(n) asm volatile("s_waitcnt vmcnt(" #n ")" ::: "memory")
; #define PG8_WAIT_L(n) asm volatile("s_waitcnt lgkmcnt(" #n ")" ::: "memory")
; template <class Epi, class Sched, class Gemm, bool ALIGN_EPI = false, bool SP2 = false>
; __device__ __forceinline__ void gemm_phase(PG8_LAS unsigned char* lds, const Gemm g, const Sched& S, const Epi& E) {
;     ...
;             PG8_LDB(B0, 0, 0); PG8_LDB(B1, 0, 1); PG8_SCHED; PG8_LDA(At, 0, 0); PG8_STAGE(PG8_SA(1, 1), a1 + hstepA, voffA);
;             PG8_WAIT_V(8); PG8_WAIT_L(0); PG8_BAR; PG8_MMA(0, 0, At, B0); PG8_MMA(0, 1, At, B1); PG8_BAR; PG8_SCHED;
;             PG8_LDA(At, 0, 1); PG8_STAGE(PG8_SB(0, 0), b2, voffB); PG8_STAGE(PG8_SB(0, 1), b2 + hB1, voffB1); PG8_STAGE(PG8_SA(0, 0), a2, voffA);
;             PG8_WAIT_V(8); PG8_WAIT_L(0); PG8_BAR; PG8_MMA(1, 0, At, B0); PG8_MMA(1, 1, At, B1); PG8_BAR; PG8_SCHED;
;             PG8_LDB(B0, 1, 0); PG8_LDB(B1, 1, 1); PG8_SCHED; PG8_LDA(At, 1, 0); PG8_STAGE(PG8_SA(0, 1), a2 + hstepA, voffA);
;             PG8_WAIT_V(8); PG8_WAIT_L(0); PG8_BAR; PG8_MMA(0, 0, At, B0); PG8_MMA(0, 1, At, B1); PG8_BAR; PG8_SCHED;
;             PG8_LDA(At, 1, 1); PG8_STAGE(PG8_SB(1, 0), b3, voffB); PG8_STAGE(PG8_SB(1, 1), b3 + hB1, voffB1); PG8_STAGE(PG8_SA(1, 0), a3, voffA);
	s_add_i32 s65, 0, 0x18000
	s_add_i32 s66, 0, 0x1c000
	v_add_u32_e32 v130, s65, v181
	v_add_u32_e32 v131, s66, v181
	ds_read_b128 v[160:163], v130
	ds_read_b128 v[172:175], v130 offset:1024
	ds_read_b128 v[188:191], v130 offset:2048
	ds_read_b128 v[192:195], v130 offset:3072
	ds_read_b128 v[134:137], v131
	ds_read_b128 v[138:141], v131 offset:1024
	ds_read_b128 v[142:145], v131 offset:2048
	ds_read_b128 v[130:133], v131 offset:3072
	s_add_u32 s2, s2, 0x20000
	s_addc_u32 s3, s3, 0
	s_mov_b32 m0, s47
	ds_read_b128 v[196:199], v187 offset:32768
	ds_read_b128 v[200:203], v187 offset:33792
	ds_read_b128 v[204:207], v187 offset:34816
	ds_read_b128 v[208:211], v187 offset:35840
	ds_read_b128 v[212:215], v187 offset:36864
	ds_read_b128 v[216:219], v187 offset:37888
	ds_read_b128 v[220:223], v187 offset:38912
	ds_read_b128 v[224:227], v187 offset:39936
	global_load_lds_dwordx4 v146, s[2:3]
	v_lshl_add_u64 v[176:177], s[2:3], 0, v[150:151]
	s_mov_b32 m0, s48
	s_nop 0
	global_load_lds_dwordx4 v150, s[2:3]
	s_waitcnt vmcnt(8)
	s_waitcnt lgkmcnt(0)
	s_nop 0
	s_setprio 1
	s_barrier
	v_mfma_i32_16x16x64_i8 v[228:231], v[160:163], v[196:199], v[126:129]
	v_mfma_i32_16x16x64_i8 v[126:129], v[172:175], v[200:203], v[228:231]
	v_mfma_i32_16x16x64_i8 v[232:235], v[188:191], v[196:199], v[122:125]
	v_mfma_i32_16x16x64_i8 v[236:239], v[160:163], v[204:207], v[110:113]
	v_mfma_i32_16x16x64_i8 v[240:243], v[188:191], v[204:207], v[106:109]
	v_mfma_i32_16x16x64_i8 v[244:247], v[160:163], v[212:215], v[94:97]
	v_mfma_i32_16x16x64_i8 v[248:251], v[188:191], v[212:215], v[90:93]
	v_mfma_i32_16x16x64_i8 v[228:231], v[160:163], v[220:223], v[78:81]
	v_mfma_i32_16x16x64_i8 v[74:77], v[188:191], v[220:223], v[74:77]
	v_mfma_i32_16x16x64_i8 v[122:125], v[192:195], v[200:203], v[232:235]
	v_mfma_i32_16x16x64_i8 v[110:113], v[172:175], v[208:211], v[236:239]
	v_mfma_i32_16x16x64_i8 v[106:109], v[192:195], v[208:211], v[240:243]
	v_mfma_i32_16x16x64_i8 v[94:97], v[172:175], v[216:219], v[244:247]
	v_mfma_i32_16x16x64_i8 v[90:93], v[192:195], v[216:219], v[248:251]
	v_mfma_i32_16x16x64_i8 v[78:81], v[172:175], v[224:227], v[228:231]
	v_mfma_i32_16x16x64_i8 v[74:77], v[192:195], v[224:227], v[74:77]
	s_setprio 0
	s_setprio 1
	v_mfma_i32_16x16x64_i8 v[228:231], v[134:137], v[196:199], v[118:121]
	v_mfma_i32_16x16x64_i8 v[118:121], v[138:141], v[200:203], v[228:231]
	v_mfma_i32_16x16x64_i8 v[232:235], v[142:145], v[196:199], v[114:117]
	v_mfma_i32_16x16x64_i8 v[236:239], v[134:137], v[204:207], v[102:105]
	v_mfma_i32_16x16x64_i8 v[240:243], v[142:145], v[204:207], v[98:101]
	v_mfma_i32_16x16x64_i8 v[244:247], v[134:137], v[212:215], v[86:89]
	v_mfma_i32_16x16x64_i8 v[248:251], v[142:145], v[212:215], v[82:85]
	v_mfma_i32_16x16x64_i8 v[196:199], v[134:137], v[220:223], v[70:73]
	v_mfma_i32_16x16x64_i8 v[66:69], v[142:145], v[220:223], v[66:69]
	v_mfma_i32_16x16x64_i8 v[114:117], v[130:133], v[200:203], v[232:235]
	v_mfma_i32_16x16x64_i8 v[102:105], v[138:141], v[208:211], v[236:239]
	v_mfma_i32_16x16x64_i8 v[98:101], v[130:133], v[208:211], v[240:243]
	v_mfma_i32_16x16x64_i8 v[86:89], v[138:141], v[216:219], v[244:247]
	v_mfma_i32_16x16x64_i8 v[82:85], v[130:133], v[216:219], v[248:251]
	v_mfma_i32_16x16x64_i8 v[70:73], v[138:141], v[224:227], v[196:199]
	v_mfma_i32_16x16x64_i8 v[66:69], v[130:133], v[224:227], v[66:69]
	s_setprio 0
	s_barrier
	s_add_i32 s2, s65, s43
	v_lshl_add_u64 v[164:165], v[164:165], 0, s[18:19]
	s_mov_b32 m0, s2
	ds_read_b128 v[196:199], v187 offset:49152
	ds_read_b128 v[200:203], v187 offset:50176
	ds_read_b128 v[204:207], v187 offset:51200
	ds_read_b128 v[208:211], v187 offset:52224
	ds_read_b128 v[212:215], v187 offset:53248
	ds_read_b128 v[216:219], v187 offset:54272
	ds_read_b128 v[220:223], v187 offset:55296
	ds_read_b128 v[224:227], v187 offset:56320
	global_load_lds_dwordx4 v[164:165], off
	s_add_i32 m0, s2, 0x2000
	s_add_u32 s2, s40, 0x2080
	v_lshl_add_u64 v[164:165], v[166:167], 0, s[18:19]
	s_addc_u32 s3, s41, 0
	s_add_i32 s40, s66, s43
	global_load_lds_dwordx4 v[164:165], off
	s_mov_b32 m0, s40
	s_nop 0
	global_load_lds_dwordx4 v148, s[2:3]
	s_add_i32 m0, s40, 0x2000
	s_nop 0
	global_load_lds_dwordx4 v152, s[2:3]
	v_lshl_add_u64 v[164:165], v[168:169], 0, s[18:19]
	s_mov_b32 m0, s51
	s_nop 0
	global_load_lds_dwordx4 v[164:165], off
	v_lshl_add_u64 v[164:165], v[170:171], 0, s[18:19]
	s_mov_b32 m0, s52
	s_nop 0
	global_load_lds_dwordx4 v[164:165], off
	s_waitcnt vmcnt(8)
	s_waitcnt lgkmcnt(0)
	s_nop 0
	s_setprio 1
	s_barrier
	v_mfma_i32_16x16x64_i8 v[164:167], v[160:163], v[196:199], v[62:65]
	v_mfma_i32_16x16x64_i8 v[62:65], v[172:175], v[200:203], v[164:167]
	v_mfma_i32_16x16x64_i8 v[168:171], v[188:191], v[196:199], v[58:61]
	v_mfma_i32_16x16x64_i8 v[228:231], v[160:163], v[204:207], v[46:49]
	v_mfma_i32_16x16x64_i8 v[232:235], v[188:191], v[204:207], v[42:45]
	v_mfma_i32_16x16x64_i8 v[236:239], v[160:163], v[212:215], v[30:33]
	v_mfma_i32_16x16x64_i8 v[240:243], v[188:191], v[212:215], v[26:29]
	v_mfma_i32_16x16x64_i8 v[164:167], v[160:163], v[220:223], v[14:17]
	v_mfma_i32_16x16x64_i8 v[10:13], v[188:191], v[220:223], v[10:13]
	v_mfma_i32_16x16x64_i8 v[58:61], v[192:195], v[200:203], v[168:171]
	v_mfma_i32_16x16x64_i8 v[46:49], v[172:175], v[208:211], v[228:231]
	v_mfma_i32_16x16x64_i8 v[42:45], v[192:195], v[208:211], v[232:235]
	v_mfma_i32_16x16x64_i8 v[30:33], v[172:175], v[216:219], v[236:239]
	v_mfma_i32_16x16x64_i8 v[26:29], v[192:195], v[216:219], v[240:243]
	v_mfma_i32_16x16x64_i8 v[14:17], v[172:175], v[224:227], v[164:167]
	v_mfma_i32_16x16x64_i8 v[10:13], v[192:195], v[224:227], v[10:13]
	s_setprio 0
	s_setprio 1
	v_mfma_i32_16x16x64_i8 v[160:163], v[134:137], v[196:199], v[54:57]
	v_mfma_i32_16x16x64_i8 v[54:57], v[138:141], v[200:203], v[160:163]
	v_mfma_i32_16x16x64_i8 v[164:167], v[142:145], v[196:199], v[50:53]
	v_mfma_i32_16x16x64_i8 v[168:171], v[134:137], v[204:207], v[38:41]
	v_mfma_i32_16x16x64_i8 v[172:175], v[142:145], v[204:207], v[34:37]
	v_mfma_i32_16x16x64_i8 v[188:191], v[134:137], v[212:215], v[22:25]
	v_mfma_i32_16x16x64_i8 v[192:195], v[142:145], v[212:215], v[18:21]
	v_mfma_i32_16x16x64_i8 v[160:163], v[134:137], v[220:223], v[6:9]
	v_mfma_i32_16x16x64_i8 v[2:5], v[142:145], v[220:223], v[2:5]
	v_mfma_i32_16x16x64_i8 v[50:53], v[130:133], v[200:203], v[164:167]
	v_mfma_i32_16x16x64_i8 v[38:41], v[138:141], v[208:211], v[168:171]
	v_mfma_i32_16x16x64_i8 v[34:37], v[130:133], v[208:211], v[172:175]
	v_mfma_i32_16x16x64_i8 v[22:25], v[138:141], v[216:219], v[188:191]
	v_mfma_i32_16x16x64_i8 v[18:21], v[130:133], v[216:219], v[192:195]
	v_mfma_i32_16x16x64_i8 v[6:9], v[138:141], v[224:227], v[160:163]
	v_mfma_i32_16x16x64_i8 v[2:5], v[130:133], v[224:227], v[2:5]
	s_setprio 0
	s_barrier
;     __device__ __forceinline__ void operator()(const f32x4 (&acc)[2][2][4][2], const Unit& u, int wr, int wc, int fr, int fq) const {
;         asm volatile("" : "+v"(fr), "+v"(fq));
;         const int row0 = u.pm * BM + wr * 64 + fr, col0 = u.pn * BM + wc * 64 + 16 * fq;
;         const int gn = u.pn >> 2, gbase = (gn < 3) ? 3072 + 1024 * gn : 0;
;         f32x4 bv[2][2];
; #pragma unroll
;         for (int bj = 0; bj < 2; ++bj)
; #pragma unroll
;             for (int n = 0; n < 2; ++n) bv[bj][n] = *(const f32x4*)(bias + col0 + 8 * bj + 4 * n) * -1.44269504f;
;         f32x4 wv[2][2];
; #pragma unroll
;         for (int bj = 0; bj < 2; ++bj)
; #pragma unroll
;             for (int n = 0; n < 2; ++n) wv[bj][n] = *(const f32x4*)(SW + col0 + 8 * bj + 4 * n) * -1.44269504f;
;         float rsv[8];
; #pragma unroll
;         for (int i = 0; i < 8; ++i) rsv[i] = SH[row0 + (i >> 2) * HALF + (i & 3) * 16];
	s_add_i32 s64, s64, 2
	s_add_u32 s62, s62, 0x100
	s_addc_u32 s63, s63, 0
	s_add_u32 s0, s0, 0x100
	s_addc_u32 s1, s1, 0
	s_cmp_gt_u32 s64, 5
	s_mov_b64 vcc, 0
	s_cbranch_scc0 .LBB0_2552
	s_lshl_b32 s0, s59, 8
	v_mov_b32_e32 v154, v1
	v_mov_b32_e32 v130, v179
	s_or_b32 s0, s0, s53
	v_cvt_f32_i32_e32 v212, v122
	v_lshl_add_u32 v144, v130, 4, s0
	s_lshl_b32 s0, s38, 8
	v_ashrrev_i32_e32 v145, 31, v144
	s_add_i32 s0, s0, s50
	v_lshlrev_b64 v[142:143], 2, v[144:145]
	v_add_u32_e32 v164, s0, v154
	v_lshl_add_u64 v[160:161], s[14:15], 0, v[142:143]
	v_ashrrev_i32_e32 v165, 31, v164
	global_load_dwordx4 v[130:133], v[160:161], off
	global_load_dwordx4 v[134:137], v[160:161], off offset:16
	global_load_dwordx4 v[138:141], v[160:161], off offset:32
	s_nop 0
	global_load_dwordx4 v[160:163], v[160:161], off offset:48
	v_lshl_add_u64 v[142:143], s[16:17], 0, v[142:143]
	v_lshl_add_u64 v[170:171], v[164:165], 2, s[12:13]
	global_load_dwordx4 v[166:169], v[142:143], off
	global_load_dwordx4 v[194:197], v[142:143], off offset:16
	global_load_dwordx4 v[198:201], v[142:143], off offset:32
	global_load_dwordx4 v[202:205], v[142:143], off offset:48
	global_load_dword v206, v[170:171], off
	global_load_dword v188, v[170:171], off offset:64
	global_load_dword v186, v[170:171], off offset:128
	global_load_dword v184, v[170:171], off offset:192
	global_load_dword v182, v[170:171], off offset:512
	global_load_dword v180, v[170:171], off offset:576
	global_load_dword v178, v[170:171], off offset:640
	global_load_dword v122, v[170:171], off offset:704
	s_ashr_i32 s0, s59, 2
	s_lshl_b32 s1, s0, 10
	v_mov_b64_e32 v[142:143], s[10:11]
	s_add_i32 s2, s1, 0xc00
	v_cvt_f32_i32_e32 v209, v127
	v_cvt_f32_i32_e32 v208, v126
	v_cvt_f32_i32_e32 v215, v125
	v_cvt_f32_i32_e32 v214, v124
	s_cmp_lt_i32 s0, 3
	v_mad_i64_i32 v[124:125], s[0:1], v164, s57, v[142:143]
	s_cselect_b32 s0, s2, 0
	v_cvt_f32_i32_e32 v211, v129
	v_cvt_f32_i32_e32 v210, v128
	s_ashr_i32 s1, s0, 31
	v_cvt_f32_i32_e32 v115, v115
	v_cvt_f32_i32_e32 v114, v114
	v_cvt_f32_i32_e32 v99, v99
	v_cvt_f32_i32_e32 v98, v98
	v_cvt_f32_i32_e32 v83, v83
	v_cvt_f32_i32_e32 v82, v82
	v_cvt_f32_i32_e32 v67, v67
	v_cvt_f32_i32_e32 v66, v66
	v_cvt_f32_i32_e32 v51, v51
	v_cvt_f32_i32_e32 v50, v50
	v_cvt_f32_i32_e32 v35, v35
	v_cvt_f32_i32_e32 v34, v34
	v_cvt_f32_i32_e32 v19, v19
	v_cvt_f32_i32_e32 v18, v18
	v_and_b32_e32 v154, 0x3f0, v144
	v_lshl_add_u64 v[124:125], v[124:125], 0, s[0:1]
	v_cvt_f32_i32_e32 v117, v117
	v_cvt_f32_i32_e32 v116, v116
	v_cvt_f32_i32_e32 v111, v111
	v_cvt_f32_i32_e32 v110, v110
	v_cvt_f32_i32_e32 v101, v101
	v_cvt_f32_i32_e32 v100, v100
	v_cvt_f32_i32_e32 v95, v95
	v_cvt_f32_i32_e32 v94, v94
	v_cvt_f32_i32_e32 v85, v85
	v_cvt_f32_i32_e32 v84, v84
	v_cvt_f32_i32_e32 v79, v79
	v_cvt_f32_i32_e32 v78, v78
	v_cvt_f32_i32_e32 v69, v69
	v_cvt_f32_i32_e32 v68, v68
	v_cvt_f32_i32_e32 v63, v63
	v_cvt_f32_i32_e32 v62, v62
	v_cvt_f32_i32_e32 v53, v53
	v_cvt_f32_i32_e32 v52, v52
	v_cvt_f32_i32_e32 v47, v47
	v_cvt_f32_i32_e32 v46, v46
	v_cvt_f32_i32_e32 v37, v37
	v_cvt_f32_i32_e32 v36, v36
	v_cvt_f32_i32_e32 v31, v31
	v_cvt_f32_i32_e32 v30, v30
	v_cvt_f32_i32_e32 v21, v21
	v_cvt_f32_i32_e32 v20, v20
	v_cvt_f32_i32_e32 v15, v15
	v_cvt_f32_i32_e32 v14, v14
	v_add_u32_e32 v207, 32, v164
	v_lshl_add_u64 v[216:217], v[124:125], 0, v[154:155]
	v_add_u32_e32 v189, 0xa0, v164
	v_cvt_f32_i32_e32 v213, v123
	v_add_u32_e32 v123, 0xb0, v164
	v_cvt_f32_i32_e32 v119, v119
	v_cvt_f32_i32_e32 v118, v118
	v_cvt_f32_i32_e32 v109, v109
	v_cvt_f32_i32_e32 v108, v108
	v_cvt_f32_i32_e32 v103, v103
	v_cvt_f32_i32_e32 v102, v102
	v_cvt_f32_i32_e32 v93, v93
	v_cvt_f32_i32_e32 v121, v121
	v_cvt_f32_i32_e32 v120, v120
	v_cvt_f32_i32_e32 v113, v113
	v_cvt_f32_i32_e32 v112, v112
	v_cvt_f32_i32_e32 v107, v107
	v_cvt_f32_i32_e32 v106, v106
	v_cvt_f32_i32_e32 v105, v105
	v_cvt_f32_i32_e32 v104, v104
	v_cvt_f32_i32_e32 v92, v92
	v_cvt_f32_i32_e32 v87, v87
	v_cvt_f32_i32_e32 v86, v86
	v_cvt_f32_i32_e32 v97, v97
	v_cvt_f32_i32_e32 v96, v96
	v_cvt_f32_i32_e32 v91, v91
	v_cvt_f32_i32_e32 v90, v90
	v_cvt_f32_i32_e32 v89, v89
	v_cvt_f32_i32_e32 v88, v88
	v_cvt_f32_i32_e32 v77, v77
	v_cvt_f32_i32_e32 v76, v76
	v_cvt_f32_i32_e32 v71, v71
	v_cvt_f32_i32_e32 v70, v70
	v_cvt_f32_i32_e32 v81, v81
	v_cvt_f32_i32_e32 v80, v80
	v_cvt_f32_i32_e32 v75, v75
	v_cvt_f32_i32_e32 v74, v74
	v_cvt_f32_i32_e32 v73, v73
	v_cvt_f32_i32_e32 v72, v72
	v_cvt_f32_i32_e32 v61, v61
	v_cvt_f32_i32_e32 v60, v60
	v_cvt_f32_i32_e32 v55, v55
	v_cvt_f32_i32_e32 v54, v54
	v_cvt_f32_i32_e32 v65, v65
	v_cvt_f32_i32_e32 v64, v64
	v_cvt_f32_i32_e32 v59, v59
	v_cvt_f32_i32_e32 v58, v58
	v_cvt_f32_i32_e32 v57, v57
	v_cvt_f32_i32_e32 v56, v56
	v_cvt_f32_i32_e32 v45, v45
	v_cvt_f32_i32_e32 v44, v44
	v_cvt_f32_i32_e32 v39, v39
	v_cvt_f32_i32_e32 v38, v38
	v_cvt_f32_i32_e32 v49, v49
	v_cvt_f32_i32_e32 v48, v48
	v_cvt_f32_i32_e32 v43, v43
	v_cvt_f32_i32_e32 v42, v42
	v_cvt_f32_i32_e32 v41, v41
	v_cvt_f32_i32_e32 v40, v40
	v_cvt_f32_i32_e32 v29, v29
	v_cvt_f32_i32_e32 v28, v28
	v_cvt_f32_i32_e32 v23, v23
	v_cvt_f32_i32_e32 v22, v22
	v_cvt_f32_i32_e32 v33, v33
	v_cvt_f32_i32_e32 v32, v32
	v_cvt_f32_i32_e32 v27, v27
	v_cvt_f32_i32_e32 v26, v26
	v_cvt_f32_i32_e32 v25, v25
	v_cvt_f32_i32_e32 v24, v24
	v_cvt_f32_i32_e32 v7, v7
	v_cvt_f32_i32_e32 v6, v6
	v_cvt_f32_i32_e32 v3, v3
	v_cvt_f32_i32_e32 v2, v2
	v_cvt_f32_i32_e32 v17, v17
	v_cvt_f32_i32_e32 v16, v16
	v_cvt_f32_i32_e32 v11, v11
	v_cvt_f32_i32_e32 v13, v13
	v_cvt_f32_i32_e32 v12, v12
	v_cvt_f32_i32_e32 v10, v10
	v_cvt_f32_i32_e32 v9, v9
	v_cvt_f32_i32_e32 v8, v8
	v_cvt_f32_i32_e32 v5, v5
	v_cvt_f32_i32_e32 v4, v4
	s_and_b64 vcc, exec, s[20:21]
	s_cbranch_vccz .LBB0_2555
	s_barrier

; #define PG8_STAGE(bufoff, gbase, voff) do { _Pragma("unroll") for (int _i = 0; _i < 2; ++_i) \
;         __builtin_amdgcn_global_load_lds((const unsigned*)((const char*)(gbase) + (voff)[_i]), (PG8_LAS unsigned*)(lds + (bufoff) + ldsw + _i * 8192), 16, 0, 0); } while (0)
; #define PG8_LDA(dst, b, h) do { _Pragma("unroll") for (int m = 0; m < 4; ++m) _Pragma("unroll") for (int k = 0; k < 2; ++k) dst[m][k] = *(const PG8_LAS bf16x8*)(lds + PG8_SA(b, h) + aoff + m * 2048 + k * 1024); } while (0)
; #define PG8_LDB(dst, b, h) do { _Pragma("unroll") for (int n = 0; n < 2; ++n) _Pragma("unroll") for (int k = 0; k < 2; ++k) dst[n][k] = *(const PG8_LAS bf16x8*)(lds + PG8_SB(b, h) + boff + n * 2048 + k * 1024); } while (0)
; #define PG8_WAIT_V(n) asm volatile("s_waitcnt vmcnt(" #n ")" ::: "memory")
; #define PG8_WAIT_L(n) asm volatile("s_waitcnt lgkmcnt(" #n ")" ::: "memory")
; #define PG8_BAR __builtin_amdgcn_s_barrier()
; #define PG8_SCHED __builtin_amdgcn_sched_barrier(0)
; template <class Epi, class Sched, class Gemm, bool ALIGN_EPI = false, bool SP2 = false>
; __device__ __forceinline__ void gemm_phase(PG8_LAS unsigned char* lds, const Gemm g, const Sched& S, const Epi& E) {
;     ...
;             PG8_LDB(B0, 0, 0); PG8_LDB(B1, 0, 1); PG8_SCHED; PG8_LDA(At, 0, 0); PG8_STAGE(PG8_SA(1, 1), a1 + hstepA, voffA);
;             PG8_WAIT_V(8); PG8_WAIT_L(0); PG8_BAR; PG8_MMA(0, 0, At, B0); PG8_MMA(0, 1, At, B1); PG8_BAR; PG8_SCHED;
;             PG8_LDA(At, 0, 1); PG8_STAGE(PG8_SB(0, 0), b2, voffB); PG8_STAGE(PG8_SB(0, 1), b2 + hB1, voffB1); PG8_STAGE(PG8_SA(0, 0), a2, voffA);
;             PG8_WAIT_V(8); PG8_WAIT_L(0); PG8_BAR; PG8_MMA(1, 0, At, B0); PG8_MMA(1, 1, At, B1); PG8_BAR; PG8_SCHED;
;             PG8_LDB(B0, 1, 0); PG8_LDB(B1, 1, 1); PG8_SCHED; PG8_LDA(At, 1, 0); PG8_STAGE(PG8_SA(0, 1), a2 + hstepA, voffA);
;             PG8_WAIT_V(8); PG8_WAIT_L(0); PG8_BAR; PG8_MMA(0, 0, At, B0); PG8_MMA(0, 1, At, B1); PG8_BAR; PG8_SCHED;
;             PG8_LDA(At, 1, 1); PG8_STAGE(PG8_SB(1, 0), b3, voffB); PG8_STAGE(PG8_SB(1, 1), b3 + hB1, voffB1); PG8_STAGE(PG8_SA(1, 0), a3, voffA);
;             PG8_WAIT_V(8);
;             if constexpr (epi_pre<Epi>::value) { if (last) E.pre(pre, cur, wr, wc, lane); }
;             PG8_WAIT_L(0); PG8_BAR; PG8_MMA(1, 0, At, B0); PG8_MMA(1, 1, At, B1); PG8_BAR; PG8_SCHED;
.LBB0_2633:
	s_add_u32 s42, s30, s36
	s_addc_u32 s43, s31, s37
	s_add_u32 s40, s42, 0x100
	s_addc_u32 s41, s43, 0
	s_and_b64 s[38:39], s[2:3], exec
	s_cselect_b32 s39, s1, s41
	s_cselect_b32 s38, s23, s40
	s_add_u32 s36, s28, s36
	s_addc_u32 s37, s29, s37
	s_add_u32 s36, s36, 0x100
	s_addc_u32 s37, s37, 0
	s_and_b64 s[2:3], s[2:3], exec
	s_cselect_b32 s41, s21, s37
	s_cselect_b32 s40, s67, s36
	s_add_u32 s74, s42, 0x40080
	s_addc_u32 s75, s43, 0
	s_add_i32 s77, s61, s49
	s_add_i32 m0, s50, 0xc000
	s_add_i32 s76, s50, 0xe000
	s_add_i32 s78, s77, 0x2000
	v_add_u32_e32 v2, s61, v184
	s_add_u32 s42, s40, 0x1000
	ds_read_b128 v[158:161], v2
	ds_read_b128 v[162:165], v2 offset:1024
	ds_read_b128 v[186:189], v2 offset:2048
	ds_read_b128 v[190:193], v2 offset:3072
	v_add_u32_e32 v2, s62, v184
	s_addc_u32 s43, s41, 0
	s_add_i32 s79, s62, s49
	ds_read_b128 v[138:141], v2
	ds_read_b128 v[142:145], v2 offset:1024
	ds_read_b128 v[146:149], v2 offset:2048
	ds_read_b128 v[134:137], v2 offset:3072
	s_add_i32 s80, s79, 0x2000
	s_add_i32 s73, 0, 0x18000
	s_add_i32 s72, 0, 0x1c000
	s_add_u32 s2, s38, 0x40000
	s_addc_u32 s3, s39, 0
	s_add_i32 s69, s73, s49
	s_add_i32 s68, s69, 0x2000
	s_add_u32 s36, s40, 0x1080
	s_addc_u32 s37, s41, 0
	s_add_i32 s71, s72, s49
	s_add_i32 s70, s71, 0x2000
	ds_read_b128 v[150:153], v185
	ds_read_b128 v[154:157], v185 offset:1024
	ds_read_b128 v[194:197], v185 offset:2048
	ds_read_b128 v[198:201], v185 offset:3072
	ds_read_b128 v[202:205], v185 offset:4096
	ds_read_b128 v[206:209], v185 offset:5120
	ds_read_b128 v[210:213], v185 offset:6144
	ds_read_b128 v[214:217], v185 offset:7168
	global_load_lds_dwordx4 v166, s[74:75]
	s_mov_b32 m0, s76
	s_nop 0
	global_load_lds_dwordx4 v170, s[74:75]
	s_waitcnt vmcnt(8)
	s_waitcnt lgkmcnt(0)
	s_nop 0
	s_setprio 1
	s_barrier
	v_mfma_f32_16x16x32_bf16 v[218:221], v[158:161], v[150:153], v[78:81]
	v_mfma_f32_16x16x32_bf16 v[78:81], v[162:165], v[154:157], v[218:221]
	v_mfma_f32_16x16x32_bf16 v[222:225], v[186:189], v[150:153], v[62:65]
	v_mfma_f32_16x16x32_bf16 v[226:229], v[158:161], v[194:197], v[130:133]
	v_mfma_f32_16x16x32_bf16 v[230:233], v[186:189], v[194:197], v[126:129]
	v_mfma_f32_16x16x32_bf16 v[234:237], v[158:161], v[202:205], v[74:77]
	v_mfma_f32_16x16x32_bf16 v[238:241], v[186:189], v[202:205], v[102:105]
	v_mfma_f32_16x16x32_bf16 v[218:221], v[158:161], v[210:213], v[122:125]
	v_mfma_f32_16x16x32_bf16 v[114:117], v[186:189], v[210:213], v[114:117]
	v_mfma_f32_16x16x32_bf16 v[62:65], v[190:193], v[154:157], v[222:225]
	v_mfma_f32_16x16x32_bf16 v[130:133], v[162:165], v[198:201], v[226:229]
	v_mfma_f32_16x16x32_bf16 v[126:129], v[190:193], v[198:201], v[230:233]
	v_mfma_f32_16x16x32_bf16 v[74:77], v[162:165], v[206:209], v[234:237]
	v_mfma_f32_16x16x32_bf16 v[102:105], v[190:193], v[206:209], v[238:241]
	v_mfma_f32_16x16x32_bf16 v[122:125], v[162:165], v[214:217], v[218:221]
	v_mfma_f32_16x16x32_bf16 v[114:117], v[190:193], v[214:217], v[114:117]
	s_setprio 0
	s_setprio 1
	v_mfma_f32_16x16x32_bf16 v[218:221], v[138:141], v[150:153], v[50:53]
	v_mfma_f32_16x16x32_bf16 v[50:53], v[142:145], v[154:157], v[218:221]
	v_mfma_f32_16x16x32_bf16 v[222:225], v[146:149], v[150:153], v[30:33]
	v_mfma_f32_16x16x32_bf16 v[226:229], v[138:141], v[194:197], v[110:113]
	v_mfma_f32_16x16x32_bf16 v[230:233], v[146:149], v[194:197], v[34:37]
	v_mfma_f32_16x16x32_bf16 v[234:237], v[138:141], v[202:205], v[46:49]
	v_mfma_f32_16x16x32_bf16 v[238:241], v[146:149], v[202:205], v[18:21]
	v_mfma_f32_16x16x32_bf16 v[150:153], v[138:141], v[210:213], v[90:93]
	v_mfma_f32_16x16x32_bf16 v[26:29], v[146:149], v[210:213], v[26:29]
	v_mfma_f32_16x16x32_bf16 v[30:33], v[134:137], v[154:157], v[222:225]
	v_mfma_f32_16x16x32_bf16 v[110:113], v[142:145], v[198:201], v[226:229]
	v_mfma_f32_16x16x32_bf16 v[34:37], v[134:137], v[198:201], v[230:233]
	v_mfma_f32_16x16x32_bf16 v[46:49], v[142:145], v[206:209], v[234:237]
	v_mfma_f32_16x16x32_bf16 v[18:21], v[134:137], v[206:209], v[238:241]
	v_mfma_f32_16x16x32_bf16 v[90:93], v[142:145], v[214:217], v[150:153]
	v_mfma_f32_16x16x32_bf16 v[26:29], v[134:137], v[214:217], v[26:29]
	s_setprio 0
	s_barrier
	s_mov_b32 m0, s77
	v_lshl_add_u64 v[150:151], s[40:41], 0, v[168:169]
	ds_read_b128 v[194:197], v185 offset:16384
	ds_read_b128 v[198:201], v185 offset:17408
	ds_read_b128 v[202:205], v185 offset:18432
	ds_read_b128 v[206:209], v185 offset:19456
	ds_read_b128 v[210:213], v185 offset:20480
	ds_read_b128 v[214:217], v185 offset:21504
	ds_read_b128 v[218:221], v185 offset:22528
	ds_read_b128 v[222:225], v185 offset:23552
	global_load_lds_dwordx4 v168, s[40:41]
	v_lshl_add_u64 v[152:153], s[40:41], 0, v[172:173]
	s_mov_b32 m0, s78
	v_lshl_add_u64 v[4:5], s[42:43], 0, v[168:169]
	global_load_lds_dwordx4 v172, s[40:41]
	s_mov_b32 m0, s79
	v_lshl_add_u64 v[154:155], s[38:39], 0, v[166:167]
	global_load_lds_dwordx4 v168, s[42:43]
	v_lshl_add_u64 v[4:5], s[42:43], 0, v[172:173]
	s_mov_b32 m0, s80
	v_lshl_add_u64 v[156:157], s[38:39], 0, v[170:171]
	global_load_lds_dwordx4 v172, s[42:43]
	s_mov_b32 m0, s50
	s_nop 0
	global_load_lds_dwordx4 v166, s[38:39]
	s_mov_b32 m0, s51
	s_nop 0
	global_load_lds_dwordx4 v170, s[38:39]
	s_waitcnt vmcnt(8)
	s_waitcnt lgkmcnt(0)
	s_nop 0
	s_setprio 1
	s_barrier
; #define PG8_STAGE(bufoff, gbase, voff) do { _Pragma("unroll") for (int _i = 0; _i < 2; ++_i) \
;         __builtin_amdgcn_global_load_lds((const unsigned*)((const char*)(gbase) + (voff)[_i]), (PG8_LAS unsigned*)(lds + (bufoff) + ldsw + _i * 8192), 16, 0, 0); } while (0)
; #define PG8_LDA(dst, b, h) do { _Pragma("unroll") for (int m = 0; m < 4; ++m) _Pragma("unroll") for (int k = 0; k < 2; ++k) dst[m][k] = *(const PG8_LAS bf16x8*)(lds + PG8_SA(b, h) + aoff + m * 2048 + k * 1024); } while (0)
; #define PG8_LDB(dst, b, h) do { _Pragma("unroll") for (int n = 0; n < 2; ++n) _Pragma("unroll") for (int k = 0; k < 2; ++k) dst[n][k] = *(const PG8_LAS bf16x8*)(lds + PG8_SB(b, h) + boff + n * 2048 + k * 1024); } while (0)
; #define PG8_WAIT_V(n) asm volatile("s_waitcnt vmcnt(" #n ")" ::: "memory")
; #define PG8_WAIT_L(n) asm volatile("s_waitcnt lgkmcnt(" #n ")" ::: "memory")
; #define PG8_BAR __builtin_amdgcn_s_barrier()
; #define PG8_SCHED __builtin_amdgcn_sched_barrier(0)
; template <class Epi, class Sched, class Gemm, bool ALIGN_EPI = false, bool SP2 = false>
; __device__ __forceinline__ void gemm_phase(PG8_LAS unsigned char* lds, const Gemm g, const Sched& S, const Epi& E) {
;     ...
;             PG8_LDB(B0, 0, 0); PG8_LDB(B1, 0, 1); PG8_SCHED; PG8_LDA(At, 0, 0); PG8_STAGE(PG8_SA(1, 1), a1 + hstepA, voffA);
;             PG8_WAIT_V(8); PG8_WAIT_L(0); PG8_BAR; PG8_MMA(0, 0, At, B0); PG8_MMA(0, 1, At, B1); PG8_BAR; PG8_SCHED;
;             PG8_LDA(At, 0, 1); PG8_STAGE(PG8_SB(0, 0), b2, voffB); PG8_STAGE(PG8_SB(0, 1), b2 + hB1, voffB1); PG8_STAGE(PG8_SA(0, 0), a2, voffA);
;             PG8_WAIT_V(8); PG8_WAIT_L(0); PG8_BAR; PG8_MMA(1, 0, At, B0); PG8_MMA(1, 1, At, B1); PG8_BAR; PG8_SCHED;
;             PG8_LDB(B0, 1, 0); PG8_LDB(B1, 1, 1); PG8_SCHED; PG8_LDA(At, 1, 0); PG8_STAGE(PG8_SA(0, 1), a2 + hstepA, voffA);
;             PG8_WAIT_V(8); PG8_WAIT_L(0); PG8_BAR; PG8_MMA(0, 0, At, B0); PG8_MMA(0, 1, At, B1); PG8_BAR; PG8_SCHED;
;             PG8_LDA(At, 1, 1); PG8_STAGE(PG8_SB(1, 0), b3, voffB); PG8_STAGE(PG8_SB(1, 1), b3 + hB1, voffB1); PG8_STAGE(PG8_SA(1, 0), a3, voffA);
;             PG8_WAIT_V(8);
;             if constexpr (epi_pre<Epi>::value) { if (last) E.pre(pre, cur, wr, wc, lane); }
;             PG8_WAIT_L(0); PG8_BAR; PG8_MMA(1, 0, At, B0); PG8_MMA(1, 1, At, B1); PG8_BAR; PG8_SCHED;
	v_mfma_f32_16x16x32_bf16 v[226:229], v[158:161], v[194:197], v[70:73]
	v_mfma_f32_16x16x32_bf16 v[70:73], v[162:165], v[198:201], v[226:229]
	v_mfma_f32_16x16x32_bf16 v[230:233], v[186:189], v[194:197], v[58:61]
	v_mfma_f32_16x16x32_bf16 v[234:237], v[158:161], v[202:205], v[98:101]
	v_mfma_f32_16x16x32_bf16 v[238:241], v[186:189], v[202:205], v[86:89]
	v_mfma_f32_16x16x32_bf16 v[242:245], v[158:161], v[210:213], v[66:69]
	v_mfma_f32_16x16x32_bf16 v[246:249], v[186:189], v[210:213], v[94:97]
	v_mfma_f32_16x16x32_bf16 v[226:229], v[158:161], v[218:221], v[118:121]
	v_mfma_f32_16x16x32_bf16 v[106:109], v[186:189], v[218:221], v[106:109]
	v_mfma_f32_16x16x32_bf16 v[58:61], v[190:193], v[198:201], v[230:233]
	v_mfma_f32_16x16x32_bf16 v[98:101], v[162:165], v[206:209], v[234:237]
	v_mfma_f32_16x16x32_bf16 v[86:89], v[190:193], v[206:209], v[238:241]
	v_mfma_f32_16x16x32_bf16 v[66:69], v[162:165], v[214:217], v[242:245]
	v_mfma_f32_16x16x32_bf16 v[94:97], v[190:193], v[214:217], v[246:249]
	v_mfma_f32_16x16x32_bf16 v[118:121], v[162:165], v[222:225], v[226:229]
	v_mfma_f32_16x16x32_bf16 v[106:109], v[190:193], v[222:225], v[106:109]
	s_setprio 0
	s_setprio 1
	v_mfma_f32_16x16x32_bf16 v[158:161], v[138:141], v[194:197], v[42:45]
	v_mfma_f32_16x16x32_bf16 v[42:45], v[142:145], v[198:201], v[158:161]
	v_mfma_f32_16x16x32_bf16 v[162:165], v[146:149], v[194:197], v[6:9]
	v_mfma_f32_16x16x32_bf16 v[186:189], v[138:141], v[202:205], v[54:57]
	v_mfma_f32_16x16x32_bf16 v[190:193], v[146:149], v[202:205], v[10:13]
	v_mfma_f32_16x16x32_bf16 v[226:229], v[138:141], v[210:213], v[38:41]
	v_mfma_f32_16x16x32_bf16 v[230:233], v[146:149], v[210:213], v[14:17]
	v_mfma_f32_16x16x32_bf16 v[158:161], v[138:141], v[218:221], v[82:85]
	v_mfma_f32_16x16x32_bf16 v[22:25], v[146:149], v[218:221], v[22:25]
	v_mfma_f32_16x16x32_bf16 v[4:7], v[134:137], v[198:201], v[162:165]
	v_mfma_f32_16x16x32_bf16 v[54:57], v[142:145], v[206:209], v[186:189]
	v_mfma_f32_16x16x32_bf16 v[10:13], v[134:137], v[206:209], v[190:193]
	v_mfma_f32_16x16x32_bf16 v[38:41], v[142:145], v[214:217], v[226:229]
	v_mfma_f32_16x16x32_bf16 v[14:17], v[134:137], v[214:217], v[230:233]
	v_mfma_f32_16x16x32_bf16 v[82:85], v[142:145], v[222:225], v[158:161]
	v_mfma_f32_16x16x32_bf16 v[22:25], v[134:137], v[222:225], v[22:25]
	s_setprio 0
	s_barrier
	v_add_u32_e32 v2, s73, v184
	ds_read_b128 v[158:161], v2
	ds_read_b128 v[162:165], v2 offset:1024
	ds_read_b128 v[186:189], v2 offset:2048
	ds_read_b128 v[190:193], v2 offset:3072
	v_add_u32_e32 v2, s72, v184
	ds_read_b128 v[138:141], v2
	ds_read_b128 v[142:145], v2 offset:1024
	ds_read_b128 v[146:149], v2 offset:2048
	ds_read_b128 v[134:137], v2 offset:3072
	s_mov_b32 m0, s52
	ds_read_b128 v[194:197], v185 offset:32768
	ds_read_b128 v[198:201], v185 offset:33792
	ds_read_b128 v[202:205], v185 offset:34816
	ds_read_b128 v[206:209], v185 offset:35840
	ds_read_b128 v[210:213], v185 offset:36864
	ds_read_b128 v[214:217], v185 offset:37888
	ds_read_b128 v[218:221], v185 offset:38912
	ds_read_b128 v[222:225], v185 offset:39936
	global_load_lds_dwordx4 v166, s[2:3]
	s_mov_b32 m0, s53
	s_nop 0
	global_load_lds_dwordx4 v170, s[2:3]
	s_waitcnt vmcnt(8)
	s_waitcnt lgkmcnt(0)
	s_nop 0
	s_setprio 1
	s_barrier
	v_mfma_f32_16x16x32_bf16 v[226:229], v[158:161], v[194:197], v[78:81]
	v_mfma_f32_16x16x32_bf16 v[78:81], v[162:165], v[198:201], v[226:229]
	v_mfma_f32_16x16x32_bf16 v[230:233], v[186:189], v[194:197], v[62:65]
	v_mfma_f32_16x16x32_bf16 v[234:237], v[158:161], v[202:205], v[130:133]
	v_mfma_f32_16x16x32_bf16 v[238:241], v[186:189], v[202:205], v[126:129]
	v_mfma_f32_16x16x32_bf16 v[242:245], v[158:161], v[210:213], v[74:77]
	v_mfma_f32_16x16x32_bf16 v[246:249], v[186:189], v[210:213], v[102:105]
	v_mfma_f32_16x16x32_bf16 v[226:229], v[158:161], v[218:221], v[122:125]
	v_mfma_f32_16x16x32_bf16 v[114:117], v[186:189], v[218:221], v[114:117]
	v_mfma_f32_16x16x32_bf16 v[62:65], v[190:193], v[198:201], v[230:233]
	v_mfma_f32_16x16x32_bf16 v[130:133], v[162:165], v[206:209], v[234:237]
	v_mfma_f32_16x16x32_bf16 v[126:129], v[190:193], v[206:209], v[238:241]
	v_mfma_f32_16x16x32_bf16 v[74:77], v[162:165], v[214:217], v[242:245]
	v_mfma_f32_16x16x32_bf16 v[102:105], v[190:193], v[214:217], v[246:249]
	v_mfma_f32_16x16x32_bf16 v[122:125], v[162:165], v[222:225], v[226:229]
	v_mfma_f32_16x16x32_bf16 v[114:117], v[190:193], v[222:225], v[114:117]
	s_setprio 0
	s_setprio 1
	v_mfma_f32_16x16x32_bf16 v[226:229], v[138:141], v[194:197], v[50:53]
	v_mfma_f32_16x16x32_bf16 v[50:53], v[142:145], v[198:201], v[226:229]
	v_mfma_f32_16x16x32_bf16 v[230:233], v[146:149], v[194:197], v[30:33]
	v_mfma_f32_16x16x32_bf16 v[234:237], v[138:141], v[202:205], v[110:113]
	v_mfma_f32_16x16x32_bf16 v[238:241], v[146:149], v[202:205], v[34:37]
	v_mfma_f32_16x16x32_bf16 v[242:245], v[138:141], v[210:213], v[46:49]
	v_mfma_f32_16x16x32_bf16 v[246:249], v[146:149], v[210:213], v[18:21]
	v_mfma_f32_16x16x32_bf16 v[194:197], v[138:141], v[218:221], v[90:93]
	v_mfma_f32_16x16x32_bf16 v[26:29], v[146:149], v[218:221], v[26:29]
	v_mfma_f32_16x16x32_bf16 v[30:33], v[134:137], v[198:201], v[230:233]
	v_mfma_f32_16x16x32_bf16 v[110:113], v[142:145], v[206:209], v[234:237]
	v_mfma_f32_16x16x32_bf16 v[34:37], v[134:137], v[206:209], v[238:241]
	v_mfma_f32_16x16x32_bf16 v[46:49], v[142:145], v[214:217], v[242:245]
	v_mfma_f32_16x16x32_bf16 v[18:21], v[134:137], v[214:217], v[246:249]
	v_mfma_f32_16x16x32_bf16 v[90:93], v[142:145], v[222:225], v[194:197]
	v_mfma_f32_16x16x32_bf16 v[26:29], v[134:137], v[222:225], v[26:29]
	s_setprio 0
	s_barrier
; #define EPC_LOAD(i) do { const unsigned o_ = gbase + EPC_GOFF(i); gq[i] = *(const u32x4*)(MG + (o_ + go)); gr[i] = *(const u32x4*)(nbase + ((o_ + gn) & nmask)); } while (0)
; #define PG8_STAGE(bufoff, gbase, voff) do { _Pragma("unroll") for (int _i = 0; _i < 2; ++_i) \
;         __builtin_amdgcn_global_load_lds((const unsigned*)((const char*)(gbase) + (voff)[_i]), (PG8_LAS unsigned*)(lds + (bufoff) + ldsw + _i * 8192), 16, 0, 0); } while (0)
; #define PG8_LDA(dst, b, h) do { _Pragma("unroll") for (int m = 0; m < 4; ++m) _Pragma("unroll") for (int k = 0; k < 2; ++k) dst[m][k] = *(const PG8_LAS bf16x8*)(lds + PG8_SA(b, h) + aoff + m * 2048 + k * 1024); } while (0)
; #define PG8_WAIT_V(n) asm volatile("s_waitcnt vmcnt(" #n ")" ::: "memory")
;     __device__ __forceinline__ void chain(f32x4 (&acc)[2][2][4][2], const Unit& u, int wr, int wc, int fr, int fq) const {
;     ...
;         const bool last = (u.sub == 3);
;         const unsigned gbase = (unsigned)(u.pm * BM + wr * 64 + fr) * 8704u + (unsigned)(u.pn * BM + wc * 64 + 16 * fq);
;         const unsigned obase = (unsigned)(u.pm * BM + wr * 64 + fr) * 1024u + (unsigned)(u.pn * BM + wc * 64 + 16 * fq);
;         const unsigned go = last ? 0u : 3072u + 1024u * (unsigned)u.sub;
;         const unsigned gn = (u.sub < 2) ? go + 1024u : 0u, nmask = last ? 0u : 0xffffffffu;
;         const unsigned char* nbase = last ? FF : MG;
;         const float keep = last ? 0.f : 1.f;
;         u32x4 gq[8], gr[8];
;     ...
; #pragma unroll
;         for (int i = 0; i < DEPTH; ++i) EPC_LOAD(i);
; template <class Epi, class Sched, class Gemm, bool ALIGN_EPI = false, bool SP2 = false>
; __device__ __forceinline__ void gemm_phase(PG8_LAS unsigned char* lds, const Gemm g, const Sched& S, const Epi& E) {
;     ...
;             PG8_LDB(B0, 1, 0); PG8_LDB(B1, 1, 1); PG8_SCHED; PG8_LDA(At, 1, 0); PG8_STAGE(PG8_SA(0, 1), a2 + hstepA, voffA);
;             PG8_WAIT_V(8); PG8_WAIT_L(0); PG8_BAR; PG8_MMA(0, 0, At, B0); PG8_MMA(0, 1, At, B1); PG8_BAR; PG8_SCHED;
;             PG8_LDA(At, 1, 1); PG8_STAGE(PG8_SB(1, 0), b3, voffB); PG8_STAGE(PG8_SB(1, 1), b3 + hB1, voffB1); PG8_STAGE(PG8_SA(1, 0), a3, voffA);
;             PG8_WAIT_V(8);
;             if constexpr (epi_pre<Epi>::value) { if (last) E.pre(pre, cur, wr, wc, lane); }
;             PG8_WAIT_L(0); PG8_BAR; PG8_MMA(1, 0, At, B0); PG8_MMA(1, 1, At, B1); PG8_BAR; PG8_SCHED;
	s_mov_b32 m0, s69
	v_lshl_add_u64 v[8:9], v[150:151], 0, s[16:17]
	ds_read_b128 v[194:197], v185 offset:49152
	ds_read_b128 v[198:201], v185 offset:50176
	ds_read_b128 v[202:205], v185 offset:51200
	ds_read_b128 v[206:209], v185 offset:52224
	ds_read_b128 v[210:213], v185 offset:53248
	ds_read_b128 v[214:217], v185 offset:54272
	ds_read_b128 v[218:221], v185 offset:55296
	ds_read_b128 v[222:225], v185 offset:56320
	global_load_lds_dwordx4 v[8:9], off
	v_lshl_add_u64 v[8:9], v[152:153], 0, s[16:17]
	s_mov_b32 m0, s68
	s_nop 0
	global_load_lds_dwordx4 v[8:9], off
	s_mov_b32 m0, s71
	s_nop 0
	global_load_lds_dwordx4 v168, s[36:37]
	s_mov_b32 m0, s70
	s_nop 0
	global_load_lds_dwordx4 v172, s[36:37]
	v_lshl_add_u64 v[8:9], v[154:155], 0, s[16:17]
	s_mov_b32 m0, s57
	s_nop 0
	global_load_lds_dwordx4 v[8:9], off
	v_lshl_add_u64 v[8:9], v[156:157], 0, s[16:17]
	s_mov_b32 m0, s58
	s_nop 0
	global_load_lds_dwordx4 v[8:9], off
	s_waitcnt vmcnt(8)
	s_waitcnt lgkmcnt(0)
	s_nop 0
	s_setprio 1
	s_barrier
	v_mfma_f32_16x16x32_bf16 v[150:153], v[158:161], v[194:197], v[70:73]
	v_mfma_f32_16x16x32_bf16 v[70:73], v[162:165], v[198:201], v[150:153]
	v_mfma_f32_16x16x32_bf16 v[154:157], v[186:189], v[194:197], v[58:61]
	v_mfma_f32_16x16x32_bf16 v[226:229], v[158:161], v[202:205], v[98:101]
	v_mfma_f32_16x16x32_bf16 v[230:233], v[186:189], v[202:205], v[86:89]
	v_mfma_f32_16x16x32_bf16 v[234:237], v[158:161], v[210:213], v[66:69]
	v_mfma_f32_16x16x32_bf16 v[238:241], v[186:189], v[210:213], v[94:97]
	v_mfma_f32_16x16x32_bf16 v[150:153], v[158:161], v[218:221], v[118:121]
	v_mfma_f32_16x16x32_bf16 v[106:109], v[186:189], v[218:221], v[106:109]
	v_mfma_f32_16x16x32_bf16 v[58:61], v[190:193], v[198:201], v[154:157]
	v_mfma_f32_16x16x32_bf16 v[98:101], v[162:165], v[206:209], v[226:229]
	v_mfma_f32_16x16x32_bf16 v[86:89], v[190:193], v[206:209], v[230:233]
	v_mfma_f32_16x16x32_bf16 v[66:69], v[162:165], v[214:217], v[234:237]
	v_mfma_f32_16x16x32_bf16 v[94:97], v[190:193], v[214:217], v[238:241]
	v_mfma_f32_16x16x32_bf16 v[118:121], v[162:165], v[222:225], v[150:153]
	v_mfma_f32_16x16x32_bf16 v[106:109], v[190:193], v[222:225], v[106:109]
	s_setprio 0
	s_setprio 1
	v_mfma_f32_16x16x32_bf16 v[150:153], v[138:141], v[194:197], v[42:45]
	v_mfma_f32_16x16x32_bf16 v[42:45], v[142:145], v[198:201], v[150:153]
	v_mfma_f32_16x16x32_bf16 v[154:157], v[146:149], v[194:197], v[4:7]
	v_mfma_f32_16x16x32_bf16 v[158:161], v[138:141], v[202:205], v[54:57]
	v_mfma_f32_16x16x32_bf16 v[162:165], v[146:149], v[202:205], v[10:13]
	v_mfma_f32_16x16x32_bf16 v[186:189], v[138:141], v[210:213], v[38:41]
	v_mfma_f32_16x16x32_bf16 v[190:193], v[146:149], v[210:213], v[14:17]
	v_mfma_f32_16x16x32_bf16 v[150:153], v[138:141], v[218:221], v[82:85]
	v_mfma_f32_16x16x32_bf16 v[22:25], v[146:149], v[218:221], v[22:25]
	v_mfma_f32_16x16x32_bf16 v[6:9], v[134:137], v[198:201], v[154:157]
	v_mfma_f32_16x16x32_bf16 v[54:57], v[142:145], v[206:209], v[158:161]
	v_mfma_f32_16x16x32_bf16 v[10:13], v[134:137], v[206:209], v[162:165]
	v_mfma_f32_16x16x32_bf16 v[38:41], v[142:145], v[214:217], v[186:189]
	v_mfma_f32_16x16x32_bf16 v[14:17], v[134:137], v[214:217], v[190:193]
	v_mfma_f32_16x16x32_bf16 v[82:85], v[142:145], v[222:225], v[150:153]
	v_mfma_f32_16x16x32_bf16 v[22:25], v[134:137], v[222:225], v[22:25]
	s_setprio 0
	s_barrier
	s_andn2_b64 vcc, exec, s[34:35]
	s_mov_b64 s[2:3], -1
	s_mov_b64 s[34:35], 0
	s_mov_b64 s[36:37], 0x100
	s_cbranch_vccz .LBB0_2633
	s_lshl_b32 s0, s0, 8
	s_lshl_b32 s1, s6, 8
	s_or_b32 s21, s0, s59
	s_lshl_b32 s0, s7, 10
	s_add_i32 s6, s1, s56
	s_add_i32 s23, s0, 0xc00
	s_cmp_eq_u32 s7, 3
	v_mov_b32_e32 v2, v181
	v_mov_b32_e32 v4, v1
	s_cselect_b64 s[0:1], -1, 0
	s_and_b64 s[2:3], s[0:1], exec
	s_cselect_b32 s2, 0, s23
	v_add_u32_e32 v4, s6, v4
	v_mul_lo_u32 v5, v4, s63
	v_lshlrev_b32_e32 v2, 4, v2
	s_cselect_b32 s28, s54, s14
	s_cselect_b32 s29, s55, s15
	s_add_i32 s3, s2, 0x400
	v_add3_u32 v180, s21, v2, v5
	s_cmp_lt_u32 s7, 2
	v_add_u32_e32 v2, s2, v180
	s_cselect_b32 s3, s3, 0
	global_load_dwordx4 v[142:145], v2, s[14:15]
	v_add_u32_e32 v2, s3, v180
	v_cndmask_b32_e64 v2, v2, 0, s[0:1]
	global_load_dwordx4 v[146:149], v2, s[28:29]
	v_add_u32_e32 v2, 0x22000, v180
	v_add_u32_e32 v138, 0x66000, v180
	v_add_u32_e32 v5, 0x44000, v180
	v_add_u32_e32 v134, s2, v2
	v_add_u32_e32 v136, s2, v138
	v_add_u32_e32 v2, s3, v2
	v_add_u32_e32 v138, s3, v138
	v_add_u32_e32 v135, s2, v5
	v_add_u32_e32 v5, s3, v5
	v_cndmask_b32_e64 v2, v2, 0, s[0:1]
	v_cndmask_b32_e64 v138, v138, 0, s[0:1]
	global_load_dwordx4 v[150:153], v134, s[14:15]
	global_load_dwordx4 v[154:157], v135, s[14:15]
	s_nop 0
	global_load_dwordx4 v[134:137], v136, s[14:15]
	v_cndmask_b32_e64 v5, v5, 0, s[0:1]
	global_load_dwordx4 v[158:161], v2, s[28:29]
	global_load_dwordx4 v[162:165], v5, s[28:29]
	s_nop 0
	global_load_dwordx4 v[138:141], v138, s[28:29]
	v_mad_u64_u32 v[4:5], s[30:31], v4, s64, v[180:181]
	s_and_b64 vcc, exec, s[18:19]
	s_cbranch_vccz .LBB0_2636
	s_barrier

; #define PG8_STAGE(bufoff, gbase, voff) do { _Pragma("unroll") for (int _i = 0; _i < 2; ++_i) \
;         __builtin_amdgcn_global_load_lds((const unsigned*)((const char*)(gbase) + (voff)[_i]), (PG8_LAS unsigned*)(lds + (bufoff) + ldsw + _i * 8192), 16, 0, 0); } while (0)
; #define PG8_LDA(dst, b, h) do { _Pragma("unroll") for (int m = 0; m < 4; ++m) _Pragma("unroll") for (int k = 0; k < 2; ++k) dst[m][k] = *(const PG8_LAS bf16x8*)(lds + PG8_SA(b, h) + aoff + m * 2048 + k * 1024); } while (0)
; #define PG8_LDB(dst, b, h) do { _Pragma("unroll") for (int n = 0; n < 2; ++n) _Pragma("unroll") for (int k = 0; k < 2; ++k) dst[n][k] = *(const PG8_LAS bf16x8*)(lds + PG8_SB(b, h) + boff + n * 2048 + k * 1024); } while (0)
; #define PG8_MMA(ai, bj, At, Bt) do { __builtin_amdgcn_s_setprio(1); _Pragma("unroll") for (int m = 0; m < 4; ++m) _Pragma("unroll") for (int n = 0; n < 2; ++n) _Pragma("unroll") for (int k = 0; k < 2; ++k) \
;         acc[ai][bj][m][n] = Gemm::i8 ? ::mfma16i8_g(Bt[n][k], At[m][k], acc[ai][bj][m][n]) : ::mfma16_g(Bt[n][k], At[m][k], acc[ai][bj][m][n]); __builtin_amdgcn_s_setprio(0); } while (0)
; #define PG8_WAIT_V(n) asm volatile("s_waitcnt vmcnt(" #n ")" ::: "memory")
; #define PG8_WAIT_L(n) asm volatile("s_waitcnt lgkmcnt(" #n ")" ::: "memory")
; template <class Epi, class Sched, class Gemm, bool ALIGN_EPI = false, bool SP2 = false>
; __device__ __forceinline__ void gemm_phase(PG8_LAS unsigned char* lds, const Gemm g, const Sched& S, const Epi& E) {
;     ...
;             PG8_LDB(B0, 0, 0); PG8_LDB(B1, 0, 1); PG8_SCHED; PG8_LDA(At, 0, 0); PG8_STAGE(PG8_SA(1, 1), a1 + hstepA, voffA);
;             PG8_WAIT_V(8); PG8_WAIT_L(0); PG8_BAR; PG8_MMA(0, 0, At, B0); PG8_MMA(0, 1, At, B1); PG8_BAR; PG8_SCHED;
;             PG8_LDA(At, 0, 1); PG8_STAGE(PG8_SB(0, 0), b2, voffB); PG8_STAGE(PG8_SB(0, 1), b2 + hB1, voffB1); PG8_STAGE(PG8_SA(0, 0), a2, voffA);
;             PG8_WAIT_V(8); PG8_WAIT_L(0); PG8_BAR; PG8_MMA(1, 0, At, B0); PG8_MMA(1, 1, At, B1); PG8_BAR; PG8_SCHED;
;             PG8_LDB(B0, 1, 0); PG8_LDB(B1, 1, 1); PG8_SCHED; PG8_LDA(At, 1, 0); PG8_STAGE(PG8_SA(0, 1), a2 + hstepA, voffA);
;             PG8_WAIT_V(8); PG8_WAIT_L(0); PG8_BAR; PG8_MMA(0, 0, At, B0); PG8_MMA(0, 1, At, B1); PG8_BAR; PG8_SCHED;
;             PG8_LDA(At, 1, 1); PG8_STAGE(PG8_SB(1, 0), b3, voffB); PG8_STAGE(PG8_SB(1, 1), b3 + hB1, voffB1); PG8_STAGE(PG8_SA(1, 0), a3, voffA);
.LBB0_2730:
	ds_read_b128 v[152:155], v233
	ds_read_b128 v[156:159], v233 offset:1024
	ds_read_b128 v[160:163], v233 offset:2048
	ds_read_b128 v[164:167], v233 offset:3072
	ds_read_b128 v[132:135], v234
	ds_read_b128 v[136:139], v234 offset:1024
	ds_read_b128 v[140:143], v234 offset:2048
	ds_read_b128 v[128:131], v234 offset:3072
	s_add_u32 s2, s46, 0xfffc0080
	s_addc_u32 s3, s47, -1
	s_cmp_eq_u32 s77, 12
	s_cselect_b32 s3, s5, s3
	s_cselect_b32 s2, s39, s2
	s_cselect_b32 s49, s37, s76
	s_cselect_b32 s48, s45, s75
	s_add_i32 m0, s55, 0xc000
	ds_read_b128 v[144:147], v235
	ds_read_b128 v[148:151], v235 offset:1024
	ds_read_b128 v[168:171], v235 offset:2048
	ds_read_b128 v[172:175], v235 offset:3072
	ds_read_b128 v[192:195], v235 offset:4096
	ds_read_b128 v[196:199], v235 offset:5120
	ds_read_b128 v[200:203], v235 offset:6144
	ds_read_b128 v[204:207], v235 offset:7168
	global_load_lds_dwordx4 v186, s[46:47]
	v_lshl_add_u64 v[208:209], s[46:47], 0, v[184:185]
	s_add_i32 m0, s55, 0xe000
	s_nop 0
	global_load_lds_dwordx4 v184, s[46:47]
	s_waitcnt vmcnt(8)
	s_waitcnt lgkmcnt(0)
	s_nop 0
	s_setprio 1
	s_barrier
	v_mfma_f32_16x16x32_bf16 v[208:211], v[152:155], v[144:147], v[124:127]
	v_mfma_f32_16x16x32_bf16 v[124:127], v[156:159], v[148:151], v[208:211]
	v_mfma_f32_16x16x32_bf16 v[212:215], v[160:163], v[144:147], v[120:123]
	v_mfma_f32_16x16x32_bf16 v[216:219], v[152:155], v[168:171], v[108:111]
	v_mfma_f32_16x16x32_bf16 v[220:223], v[160:163], v[168:171], v[104:107]
	v_mfma_f32_16x16x32_bf16 v[224:227], v[152:155], v[192:195], v[92:95]
	v_mfma_f32_16x16x32_bf16 v[240:243], v[160:163], v[192:195], v[88:91]
	v_mfma_f32_16x16x32_bf16 v[208:211], v[152:155], v[200:203], v[76:79]
	v_mfma_f32_16x16x32_bf16 v[72:75], v[160:163], v[200:203], v[72:75]
	v_mfma_f32_16x16x32_bf16 v[120:123], v[164:167], v[148:151], v[212:215]
	v_mfma_f32_16x16x32_bf16 v[108:111], v[156:159], v[172:175], v[216:219]
	v_mfma_f32_16x16x32_bf16 v[104:107], v[164:167], v[172:175], v[220:223]
	v_mfma_f32_16x16x32_bf16 v[92:95], v[156:159], v[196:199], v[224:227]
	v_mfma_f32_16x16x32_bf16 v[88:91], v[164:167], v[196:199], v[240:243]
	v_mfma_f32_16x16x32_bf16 v[76:79], v[156:159], v[204:207], v[208:211]
	v_mfma_f32_16x16x32_bf16 v[72:75], v[164:167], v[204:207], v[72:75]
	s_setprio 0
	s_setprio 1
	v_mfma_f32_16x16x32_bf16 v[208:211], v[132:135], v[144:147], v[116:119]
	v_mfma_f32_16x16x32_bf16 v[116:119], v[136:139], v[148:151], v[208:211]
	v_mfma_f32_16x16x32_bf16 v[212:215], v[140:143], v[144:147], v[112:115]
	v_mfma_f32_16x16x32_bf16 v[216:219], v[132:135], v[168:171], v[100:103]
	v_mfma_f32_16x16x32_bf16 v[220:223], v[140:143], v[168:171], v[96:99]
	v_mfma_f32_16x16x32_bf16 v[224:227], v[132:135], v[192:195], v[84:87]
	v_mfma_f32_16x16x32_bf16 v[240:243], v[140:143], v[192:195], v[80:83]
	v_mfma_f32_16x16x32_bf16 v[144:147], v[132:135], v[200:203], v[68:71]
	v_mfma_f32_16x16x32_bf16 v[64:67], v[140:143], v[200:203], v[64:67]
	v_mfma_f32_16x16x32_bf16 v[112:115], v[128:131], v[148:151], v[212:215]
	v_mfma_f32_16x16x32_bf16 v[100:103], v[136:139], v[172:175], v[216:219]
	v_mfma_f32_16x16x32_bf16 v[96:99], v[128:131], v[172:175], v[220:223]
	v_mfma_f32_16x16x32_bf16 v[84:87], v[136:139], v[196:199], v[224:227]
	v_mfma_f32_16x16x32_bf16 v[80:83], v[128:131], v[196:199], v[240:243]
	v_mfma_f32_16x16x32_bf16 v[68:71], v[136:139], v[204:207], v[144:147]
	v_mfma_f32_16x16x32_bf16 v[64:67], v[128:131], v[204:207], v[64:67]
	s_setprio 0
	s_barrier
	s_add_i32 s78, s68, s54
	v_lshl_add_u64 v[144:145], s[48:49], 0, v[178:179]
	s_mov_b32 m0, s78
	ds_read_b128 v[168:171], v235 offset:16384
	ds_read_b128 v[172:175], v235 offset:17408
	ds_read_b128 v[192:195], v235 offset:18432
	ds_read_b128 v[196:199], v235 offset:19456
	ds_read_b128 v[200:203], v235 offset:20480
	ds_read_b128 v[204:207], v235 offset:21504
	ds_read_b128 v[208:211], v235 offset:22528
	ds_read_b128 v[212:215], v235 offset:23552
	global_load_lds_dwordx4 v178, s[48:49]
	s_add_i32 m0, s78, 0x2000
	s_add_u32 s78, s48, 0x40000
	v_lshl_add_u64 v[146:147], s[48:49], 0, v[182:183]
	s_addc_u32 s79, s49, 0
	s_add_i32 s80, s69, s54
	global_load_lds_dwordx4 v182, s[48:49]
	s_mov_b32 m0, s80
	v_lshl_add_u64 v[150:151], s[2:3], 0, v[180:181]
	global_load_lds_dwordx4 v178, s[78:79]
	s_add_i32 m0, s80, 0x2000
	s_nop 0
	global_load_lds_dwordx4 v182, s[78:79]
	v_lshl_add_u64 v[148:149], s[2:3], 0, v[176:177]
	s_mov_b32 m0, s55
	s_nop 0
	global_load_lds_dwordx4 v176, s[2:3]
	s_mov_b32 m0, s56
	s_nop 0
	global_load_lds_dwordx4 v180, s[2:3]
	s_waitcnt vmcnt(8)
	s_waitcnt lgkmcnt(0)
	s_nop 0
	s_setprio 1
	s_barrier
; #define PG8_STAGE(bufoff, gbase, voff) do { _Pragma("unroll") for (int _i = 0; _i < 2; ++_i) \
;         __builtin_amdgcn_global_load_lds((const unsigned*)((const char*)(gbase) + (voff)[_i]), (PG8_LAS unsigned*)(lds + (bufoff) + ldsw + _i * 8192), 16, 0, 0); } while (0)
; #define PG8_LDA(dst, b, h) do { _Pragma("unroll") for (int m = 0; m < 4; ++m) _Pragma("unroll") for (int k = 0; k < 2; ++k) dst[m][k] = *(const PG8_LAS bf16x8*)(lds + PG8_SA(b, h) + aoff + m * 2048 + k * 1024); } while (0)
; #define PG8_LDB(dst, b, h) do { _Pragma("unroll") for (int n = 0; n < 2; ++n) _Pragma("unroll") for (int k = 0; k < 2; ++k) dst[n][k] = *(const PG8_LAS bf16x8*)(lds + PG8_SB(b, h) + boff + n * 2048 + k * 1024); } while (0)
; #define PG8_MMA(ai, bj, At, Bt) do { __builtin_amdgcn_s_setprio(1); _Pragma("unroll") for (int m = 0; m < 4; ++m) _Pragma("unroll") for (int n = 0; n < 2; ++n) _Pragma("unroll") for (int k = 0; k < 2; ++k) \
;         acc[ai][bj][m][n] = Gemm::i8 ? ::mfma16i8_g(Bt[n][k], At[m][k], acc[ai][bj][m][n]) : ::mfma16_g(Bt[n][k], At[m][k], acc[ai][bj][m][n]); __builtin_amdgcn_s_setprio(0); } while (0)
; #define PG8_WAIT_V(n) asm volatile("s_waitcnt vmcnt(" #n ")" ::: "memory")
; #define PG8_WAIT_L(n) asm volatile("s_waitcnt lgkmcnt(" #n ")" ::: "memory")
; template <class Epi, class Sched, class Gemm, bool ALIGN_EPI = false, bool SP2 = false>
; __device__ __forceinline__ void gemm_phase(PG8_LAS unsigned char* lds, const Gemm g, const Sched& S, const Epi& E) {
;     ...
;             PG8_LDB(B0, 0, 0); PG8_LDB(B1, 0, 1); PG8_SCHED; PG8_LDA(At, 0, 0); PG8_STAGE(PG8_SA(1, 1), a1 + hstepA, voffA);
;             PG8_WAIT_V(8); PG8_WAIT_L(0); PG8_BAR; PG8_MMA(0, 0, At, B0); PG8_MMA(0, 1, At, B1); PG8_BAR; PG8_SCHED;
;             PG8_LDA(At, 0, 1); PG8_STAGE(PG8_SB(0, 0), b2, voffB); PG8_STAGE(PG8_SB(0, 1), b2 + hB1, voffB1); PG8_STAGE(PG8_SA(0, 0), a2, voffA);
;             PG8_WAIT_V(8); PG8_WAIT_L(0); PG8_BAR; PG8_MMA(1, 0, At, B0); PG8_MMA(1, 1, At, B1); PG8_BAR; PG8_SCHED;
;             PG8_LDB(B0, 1, 0); PG8_LDB(B1, 1, 1); PG8_SCHED; PG8_LDA(At, 1, 0); PG8_STAGE(PG8_SA(0, 1), a2 + hstepA, voffA);
;             PG8_WAIT_V(8); PG8_WAIT_L(0); PG8_BAR; PG8_MMA(0, 0, At, B0); PG8_MMA(0, 1, At, B1); PG8_BAR; PG8_SCHED;
;             PG8_LDA(At, 1, 1); PG8_STAGE(PG8_SB(1, 0), b3, voffB); PG8_STAGE(PG8_SB(1, 1), b3 + hB1, voffB1); PG8_STAGE(PG8_SA(1, 0), a3, voffA);
	v_mfma_f32_16x16x32_bf16 v[216:219], v[152:155], v[168:171], v[60:63]
	v_mfma_f32_16x16x32_bf16 v[60:63], v[156:159], v[172:175], v[216:219]
	v_mfma_f32_16x16x32_bf16 v[220:223], v[160:163], v[168:171], v[56:59]
	v_mfma_f32_16x16x32_bf16 v[224:227], v[152:155], v[192:195], v[44:47]
	v_mfma_f32_16x16x32_bf16 v[240:243], v[160:163], v[192:195], v[40:43]
	v_mfma_f32_16x16x32_bf16 v[244:247], v[152:155], v[200:203], v[28:31]
	v_mfma_f32_16x16x32_bf16 v[248:251], v[160:163], v[200:203], v[24:27]
	v_mfma_f32_16x16x32_bf16 v[216:219], v[152:155], v[208:211], v[12:15]
	v_mfma_f32_16x16x32_bf16 v[8:11], v[160:163], v[208:211], v[8:11]
	v_mfma_f32_16x16x32_bf16 v[56:59], v[164:167], v[172:175], v[220:223]
	v_mfma_f32_16x16x32_bf16 v[44:47], v[156:159], v[196:199], v[224:227]
	v_mfma_f32_16x16x32_bf16 v[40:43], v[164:167], v[196:199], v[240:243]
	v_mfma_f32_16x16x32_bf16 v[28:31], v[156:159], v[204:207], v[244:247]
	v_mfma_f32_16x16x32_bf16 v[24:27], v[164:167], v[204:207], v[248:251]
	v_mfma_f32_16x16x32_bf16 v[12:15], v[156:159], v[212:215], v[216:219]
	v_mfma_f32_16x16x32_bf16 v[8:11], v[164:167], v[212:215], v[8:11]
	s_setprio 0
	s_setprio 1
	v_mfma_f32_16x16x32_bf16 v[152:155], v[132:135], v[168:171], v[52:55]
	v_mfma_f32_16x16x32_bf16 v[52:55], v[136:139], v[172:175], v[152:155]
	v_mfma_f32_16x16x32_bf16 v[156:159], v[140:143], v[168:171], v[48:51]
	v_mfma_f32_16x16x32_bf16 v[160:163], v[132:135], v[192:195], v[36:39]
	v_mfma_f32_16x16x32_bf16 v[164:167], v[140:143], v[192:195], v[32:35]
	v_mfma_f32_16x16x32_bf16 v[216:219], v[132:135], v[200:203], v[20:23]
	v_mfma_f32_16x16x32_bf16 v[220:223], v[140:143], v[200:203], v[16:19]
	v_mfma_f32_16x16x32_bf16 v[152:155], v[132:135], v[208:211], v[4:7]
	v_mfma_f32_16x16x32_bf16 v[0:3], v[140:143], v[208:211], v[0:3]
	v_mfma_f32_16x16x32_bf16 v[48:51], v[128:131], v[172:175], v[156:159]
	v_mfma_f32_16x16x32_bf16 v[36:39], v[136:139], v[196:199], v[160:163]
	v_mfma_f32_16x16x32_bf16 v[32:35], v[128:131], v[196:199], v[164:167]
	v_mfma_f32_16x16x32_bf16 v[20:23], v[136:139], v[204:207], v[216:219]
	v_mfma_f32_16x16x32_bf16 v[16:19], v[128:131], v[204:207], v[220:223]
	v_mfma_f32_16x16x32_bf16 v[4:7], v[136:139], v[212:215], v[152:155]
	v_mfma_f32_16x16x32_bf16 v[0:3], v[128:131], v[212:215], v[0:3]
	s_setprio 0
	s_barrier
	s_add_i32 s78, 0, 0x18000
	v_add_u32_e32 v128, s78, v232
	s_add_i32 s79, 0, 0x1c000
	ds_read_b128 v[152:155], v128
	ds_read_b128 v[156:159], v128 offset:1024
	ds_read_b128 v[160:163], v128 offset:2048
	ds_read_b128 v[164:167], v128 offset:3072
	v_add_u32_e32 v128, s79, v232
	ds_read_b128 v[132:135], v128
	ds_read_b128 v[136:139], v128 offset:1024
	ds_read_b128 v[140:143], v128 offset:2048
	ds_read_b128 v[128:131], v128 offset:3072
	s_add_u32 s2, s2, 0x40000
	s_addc_u32 s3, s3, 0
	s_mov_b32 m0, s57
	ds_read_b128 v[168:171], v235 offset:32768
	ds_read_b128 v[172:175], v235 offset:33792
	ds_read_b128 v[192:195], v235 offset:34816
	ds_read_b128 v[196:199], v235 offset:35840
	ds_read_b128 v[200:203], v235 offset:36864
	ds_read_b128 v[204:207], v235 offset:37888
	ds_read_b128 v[208:211], v235 offset:38912
	ds_read_b128 v[212:215], v235 offset:39936
	global_load_lds_dwordx4 v176, s[2:3]
	v_lshl_add_u64 v[216:217], s[2:3], 0, v[180:181]
	s_mov_b32 m0, s58
	s_nop 0
	global_load_lds_dwordx4 v180, s[2:3]
	s_waitcnt vmcnt(8)
	s_waitcnt lgkmcnt(0)
	s_nop 0
	s_setprio 1
	s_barrier
	v_mfma_f32_16x16x32_bf16 v[216:219], v[152:155], v[168:171], v[124:127]
	v_mfma_f32_16x16x32_bf16 v[124:127], v[156:159], v[172:175], v[216:219]
	v_mfma_f32_16x16x32_bf16 v[220:223], v[160:163], v[168:171], v[120:123]
	v_mfma_f32_16x16x32_bf16 v[224:227], v[152:155], v[192:195], v[108:111]
	v_mfma_f32_16x16x32_bf16 v[240:243], v[160:163], v[192:195], v[104:107]
	v_mfma_f32_16x16x32_bf16 v[244:247], v[152:155], v[200:203], v[92:95]
	v_mfma_f32_16x16x32_bf16 v[248:251], v[160:163], v[200:203], v[88:91]
	v_mfma_f32_16x16x32_bf16 v[216:219], v[152:155], v[208:211], v[76:79]
	v_mfma_f32_16x16x32_bf16 v[72:75], v[160:163], v[208:211], v[72:75]
	v_mfma_f32_16x16x32_bf16 v[120:123], v[164:167], v[172:175], v[220:223]
	v_mfma_f32_16x16x32_bf16 v[108:111], v[156:159], v[196:199], v[224:227]
	v_mfma_f32_16x16x32_bf16 v[104:107], v[164:167], v[196:199], v[240:243]
	v_mfma_f32_16x16x32_bf16 v[92:95], v[156:159], v[204:207], v[244:247]
	v_mfma_f32_16x16x32_bf16 v[88:91], v[164:167], v[204:207], v[248:251]
	v_mfma_f32_16x16x32_bf16 v[76:79], v[156:159], v[212:215], v[216:219]
	v_mfma_f32_16x16x32_bf16 v[72:75], v[164:167], v[212:215], v[72:75]
	s_setprio 0
	s_setprio 1
	v_mfma_f32_16x16x32_bf16 v[216:219], v[132:135], v[168:171], v[116:119]
	v_mfma_f32_16x16x32_bf16 v[116:119], v[136:139], v[172:175], v[216:219]
	v_mfma_f32_16x16x32_bf16 v[220:223], v[140:143], v[168:171], v[112:115]
	v_mfma_f32_16x16x32_bf16 v[224:227], v[132:135], v[192:195], v[100:103]
	v_mfma_f32_16x16x32_bf16 v[240:243], v[140:143], v[192:195], v[96:99]
	v_mfma_f32_16x16x32_bf16 v[244:247], v[132:135], v[200:203], v[84:87]
	v_mfma_f32_16x16x32_bf16 v[248:251], v[140:143], v[200:203], v[80:83]
	v_mfma_f32_16x16x32_bf16 v[168:171], v[132:135], v[208:211], v[68:71]
	v_mfma_f32_16x16x32_bf16 v[64:67], v[140:143], v[208:211], v[64:67]
	v_mfma_f32_16x16x32_bf16 v[112:115], v[128:131], v[172:175], v[220:223]
	v_mfma_f32_16x16x32_bf16 v[100:103], v[136:139], v[196:199], v[224:227]
	v_mfma_f32_16x16x32_bf16 v[96:99], v[128:131], v[196:199], v[240:243]
	v_mfma_f32_16x16x32_bf16 v[84:87], v[136:139], v[204:207], v[244:247]
	v_mfma_f32_16x16x32_bf16 v[80:83], v[128:131], v[204:207], v[248:251]
	v_mfma_f32_16x16x32_bf16 v[68:71], v[136:139], v[212:215], v[168:171]
	v_mfma_f32_16x16x32_bf16 v[64:67], v[128:131], v[212:215], v[64:67]
	s_setprio 0
	s_barrier
; #define PG8_STAGE(bufoff, gbase, voff) do { _Pragma("unroll") for (int _i = 0; _i < 2; ++_i) \
;         __builtin_amdgcn_global_load_lds((const unsigned*)((const char*)(gbase) + (voff)[_i]), (PG8_LAS unsigned*)(lds + (bufoff) + ldsw + _i * 8192), 16, 0, 0); } while (0)
; #define PG8_LDA(dst, b, h) do { _Pragma("unroll") for (int m = 0; m < 4; ++m) _Pragma("unroll") for (int k = 0; k < 2; ++k) dst[m][k] = *(const PG8_LAS bf16x8*)(lds + PG8_SA(b, h) + aoff + m * 2048 + k * 1024); } while (0)
; #define PG8_LDB(dst, b, h) do { _Pragma("unroll") for (int n = 0; n < 2; ++n) _Pragma("unroll") for (int k = 0; k < 2; ++k) dst[n][k] = *(const PG8_LAS bf16x8*)(lds + PG8_SB(b, h) + boff + n * 2048 + k * 1024); } while (0)
; #define PG8_MMA(ai, bj, At, Bt) do { __builtin_amdgcn_s_setprio(1); _Pragma("unroll") for (int m = 0; m < 4; ++m) _Pragma("unroll") for (int n = 0; n < 2; ++n) _Pragma("unroll") for (int k = 0; k < 2; ++k) \
;         acc[ai][bj][m][n] = Gemm::i8 ? ::mfma16i8_g(Bt[n][k], At[m][k], acc[ai][bj][m][n]) : ::mfma16_g(Bt[n][k], At[m][k], acc[ai][bj][m][n]); __builtin_amdgcn_s_setprio(0); } while (0)
; #define PG8_WAIT_V(n) asm volatile("s_waitcnt vmcnt(" #n ")" ::: "memory")
; #define PG8_WAIT_L(n) asm volatile("s_waitcnt lgkmcnt(" #n ")" ::: "memory")
; #define PG8_BAR __builtin_amdgcn_s_barrier()
; #define PG8_SCHED __builtin_amdgcn_sched_barrier(0)
; template <class Epi, class Sched, class Gemm, bool ALIGN_EPI = false, bool SP2 = false>
; __device__ __forceinline__ void gemm_phase(PG8_LAS unsigned char* lds, const Gemm g, const Sched& S, const Epi& E) {
;     ...
;             PG8_LDB(B0, 1, 0); PG8_LDB(B1, 1, 1); PG8_SCHED; PG8_LDA(At, 1, 0); PG8_STAGE(PG8_SA(0, 1), a2 + hstepA, voffA);
;             PG8_WAIT_V(8); PG8_WAIT_L(0); PG8_BAR; PG8_MMA(0, 0, At, B0); PG8_MMA(0, 1, At, B1); PG8_BAR; PG8_SCHED;
;             PG8_LDA(At, 1, 1); PG8_STAGE(PG8_SB(1, 0), b3, voffB); PG8_STAGE(PG8_SB(1, 1), b3 + hB1, voffB1); PG8_STAGE(PG8_SA(1, 0), a3, voffA);
;             PG8_WAIT_V(8);
;             if constexpr (epi_pre<Epi>::value) { if (last) E.pre(pre, cur, wr, wc, lane); }
;             PG8_WAIT_L(0); PG8_BAR; PG8_MMA(1, 0, At, B0); PG8_MMA(1, 1, At, B1); PG8_BAR; PG8_SCHED;
	s_add_i32 s2, s78, s54
	v_lshl_add_u64 v[144:145], v[144:145], 0, s[16:17]
	s_mov_b32 m0, s2
	ds_read_b128 v[168:171], v235 offset:49152
	ds_read_b128 v[172:175], v235 offset:50176
	ds_read_b128 v[192:195], v235 offset:51200
	ds_read_b128 v[196:199], v235 offset:52224
	ds_read_b128 v[200:203], v235 offset:53248
	ds_read_b128 v[204:207], v235 offset:54272
	ds_read_b128 v[208:211], v235 offset:55296
	ds_read_b128 v[212:215], v235 offset:56320
	global_load_lds_dwordx4 v[144:145], off
	s_add_i32 m0, s2, 0x2000
	s_add_u32 s2, s48, 0x40080
	v_lshl_add_u64 v[144:145], v[146:147], 0, s[16:17]
	s_addc_u32 s3, s49, 0
	s_add_i32 s48, s79, s54
	global_load_lds_dwordx4 v[144:145], off
	s_mov_b32 m0, s48
	s_nop 0
	global_load_lds_dwordx4 v178, s[2:3]
	s_add_i32 m0, s48, 0x2000
	s_nop 0
	global_load_lds_dwordx4 v182, s[2:3]
	v_lshl_add_u64 v[144:145], v[148:149], 0, s[16:17]
	s_mov_b32 m0, s64
	s_nop 0
	global_load_lds_dwordx4 v[144:145], off
	v_lshl_add_u64 v[144:145], v[150:151], 0, s[16:17]
	s_mov_b32 m0, s65
	s_nop 0
	global_load_lds_dwordx4 v[144:145], off
	s_waitcnt vmcnt(8)
	s_waitcnt lgkmcnt(0)
	s_nop 0
	s_setprio 1
	s_barrier
	v_mfma_f32_16x16x32_bf16 v[144:147], v[152:155], v[168:171], v[60:63]
	v_mfma_f32_16x16x32_bf16 v[60:63], v[156:159], v[172:175], v[144:147]
	v_mfma_f32_16x16x32_bf16 v[148:151], v[160:163], v[168:171], v[56:59]
	v_mfma_f32_16x16x32_bf16 v[216:219], v[152:155], v[192:195], v[44:47]
	v_mfma_f32_16x16x32_bf16 v[220:223], v[160:163], v[192:195], v[40:43]
	v_mfma_f32_16x16x32_bf16 v[224:227], v[152:155], v[200:203], v[28:31]
	v_mfma_f32_16x16x32_bf16 v[240:243], v[160:163], v[200:203], v[24:27]
	v_mfma_f32_16x16x32_bf16 v[144:147], v[152:155], v[208:211], v[12:15]
	v_mfma_f32_16x16x32_bf16 v[8:11], v[160:163], v[208:211], v[8:11]
	v_mfma_f32_16x16x32_bf16 v[56:59], v[164:167], v[172:175], v[148:151]
	v_mfma_f32_16x16x32_bf16 v[44:47], v[156:159], v[196:199], v[216:219]
	v_mfma_f32_16x16x32_bf16 v[40:43], v[164:167], v[196:199], v[220:223]
	v_mfma_f32_16x16x32_bf16 v[28:31], v[156:159], v[204:207], v[224:227]
	v_mfma_f32_16x16x32_bf16 v[24:27], v[164:167], v[204:207], v[240:243]
	v_mfma_f32_16x16x32_bf16 v[12:15], v[156:159], v[212:215], v[144:147]
	v_mfma_f32_16x16x32_bf16 v[8:11], v[164:167], v[212:215], v[8:11]
	s_setprio 0
	s_setprio 1
	v_mfma_f32_16x16x32_bf16 v[144:147], v[132:135], v[168:171], v[52:55]
	v_mfma_f32_16x16x32_bf16 v[52:55], v[136:139], v[172:175], v[144:147]
	v_mfma_f32_16x16x32_bf16 v[148:151], v[140:143], v[168:171], v[48:51]
	v_mfma_f32_16x16x32_bf16 v[152:155], v[132:135], v[192:195], v[36:39]
	v_mfma_f32_16x16x32_bf16 v[156:159], v[140:143], v[192:195], v[32:35]
	v_mfma_f32_16x16x32_bf16 v[160:163], v[132:135], v[200:203], v[20:23]
	v_mfma_f32_16x16x32_bf16 v[164:167], v[140:143], v[200:203], v[16:19]
	v_mfma_f32_16x16x32_bf16 v[144:147], v[132:135], v[208:211], v[4:7]
	v_mfma_f32_16x16x32_bf16 v[0:3], v[140:143], v[208:211], v[0:3]
	v_mfma_f32_16x16x32_bf16 v[48:51], v[128:131], v[172:175], v[148:151]
	v_mfma_f32_16x16x32_bf16 v[36:39], v[136:139], v[196:199], v[152:155]
	v_mfma_f32_16x16x32_bf16 v[32:35], v[128:131], v[196:199], v[156:159]
	v_mfma_f32_16x16x32_bf16 v[20:23], v[136:139], v[204:207], v[160:163]
	v_mfma_f32_16x16x32_bf16 v[16:19], v[128:131], v[204:207], v[164:167]
	v_mfma_f32_16x16x32_bf16 v[4:7], v[136:139], v[212:215], v[144:147]
	v_mfma_f32_16x16x32_bf16 v[0:3], v[128:131], v[212:215], v[0:3]
	s_setprio 0
	s_barrier
	s_add_i32 s77, s77, 2
	s_add_u32 s75, s75, 0x100
	s_addc_u32 s76, s76, 0
	s_add_u32 s46, s46, 0x100
	s_addc_u32 s47, s47, 0
	s_cmp_gt_u32 s77, 13
	s_cbranch_scc0 .LBB0_2730
	s_and_b64 vcc, exec, s[18:19]
	s_cbranch_vccz .LBB0_2733
	s_barrier
